# mix1 unit epilogues: gate (and pool bias/scale) loads hoisted ahead of the store ladders with counted vmcnt waits; plus hand-written LDS-DMA GEMM mainloops and de-serialized gemm_out epilogue
# speedup vs baseline: 1.1088x; 1.0112x over previous
.LBB0_129:
	s_waitcnt vmcnt(7)
	ds_write_b128 v124, v[16:19] offset:17408
	s_waitcnt vmcnt(6)
	ds_write_b128 v124, v[20:23] offset:21760
	s_waitcnt vmcnt(5)
	ds_write_b128 v124, v[24:27] offset:26112
	s_waitcnt vmcnt(4)
	ds_write_b128 v124, v[28:31] offset:30464
	s_waitcnt vmcnt(3)
	ds_write_b128 v126, v[32:35] offset:53248
	s_waitcnt vmcnt(2)
	ds_write_b128 v126, v[36:39] offset:57856
	s_waitcnt vmcnt(1)
	ds_write_b128 v126, v[40:43] offset:62464
	s_waitcnt vmcnt(0)
	ds_write_b128 v111, v[44:47] offset:32256
	v_add_u32_e32 v81, v122, v113
	ds_read_b128 v[16:19], v81
	ds_read_b128 v[20:23], v81 offset:64
	s_mov_b32 s4, 0xf149f2ca
	s_mov_b32 s0, 0x3db504f3
	s_mov_b32 s2, 0xf149f2ca
	s_movk_i32 s68, 0xff
	s_waitcnt lgkmcnt(1)
	v_mfma_f32_16x16x32_f16 v[16:19], v[16:19], v[12:15], 0
	ds_read_b128 v[24:27], v81 offset:4416
	ds_read_b128 v[28:31], v81 offset:8768
	ds_read_b128 v[32:35], v81 offset:13120
	s_waitcnt lgkmcnt(3)
	v_mfma_f32_16x16x32_f16 v[16:19], v[20:23], v[8:11], v[16:19]
	ds_read_b128 v[20:23], v81 offset:128
	s_waitcnt lgkmcnt(0)
	v_mfma_f32_16x16x32_f16 v[16:19], v[20:23], v[4:7], v[16:19]
	ds_read_b128 v[20:23], v81 offset:192
	s_waitcnt lgkmcnt(0)
	v_mfma_f32_16x16x32_f16 v[16:19], v[20:23], v[0:3], v[16:19]
	ds_read_b128 v[20:23], v81 offset:4352
	s_waitcnt lgkmcnt(0)
	v_mfma_f32_16x16x32_f16 v[20:23], v[20:23], v[12:15], 0
	v_mfma_f32_16x16x32_f16 v[20:23], v[24:27], v[8:11], v[20:23]
	ds_read_b128 v[24:27], v81 offset:4480
	s_waitcnt lgkmcnt(0)
	v_mfma_f32_16x16x32_f16 v[20:23], v[24:27], v[4:7], v[20:23]
	ds_read_b128 v[24:27], v81 offset:4544
	s_waitcnt lgkmcnt(0)
	v_mfma_f32_16x16x32_f16 v[20:23], v[24:27], v[0:3], v[20:23]
	ds_read_b128 v[24:27], v81 offset:8704
	s_nop 6
	v_mul_f32_e32 v36, 0x3db504f3, v20
	s_waitcnt lgkmcnt(0)
	v_mfma_f32_16x16x32_f16 v[24:27], v[24:27], v[12:15], 0
	v_mul_f32_e32 v37, 0x3db504f3, v21
	v_mul_f32_e32 v38, 0x3db504f3, v22
	v_mul_f32_e32 v39, 0x3db504f3, v23
	v_mfma_f32_16x16x32_f16 v[24:27], v[28:31], v[8:11], v[24:27]
	ds_read_b128 v[28:31], v81 offset:8832
	s_waitcnt lgkmcnt(0)
	v_mfma_f32_16x16x32_f16 v[24:27], v[28:31], v[4:7], v[24:27]
	ds_read_b128 v[28:31], v81 offset:8896
	s_waitcnt lgkmcnt(0)
	v_mfma_f32_16x16x32_f16 v[24:27], v[28:31], v[0:3], v[24:27]
	ds_read_b128 v[28:31], v81 offset:13056
	s_nop 6
	v_mul_f32_e32 v40, 0x3db504f3, v24
	s_waitcnt lgkmcnt(0)
	v_mfma_f32_16x16x32_f16 v[28:31], v[28:31], v[12:15], 0
	v_mul_f32_e32 v41, 0x3db504f3, v25
	v_mul_f32_e32 v42, 0x3db504f3, v26
	v_mul_f32_e32 v43, 0x3db504f3, v27
	v_mfma_f32_16x16x32_f16 v[28:31], v[32:35], v[8:11], v[28:31]
	ds_read_b128 v[32:35], v81 offset:13184
	s_waitcnt lgkmcnt(0)
	v_mfma_f32_16x16x32_f16 v[28:31], v[32:35], v[4:7], v[28:31]
	ds_read_b128 v[32:35], v81 offset:13248
	s_waitcnt lgkmcnt(0)
	v_mfma_f32_16x16x32_f16 v[28:31], v[32:35], v[0:3], v[28:31]
	v_mul_f32_e32 v32, 0x3db504f3, v16
	v_mul_f32_e32 v33, 0x3db504f3, v17
	v_mul_f32_e32 v34, 0x3db504f3, v18
	v_mul_f32_e32 v35, 0x3db504f3, v19
	v_max3_f32 v32, v32, s4, v33
	v_max3_f32 v32, v32, v34, v35
	v_max3_f32 v32, v32, v36, v37
	v_max3_f32 v32, v32, v38, v39
	v_max3_f32 v32, v32, v40, v41
	v_mul_f32_e32 v44, 0x3db504f3, v28
	v_mul_f32_e32 v45, 0x3db504f3, v29
	v_max3_f32 v32, v32, v42, v43
	v_mul_f32_e32 v46, 0x3db504f3, v30
	v_mul_f32_e32 v47, 0x3db504f3, v31
	v_max3_f32 v32, v32, v44, v45
	v_max3_f32 v32, v32, v46, v47
	ds_bpermute_b32 v33, v117, v32
	s_waitcnt lgkmcnt(0)
	v_max_f32_e32 v33, v33, v33
	v_max_f32_e32 v32, v32, v33
	ds_bpermute_b32 v33, v119, v32
	s_waitcnt lgkmcnt(0)
	v_max3_f32 v83, v85, v32, v33
	v_fma_f32 v16, v16, s0, -v83
	v_mul_f32_e32 v16, 0x3fb8aa3b, v16
	v_fma_f32 v17, v17, s0, -v83
	v_sub_f32_e32 v32, v85, v83
	v_exp_f32_e32 v85, v16
	v_mul_f32_e32 v17, 0x3fb8aa3b, v17
	v_exp_f32_e32 v89, v17
	v_mul_f32_e32 v32, 0x3fb8aa3b, v32
	v_add_f32_e32 v16, 0, v85
	v_add_f32_e32 v168, v89, v16
	v_fma_f32 v16, v18, s0, -v83
	v_mul_f32_e32 v16, 0x3fb8aa3b, v16
	v_exp_f32_e32 v94, v16
	v_fma_f32 v16, v19, s0, -v83
	v_mul_f32_e32 v16, 0x3fb8aa3b, v16
	v_exp_f32_e32 v96, v16
	v_fma_f32 v16, v20, s0, -v83
	v_mul_f32_e32 v16, 0x3fb8aa3b, v16
	v_exp_f32_e32 v98, v16
	v_fma_f32 v16, v21, s0, -v83
	v_mul_f32_e32 v16, 0x3fb8aa3b, v16
	v_exp_f32_e32 v104, v16
	v_fma_f32 v16, v22, s0, -v83
	v_mul_f32_e32 v16, 0x3fb8aa3b, v16
	v_exp_f32_e32 v106, v16
	v_fma_f32 v16, v23, s0, -v83
	v_mul_f32_e32 v16, 0x3fb8aa3b, v16
	v_exp_f32_e32 v108, v16
	v_fma_f32 v16, v24, s0, -v83
	v_mul_f32_e32 v16, 0x3fb8aa3b, v16
	v_exp_f32_e32 v110, v16
	v_fma_f32 v16, v25, s0, -v83
	v_mul_f32_e32 v16, 0x3fb8aa3b, v16
	v_exp_f32_e32 v112, v16
	v_fma_f32 v16, v26, s0, -v83
	v_mul_f32_e32 v16, 0x3fb8aa3b, v16
	v_exp_f32_e32 v80, v16
	v_fma_f32 v16, v27, s0, -v83
	v_mul_f32_e32 v16, 0x3fb8aa3b, v16
	v_exp_f32_e32 v82, v16
	v_fma_f32 v16, v28, s0, -v83
	v_mul_f32_e32 v16, 0x3fb8aa3b, v16
	v_exp_f32_e32 v84, v16
	v_fma_f32 v16, v29, s0, -v83
	v_mul_f32_e32 v16, 0x3fb8aa3b, v16
	v_exp_f32_e32 v86, v16
	v_fma_f32 v16, v30, s0, -v83
	v_mul_f32_e32 v16, 0x3fb8aa3b, v16
	v_exp_f32_e32 v88, v16
	v_fma_f32 v16, v31, s0, -v83
	v_mul_f32_e32 v16, 0x3fb8aa3b, v16
	v_exp_f32_e32 v90, v16
	v_exp_f32_e32 v16, v32
	s_nop 0
	v_pk_mul_f32 v[36:37], v[56:57], v[16:17] op_sel_hi:[1,0]
	v_add_u32_e32 v57, v105, v107
	v_add_u32_e32 v56, 0x8800, v57
	v_pk_mul_f32 v[42:43], v[54:55], v[16:17] op_sel_hi:[1,0]
	v_pk_mul_f32 v[40:41], v[52:53], v[16:17] op_sel_hi:[1,0]
	ds_read2_b64 v[52:55], v56 offset1:4
	v_pk_mul_f32 v[46:47], v[50:51], v[16:17] op_sel_hi:[1,0]
	v_pk_mul_f32 v[44:45], v[48:49], v[16:17] op_sel_hi:[1,0]
	v_pk_mul_f32 v[26:27], v[70:71], v[16:17] op_sel_hi:[1,0]
	v_cvt_pk_f16_f32 v51, v106, v108
	v_cvt_pk_f16_f32 v50, v98, v104
	v_cvt_pk_f16_f32 v49, v94, v96
	v_cvt_pk_f16_f32 v48, v85, v89
	v_add_u32_e32 v70, 0x9000, v57
	v_add_u32_e32 v71, 0x9800, v57
	s_waitcnt lgkmcnt(0)
	v_mfma_f32_16x16x32_f16 v[44:47], v[52:55], v[48:51], v[44:47]
	ds_read2_b64 v[52:55], v70 offset0:32 offset1:36
	v_pk_mul_f32 v[38:39], v[58:59], v[16:17] op_sel_hi:[1,0]
	v_pk_mul_f32 v[20:21], v[72:73], v[16:17] op_sel_hi:[1,0]
	s_waitcnt lgkmcnt(0)
	v_mfma_f32_16x16x32_f16 v[40:43], v[52:55], v[48:51], v[40:43]
	ds_read2_b64 v[52:55], v71 offset0:64 offset1:68
	v_add_u32_e32 v72, 0xa000, v57
	v_pk_mul_f32 v[34:35], v[62:63], v[16:17] op_sel_hi:[1,0]
	s_waitcnt lgkmcnt(0)
	v_mfma_f32_16x16x32_f16 v[36:39], v[52:55], v[48:51], v[36:39]
	ds_read2_b64 v[52:55], v72 offset0:96 offset1:100
	v_pk_mul_f32 v[32:33], v[60:61], v[16:17] op_sel_hi:[1,0]
	v_add_u32_e32 v73, 0xa800, v57
	v_pk_mul_f32 v[30:31], v[66:67], v[16:17] op_sel_hi:[1,0]
	s_waitcnt lgkmcnt(0)
	v_mfma_f32_16x16x32_f16 v[32:35], v[52:55], v[48:51], v[32:35]
	ds_read2_b64 v[52:55], v73 offset0:128 offset1:132
	v_pk_mul_f32 v[28:29], v[64:65], v[16:17] op_sel_hi:[1,0]
	v_pk_mul_f32 v[22:23], v[74:75], v[16:17] op_sel_hi:[1,0]
	v_add_u32_e32 v74, 0xb000, v57
	s_waitcnt lgkmcnt(0)
	v_mfma_f32_16x16x32_f16 v[52:55], v[52:55], v[48:51], v[28:31]
	s_nop 2
	ds_read2_b64 v[28:31], v74 offset0:160 offset1:164
	v_pk_mul_f32 v[24:25], v[68:69], v[16:17] op_sel_hi:[1,0]
	v_add_u32_e32 v75, 0xb800, v57
	v_mul_f32_e32 v92, v87, v16
	s_waitcnt lgkmcnt(0)
	v_mfma_f32_16x16x32_f16 v[58:61], v[28:31], v[48:51], v[24:27]
	s_nop 2
	ds_read2_b64 v[24:27], v75 offset0:192 offset1:196
	v_pk_mul_f32 v[18:19], v[78:79], v[16:17] op_sel_hi:[1,0]
	v_pk_mul_f32 v[16:17], v[76:77], v[16:17] op_sel_hi:[1,0]
	v_add_u32_e32 v76, 0xc000, v57
	s_waitcnt lgkmcnt(0)
	v_mfma_f32_16x16x32_f16 v[62:65], v[24:27], v[48:51], v[20:23]
	s_nop 2
	ds_read2_b64 v[20:23], v76 offset0:224 offset1:228
	ds_read2_b64 v[28:31], v72 offset0:104 offset1:108
	v_cvt_pk_f16_f32 v69, v88, v90
	s_waitcnt lgkmcnt(1)
	v_mfma_f32_16x16x32_f16 v[48:51], v[20:23], v[48:51], v[16:19]
	s_nop 2
	ds_read2_b64 v[16:19], v56 offset0:8 offset1:12
	v_cvt_pk_f16_f32 v68, v84, v86
	v_cvt_pk_f16_f32 v67, v80, v82
	v_cvt_pk_f16_f32 v66, v110, v112
	ds_read2_b64 v[20:23], v70 offset0:40 offset1:44
	ds_read2_b64 v[24:27], v71 offset0:72 offset1:76
	s_waitcnt lgkmcnt(2)
	v_mfma_f32_16x16x32_f16 v[16:19], v[16:19], v[66:69], v[44:47]
	s_nop 2
	ds_read2_b64 v[44:47], v76 offset0:232 offset1:236
	v_mfma_f32_16x16x32_f16 v[28:31], v[28:31], v[66:69], v[32:35]
	s_nop 2
	ds_read2_b64 v[32:35], v73 offset0:136 offset1:140
	s_waitcnt lgkmcnt(3)
	v_mfma_f32_16x16x32_f16 v[20:23], v[20:23], v[66:69], v[40:43]
	s_waitcnt lgkmcnt(2)
	v_mfma_f32_16x16x32_f16 v[24:27], v[24:27], v[66:69], v[36:39]
	s_nop 0
	ds_read2_b64 v[40:43], v75 offset0:200 offset1:204
	s_nop 0
	ds_read2_b64 v[36:39], v74 offset0:168 offset1:172
	s_waitcnt lgkmcnt(3)
	v_mfma_f32_16x16x32_f16 v[44:47], v[44:47], v[66:69], v[48:51]
	s_waitcnt lgkmcnt(0)
	s_barrier
	s_nop 0
	ds_read_b128 v[48:51], v81 offset:17408
	v_mfma_f32_16x16x32_f16 v[32:35], v[32:35], v[66:69], v[52:55]
	s_nop 2
	ds_read_b128 v[52:55], v81 offset:17472
	s_waitcnt lgkmcnt(1)
	v_mfma_f32_16x16x32_f16 v[48:51], v[48:51], v[12:15], 0
	s_waitcnt lgkmcnt(0)
	v_mfma_f32_16x16x32_f16 v[48:51], v[52:55], v[8:11], v[48:51]
	ds_read_b128 v[52:55], v81 offset:17536
	v_mfma_f32_16x16x32_f16 v[36:39], v[36:39], v[66:69], v[58:61]
	s_nop 2
	ds_read_b128 v[58:61], v81 offset:21824
	s_waitcnt lgkmcnt(1)
	v_mfma_f32_16x16x32_f16 v[48:51], v[52:55], v[4:7], v[48:51]
	ds_read_b128 v[52:55], v81 offset:17600
	v_mfma_f32_16x16x32_f16 v[40:43], v[40:43], v[66:69], v[62:65]
	s_nop 2
	ds_read_b128 v[62:65], v81 offset:26176
	s_waitcnt lgkmcnt(1)
	v_mfma_f32_16x16x32_f16 v[48:51], v[52:55], v[0:3], v[48:51]
	ds_read_b128 v[52:55], v81 offset:21760
	s_waitcnt lgkmcnt(0)
	v_mfma_f32_16x16x32_f16 v[52:55], v[52:55], v[12:15], 0
	v_mfma_f32_16x16x32_f16 v[52:55], v[58:61], v[8:11], v[52:55]
	ds_read_b128 v[58:61], v81 offset:21888
	s_waitcnt lgkmcnt(0)
	v_mfma_f32_16x16x32_f16 v[52:55], v[58:61], v[4:7], v[52:55]
	ds_read_b128 v[58:61], v81 offset:21952
	s_waitcnt lgkmcnt(0)
	v_mfma_f32_16x16x32_f16 v[52:55], v[58:61], v[0:3], v[52:55]
	ds_read_b128 v[58:61], v81 offset:26112
	s_waitcnt lgkmcnt(0)
	v_mfma_f32_16x16x32_f16 v[58:61], v[58:61], v[12:15], 0
	v_mfma_f32_16x16x32_f16 v[58:61], v[62:65], v[8:11], v[58:61]
	ds_read_b128 v[62:65], v81 offset:26240
	s_waitcnt lgkmcnt(0)
	v_mfma_f32_16x16x32_f16 v[58:61], v[62:65], v[4:7], v[58:61]
	ds_read_b128 v[62:65], v81 offset:26304
	s_waitcnt lgkmcnt(0)
	v_mfma_f32_16x16x32_f16 v[58:61], v[62:65], v[0:3], v[58:61]
	ds_read_b128 v[62:65], v81 offset:30464
	s_waitcnt lgkmcnt(0)
	v_mfma_f32_16x16x32_f16 v[12:15], v[62:65], v[12:15], 0
	ds_read_b128 v[62:65], v81 offset:30528
	s_waitcnt lgkmcnt(0)
	v_mfma_f32_16x16x32_f16 v[8:11], v[62:65], v[8:11], v[12:15]
	s_nop 4
	ds_read_b128 v[12:15], v81 offset:30592
	s_waitcnt lgkmcnt(0)
	v_mfma_f32_16x16x32_f16 v[4:7], v[12:15], v[4:7], v[8:11]
	s_nop 2
	ds_read_b128 v[8:11], v81 offset:30656
	v_mul_f32_e32 v12, 0x3db504f3, v58
	v_mul_f32_e32 v13, 0x3db504f3, v59
	s_waitcnt lgkmcnt(0)
	v_mfma_f32_16x16x32_f16 v[0:3], v[8:11], v[0:3], v[4:7]
	s_nop 2
	v_mul_f32_e32 v4, 0x3db504f3, v48
	v_mul_f32_e32 v5, 0x3db504f3, v49
	v_mul_f32_e32 v6, 0x3db504f3, v50
	v_mul_f32_e32 v7, 0x3db504f3, v51
	v_max3_f32 v4, v4, s4, v5
	v_mul_f32_e32 v8, 0x3db504f3, v52
	v_mul_f32_e32 v9, 0x3db504f3, v53
	v_max3_f32 v4, v4, v6, v7
	v_mul_f32_e32 v10, 0x3db504f3, v54
	v_mul_f32_e32 v11, 0x3db504f3, v55
	v_max3_f32 v4, v4, v8, v9
	v_max3_f32 v4, v4, v10, v11
	v_mul_f32_e32 v14, 0x3db504f3, v60
	v_mul_f32_e32 v15, 0x3db504f3, v61
	v_max3_f32 v4, v4, v12, v13
	v_mul_f32_e32 v56, 0x3db504f3, v0
	v_mul_f32_e32 v62, 0x3db504f3, v1
	v_max3_f32 v4, v4, v14, v15
	v_mul_f32_e32 v63, 0x3db504f3, v2
	v_mul_f32_e32 v64, 0x3db504f3, v3
	v_max3_f32 v4, v4, v56, v62
	v_max3_f32 v4, v4, v63, v64
	ds_bpermute_b32 v5, v117, v4
	s_waitcnt lgkmcnt(0)
	v_max_f32_e32 v5, v5, v5
	v_max_f32_e32 v4, v4, v5
	ds_bpermute_b32 v5, v119, v4
	s_waitcnt lgkmcnt(0)
	v_max3_f32 v6, v83, v4, v5
	v_fma_f32 v8, v52, s0, -v6
	v_mul_f32_e32 v8, 0x3fb8aa3b, v8
	v_exp_f32_e32 v107, v8
	v_fma_f32 v8, v53, s0, -v6
	v_mul_f32_e32 v8, 0x3fb8aa3b, v8
	v_exp_f32_e32 v109, v8
	v_fma_f32 v8, v54, s0, -v6
	v_mul_f32_e32 v8, 0x3fb8aa3b, v8
	v_exp_f32_e32 v111, v8
	v_fma_f32 v8, v55, s0, -v6
	v_mul_f32_e32 v8, 0x3fb8aa3b, v8
	v_sub_f32_e32 v4, v83, v6
	v_exp_f32_e32 v113, v8
	v_fma_f32 v8, v58, s0, -v6
	v_mul_f32_e32 v7, 0x3fb8aa3b, v4
	v_fma_f32 v4, v48, s0, -v6
	v_mul_f32_e32 v8, 0x3fb8aa3b, v8
	v_fma_f32 v0, v0, s0, -v6
	v_mul_f32_e32 v4, 0x3fb8aa3b, v4
	v_exp_f32_e32 v81, v8
	v_fma_f32 v8, v59, s0, -v6
	v_mul_f32_e32 v0, 0x3fb8aa3b, v0
	v_exp_f32_e32 v95, v4
	v_fma_f32 v4, v49, s0, -v6
	v_mul_f32_e32 v8, 0x3fb8aa3b, v8
	v_exp_f32_e32 v89, v0
	v_fma_f32 v0, v1, s0, -v6
	v_exp_f32_e32 v56, v7
	v_mul_f32_e32 v4, 0x3fb8aa3b, v4
	v_exp_f32_e32 v83, v8
	v_fma_f32 v8, v60, s0, -v6
	v_mul_f32_e32 v0, 0x3fb8aa3b, v0
	v_exp_f32_e32 v97, v4
	v_fma_f32 v4, v50, s0, -v6
	v_mul_f32_e32 v8, 0x3fb8aa3b, v8
	v_exp_f32_e32 v91, v0
	v_fma_f32 v0, v2, s0, -v6
	v_mul_f32_e32 v4, 0x3fb8aa3b, v4
	v_exp_f32_e32 v85, v8
	v_fma_f32 v8, v61, s0, -v6
	v_mul_f32_e32 v0, 0x3fb8aa3b, v0
	v_exp_f32_e32 v99, v4
	v_fma_f32 v4, v51, s0, -v6
	v_mul_f32_e32 v8, 0x3fb8aa3b, v8
	v_exp_f32_e32 v93, v0
	v_fma_f32 v0, v3, s0, -v6
	v_pk_mul_f32 v[6:7], v[42:43], v[56:57] op_sel_hi:[1,0]
	v_add_u32_e32 v42, 0xe000, v57
	v_exp_f32_e32 v87, v8
	v_pk_mul_f32 v[10:11], v[38:39], v[56:57] op_sel_hi:[1,0]
	v_pk_mul_f32 v[8:9], v[36:37], v[56:57] op_sel_hi:[1,0]
	ds_read2_b64 v[36:39], v42 offset0:64 offset1:68
	v_mul_f32_e32 v4, 0x3fb8aa3b, v4
	v_exp_f32_e32 v105, v4
	v_pk_add_f32 v[4:5], v[94:95], v[168:169]
	v_mul_f32_e32 v0, 0x3fb8aa3b, v0
	v_pk_add_f32 v[4:5], v[96:97], v[4:5]
	v_exp_f32_e32 v60, v0
	v_pk_add_f32 v[4:5], v[98:99], v[4:5]
	v_pk_mul_f32 v[50:51], v[22:23], v[56:57] op_sel_hi:[1,0]
	v_pk_add_f32 v[4:5], v[104:105], v[4:5]
	v_pk_mul_f32 v[48:49], v[20:21], v[56:57] op_sel_hi:[1,0]
	v_pk_add_f32 v[0:1], v[106:107], v[4:5]
	v_pk_mul_f32 v[22:23], v[26:27], v[56:57] op_sel_hi:[1,0]
	v_pk_add_f32 v[0:1], v[108:109], v[0:1]
	v_pk_mul_f32 v[20:21], v[24:25], v[56:57] op_sel_hi:[1,0]
	v_cvt_pk_f16_f32 v27, v111, v113
	v_cvt_pk_f16_f32 v26, v107, v109
	v_cvt_pk_f16_f32 v25, v99, v105
	v_cvt_pk_f16_f32 v24, v95, v97
	v_add_u32_e32 v43, 0xe800, v57
	v_pk_add_f32 v[0:1], v[110:111], v[0:1]
	s_waitcnt lgkmcnt(0)
	v_mfma_f32_16x16x32_f16 v[20:23], v[36:39], v[24:27], v[20:23]
	ds_read2_b64 v[36:39], v43 offset0:96 offset1:100
	v_pk_add_f32 v[0:1], v[112:113], v[0:1]
	v_pk_mul_f32 v[54:55], v[18:19], v[56:57] op_sel_hi:[1,0]
	v_pk_add_f32 v[0:1], v[80:81], v[0:1]
	v_pk_mul_f32 v[52:53], v[16:17], v[56:57] op_sel_hi:[1,0]
	v_pk_add_f32 v[0:1], v[82:83], v[0:1]
	v_pk_mul_f32 v[18:19], v[30:31], v[56:57] op_sel_hi:[1,0]
	v_pk_add_f32 v[0:1], v[84:85], v[0:1]
	v_pk_mul_f32 v[16:17], v[28:29], v[56:57] op_sel_hi:[1,0]
	v_pk_add_f32 v[0:1], v[86:87], v[0:1]
	v_pk_mul_f32 v[14:15], v[34:35], v[56:57] op_sel_hi:[1,0]
	v_pk_add_f32 v[0:1], v[88:89], v[0:1]
	s_waitcnt lgkmcnt(0)
	v_mfma_f32_16x16x32_f16 v[16:19], v[36:39], v[24:27], v[16:19]
	v_add_f32_e64 v0, v90, v0
	v_add_f32_e64 v1, v91, v1
	v_pk_mul_f32 v[12:13], v[32:33], v[56:57] op_sel_hi:[1,0]
	v_pk_add_f32 v[58:59], v[92:93], v[0:1]
	v_pk_mul_f32 v[0:1], v[44:45], v[56:57] op_sel_hi:[1,0]
	v_add_u32_e32 v44, 0xf000, v57
	ds_read2_b64 v[36:39], v44 offset0:128 offset1:132
	v_add_u32_e32 v45, 0xf800, v57
	s_waitcnt lgkmcnt(0)
	v_mfma_f32_16x16x32_f16 v[12:15], v[36:39], v[24:27], v[12:15]
	ds_read2_b64 v[36:39], v45 offset0:160 offset1:164
	v_pk_mul_f32 v[4:5], v[40:41], v[56:57] op_sel_hi:[1,0]
	v_add_u32_e32 v40, 0xd000, v57
	v_pk_mul_f32 v[2:3], v[46:47], v[56:57] op_sel_hi:[1,0]
	v_add_u32_e32 v46, 0x3000, v40
	s_waitcnt lgkmcnt(0)
	v_mfma_f32_16x16x32_f16 v[8:11], v[36:39], v[24:27], v[8:11]
	ds_read2_b64 v[36:39], v46 offset0:192 offset1:196
	v_add_u32_e32 v41, 0xd800, v57
	v_add_u32_e32 v47, 0x3800, v40
	ds_read2_b64 v[28:31], v40 offset1:4
	ds_read2_b64 v[32:35], v41 offset0:32 offset1:36
	s_waitcnt lgkmcnt(2)
	v_mfma_f32_16x16x32_f16 v[4:7], v[36:39], v[24:27], v[4:7]
	ds_read2_b64 v[36:39], v47 offset0:224 offset1:228
	v_readlane_b32 s0, v255, 59
	s_lshl_b32 s0, s0, 1
	s_waitcnt lgkmcnt(2)
	v_mfma_f32_16x16x32_f16 v[28:31], v[28:31], v[24:27], v[52:55]
	v_lshlrev_b32_e32 v168, 1, v115
	s_waitcnt lgkmcnt(1)
	v_mfma_f32_16x16x32_f16 v[32:35], v[32:35], v[24:27], v[48:51]
	s_waitcnt lgkmcnt(0)
	v_mfma_f32_16x16x32_f16 v[0:3], v[36:39], v[24:27], v[0:3]
	ds_read2_b64 v[24:27], v40 offset0:8 offset1:12
	v_cvt_pk_f16_f32 v39, v93, v60
	v_cvt_pk_f16_f32 v38, v89, v91
	v_cvt_pk_f16_f32 v37, v85, v87
	v_cvt_pk_f16_f32 v36, v81, v83
	s_waitcnt lgkmcnt(0)
	s_nop 0
	v_mfma_f32_16x16x32_f16 v[28:31], v[24:27], v[36:39], v[28:31]
	ds_read2_b64 v[24:27], v41 offset0:40 offset1:44
	s_waitcnt lgkmcnt(0)
	v_mfma_f32_16x16x32_f16 v[24:27], v[24:27], v[36:39], v[32:35]
	s_nop 2
	ds_read2_b64 v[32:35], v42 offset0:72 offset1:76
	s_waitcnt lgkmcnt(0)
	v_mfma_f32_16x16x32_f16 v[20:23], v[32:35], v[36:39], v[20:23]
	ds_read2_b64 v[32:35], v43 offset0:104 offset1:108
	s_waitcnt lgkmcnt(0)
	v_mfma_f32_16x16x32_f16 v[16:19], v[32:35], v[36:39], v[16:19]
	ds_read2_b64 v[32:35], v44 offset0:136 offset1:140
	s_waitcnt lgkmcnt(0)
	v_mfma_f32_16x16x32_f16 v[12:15], v[32:35], v[36:39], v[12:15]
	ds_read2_b64 v[32:35], v45 offset0:168 offset1:172
	s_waitcnt lgkmcnt(0)
	v_mfma_f32_16x16x32_f16 v[8:11], v[32:35], v[36:39], v[8:11]
	ds_read2_b64 v[32:35], v46 offset0:200 offset1:204
	s_waitcnt lgkmcnt(0)
	v_mfma_f32_16x16x32_f16 v[4:7], v[32:35], v[36:39], v[4:7]
	ds_read2_b64 v[32:35], v47 offset0:232 offset1:236
	s_waitcnt lgkmcnt(0)
	s_barrier
	v_mfma_f32_16x16x32_f16 v[0:3], v[32:35], v[36:39], v[0:3]
	v_add_f32_e32 v32, v59, v60
	v_fmac_f32_e32 v32, v58, v56
	ds_bpermute_b32 v33, v117, v32
	s_waitcnt lgkmcnt(0)
	v_add_f32_e32 v32, v32, v33
	ds_bpermute_b32 v33, v119, v32
	s_waitcnt lgkmcnt(0)
	v_add_f32_e32 v32, v32, v33
	v_div_scale_f32 v33, s[4:5], v32, v32, 1.0
	v_rcp_f32_e32 v34, v33
	s_mov_b64 s[4:5], 0x2c20
	v_fma_f32 v35, -v33, v34, 1.0
	v_fmac_f32_e32 v34, v35, v34
	v_div_scale_f32 v35, vcc, 1.0, v32, 1.0
	v_mul_f32_e32 v36, v35, v34
	v_fma_f32 v37, -v33, v36, v35
	v_fmac_f32_e32 v36, v37, v34
	v_fma_f32 v33, -v33, v36, v35
	v_div_fmas_f32 v33, v33, v34, v36
	v_lshl_add_u64 v[34:35], v[102:103], 0, s[0:1]
	v_lshl_add_u64 v[38:39], v[34:35], 0, v[168:169]
	v_lshl_add_u64 v[34:35], v[38:39], 0, s[4:5]
	v_add_co_u32_e32 v38, vcc, s33, v38
	v_div_fixup_f32 v32, v33, v32, 1.0
	s_nop 0
	v_addc_co_u32_e32 v39, vcc, 0, v39, vcc
	global_load_dwordx2 v[38:39], v[38:39], off offset:3104
	v_lshlrev_b64 v[36:37], 12, v[100:101]
	v_lshl_add_u64 v[36:37], s[20:21], 0, v[36:37]
	v_lshl_add_u64 v[36:37], v[36:37], 0, s[0:1]
	s_mov_b32 s0, 0x4800000
	s_waitcnt vmcnt(0)
	v_cvt_f32_f16_sdwa v33, v38 dst_sel:DWORD dst_unused:UNUSED_PAD src0_sel:WORD_1
	v_cvt_f32_f16_e32 v38, v38
	v_mul_f32_e32 v41, 0xbfb8aa3b, v33
	v_mul_f32_e32 v40, 0xbfb8aa3b, v38
	v_exp_f32_e32 v40, v40
	v_exp_f32_e32 v41, v41
	v_pk_mul_f32 v[28:29], v[28:29], v[32:33] op_sel_hi:[1,0]
	v_pk_add_f32 v[40:41], v[40:41], 1.0 op_sel_hi:[1,0]
	s_nop 0
	v_div_scale_f32 v42, s[4:5], v41, v41, v33
	v_rcp_f32_e32 v43, v42
	s_nop 0
	v_fma_f32 v44, -v42, v43, 1.0
	v_fmac_f32_e32 v43, v44, v43
	v_div_scale_f32 v44, vcc, v33, v41, v33
	v_mul_f32_e32 v45, v44, v43
	v_fma_f32 v46, -v42, v45, v44
	v_fmac_f32_e32 v45, v46, v43
	v_fma_f32 v42, -v42, v45, v44
	v_div_fmas_f32 v42, v42, v43, v45
	v_div_fixup_f32 v41, v42, v41, v33
	v_div_scale_f32 v33, s[4:5], v40, v40, v38
	v_rcp_f32_e32 v42, v33
	s_nop 0
	v_fma_f32 v43, -v33, v42, 1.0
	v_fmac_f32_e32 v42, v43, v42
	v_div_scale_f32 v43, vcc, v38, v40, v38
	v_mul_f32_e32 v44, v43, v42
	v_fma_f32 v45, -v33, v44, v43
	v_fmac_f32_e32 v44, v45, v42
	v_fma_f32 v33, -v33, v44, v43
	v_div_fmas_f32 v33, v33, v42, v44
	v_div_fixup_f32 v40, v33, v40, v38
	v_cvt_f32_f16_sdwa v33, v39 dst_sel:DWORD dst_unused:UNUSED_PAD src0_sel:WORD_1
	v_cvt_f32_f16_e32 v39, v39
	v_pk_mul_f32 v[28:29], v[28:29], v[40:41]
	v_pk_mul_f32 v[30:31], v[30:31], v[32:33] op_sel_hi:[1,0]
	v_cvt_pk_f16_f32 v38, v28, v29
	v_mul_f32_e32 v28, 0xbfb8aa3b, v39
	v_mul_f32_e32 v29, 0xbfb8aa3b, v33
	v_exp_f32_e32 v28, v28
	v_exp_f32_e32 v29, v29
	s_nop 0
	v_pk_add_f32 v[28:29], v[28:29], 1.0 op_sel_hi:[1,0]
	s_nop 0
	v_div_scale_f32 v40, s[4:5], v29, v29, v33
	v_rcp_f32_e32 v41, v40
	s_nop 0
	v_fma_f32 v42, -v40, v41, 1.0
	v_fmac_f32_e32 v41, v42, v41
	v_div_scale_f32 v42, vcc, v33, v29, v33
	v_mul_f32_e32 v43, v42, v41
	v_fma_f32 v44, -v40, v43, v42
	v_fmac_f32_e32 v43, v44, v41
	v_fma_f32 v40, -v40, v43, v42
	v_div_fmas_f32 v40, v40, v41, v43
	v_div_fixup_f32 v29, v40, v29, v33
	v_div_scale_f32 v33, s[4:5], v28, v28, v39
	v_rcp_f32_e32 v40, v33
	s_mov_b64 s[4:5], 0x4800300
	v_fma_f32 v41, -v33, v40, 1.0
	v_fmac_f32_e32 v40, v41, v40
	v_div_scale_f32 v41, vcc, v39, v28, v39
	v_mul_f32_e32 v42, v41, v40
	v_fma_f32 v43, -v33, v42, v41
	v_fmac_f32_e32 v42, v43, v40
	v_fma_f32 v33, -v33, v42, v41
	v_div_fmas_f32 v33, v33, v40, v42
	v_div_fixup_f32 v28, v33, v28, v39
	v_pk_mul_f32 v[28:29], v[30:31], v[28:29]
	v_lshl_add_u64 v[30:31], v[36:37], 0, v[168:169]
	v_cvt_pk_f16_f32 v39, v28, v29
	v_lshl_add_u64 v[28:29], v[30:31], 0, s[4:5]
	v_add_co_u32_e32 v30, vcc, s0, v30
	s_nop 1
	v_addc_co_u32_e32 v31, vcc, 0, v31, vcc
	global_load_dwordx2 v[60:61], v[34:35], off offset:32
	global_load_dwordx2 v[62:63], v[34:35], off offset:64
	global_load_dwordx2 v[64:65], v[34:35], off offset:96
	global_load_dwordx2 v[66:67], v[34:35], off offset:128
	global_load_dwordx2 v[68:69], v[34:35], off offset:160
	global_load_dwordx2 v[70:71], v[34:35], off offset:192
	global_load_dwordx2 v[72:73], v[34:35], off offset:224
	global_store_dwordx2 v[30:31], v[38:39], off offset:768
	s_waitcnt vmcnt(7)
	v_cvt_f32_f16_sdwa v33, v60 dst_sel:DWORD dst_unused:UNUSED_PAD src0_sel:WORD_1
	v_cvt_f32_f16_e32 v30, v60
	v_mul_f32_e32 v37, 0xbfb8aa3b, v33
	v_mul_f32_e32 v36, 0xbfb8aa3b, v30
	v_exp_f32_e32 v36, v36
	v_exp_f32_e32 v37, v37
	v_pk_mul_f32 v[24:25], v[24:25], v[32:33] op_sel_hi:[1,0]
	v_pk_add_f32 v[36:37], v[36:37], 1.0 op_sel_hi:[1,0]
	s_nop 0
	v_div_scale_f32 v38, s[4:5], v37, v37, v33
	v_rcp_f32_e32 v39, v38
	s_nop 0
	v_fma_f32 v40, -v38, v39, 1.0
	v_fmac_f32_e32 v39, v40, v39
	v_div_scale_f32 v40, vcc, v33, v37, v33
	v_mul_f32_e32 v41, v40, v39
	v_fma_f32 v42, -v38, v41, v40
	v_fmac_f32_e32 v41, v42, v39
	v_fma_f32 v38, -v38, v41, v40
	v_div_fmas_f32 v38, v38, v39, v41
	v_div_fixup_f32 v37, v38, v37, v33
	v_div_scale_f32 v33, s[4:5], v36, v36, v30
	v_rcp_f32_e32 v38, v33
	s_nop 0
	v_fma_f32 v39, -v33, v38, 1.0
	v_fmac_f32_e32 v38, v39, v38
	v_div_scale_f32 v39, vcc, v30, v36, v30
	v_mul_f32_e32 v40, v39, v38
	v_fma_f32 v41, -v33, v40, v39
	v_fmac_f32_e32 v40, v41, v38
	v_fma_f32 v33, -v33, v40, v39
	v_div_fmas_f32 v33, v33, v38, v40
	v_div_fixup_f32 v36, v33, v36, v30
	v_pk_mul_f32 v[24:25], v[24:25], v[36:37]
	v_cvt_f32_f16_e32 v33, v61
	v_cvt_pk_f16_f32 v24, v24, v25
	v_cvt_f32_f16_sdwa v25, v61 dst_sel:DWORD dst_unused:UNUSED_PAD src0_sel:WORD_1
	v_mul_f32_e32 v30, 0xbfb8aa3b, v33
	v_exp_f32_e32 v30, v30
	v_mul_f32_e32 v31, 0xbfb8aa3b, v25
	v_exp_f32_e32 v31, v31
	v_pk_mul_f32 v[26:27], v[26:27], v[32:33] op_sel_hi:[1,0]
	v_pk_mul_f32 v[20:21], v[20:21], v[32:33] op_sel_hi:[1,0]
	v_pk_add_f32 v[30:31], v[30:31], 1.0 op_sel_hi:[1,0]
	s_nop 0
	v_div_scale_f32 v36, s[4:5], v31, v31, v25
	v_rcp_f32_e32 v37, v36
	s_nop 0
	v_fma_f32 v38, -v36, v37, 1.0
	v_fmac_f32_e32 v37, v38, v37
	v_div_scale_f32 v38, vcc, v25, v31, v25
	v_mul_f32_e32 v39, v38, v37
	v_fma_f32 v40, -v36, v39, v38
	v_fmac_f32_e32 v39, v40, v37
	v_fma_f32 v36, -v36, v39, v38
	v_div_fmas_f32 v36, v36, v37, v39
	v_div_fixup_f32 v31, v36, v31, v25
	v_div_scale_f32 v25, s[4:5], v30, v30, v33
	v_rcp_f32_e32 v36, v25
	s_nop 0
	v_fma_f32 v37, -v25, v36, 1.0
	v_fmac_f32_e32 v36, v37, v36
	v_div_scale_f32 v37, vcc, v33, v30, v33
	v_mul_f32_e32 v38, v37, v36
	v_fma_f32 v39, -v25, v38, v37
	v_fmac_f32_e32 v38, v39, v36
	v_fma_f32 v25, -v25, v38, v37
	v_div_fmas_f32 v25, v25, v36, v38
	v_div_fixup_f32 v30, v25, v30, v33
	v_pk_mul_f32 v[26:27], v[26:27], v[30:31]
	s_nop 0
	v_cvt_pk_f16_f32 v25, v26, v27
	global_store_dwordx2 v[28:29], v[24:25], off offset:32
	s_waitcnt vmcnt(7)
	v_cvt_f32_f16_sdwa v30, v62 dst_sel:DWORD dst_unused:UNUSED_PAD src0_sel:WORD_1
	v_cvt_f32_f16_e32 v24, v62
	v_mul_f32_e32 v27, 0xbfb8aa3b, v30
	v_mul_f32_e32 v26, 0xbfb8aa3b, v24
	v_exp_f32_e32 v26, v26
	v_exp_f32_e32 v27, v27
	s_nop 0
	v_pk_add_f32 v[26:27], v[26:27], 1.0 op_sel_hi:[1,0]
	s_nop 0
	v_div_scale_f32 v31, s[4:5], v27, v27, v30
	v_rcp_f32_e32 v33, v31
	s_nop 0
	v_fma_f32 v36, -v31, v33, 1.0
	v_fmac_f32_e32 v33, v36, v33
	v_div_scale_f32 v36, vcc, v30, v27, v30
	v_mul_f32_e32 v37, v36, v33
	v_fma_f32 v38, -v31, v37, v36
	v_fmac_f32_e32 v37, v38, v33
	v_fma_f32 v31, -v31, v37, v36
	v_div_fmas_f32 v31, v31, v33, v37
	v_div_fixup_f32 v27, v31, v27, v30
	v_div_scale_f32 v30, s[4:5], v26, v26, v24
	v_rcp_f32_e32 v31, v30
	s_nop 0
	v_fma_f32 v33, -v30, v31, 1.0
	v_fmac_f32_e32 v31, v33, v31
	v_div_scale_f32 v33, vcc, v24, v26, v24
	v_mul_f32_e32 v36, v33, v31
	v_fma_f32 v37, -v30, v36, v33
	v_fmac_f32_e32 v36, v37, v31
	v_fma_f32 v30, -v30, v36, v33
	v_div_fmas_f32 v30, v30, v31, v36
	v_div_fixup_f32 v26, v30, v26, v24
	v_pk_mul_f32 v[20:21], v[20:21], v[26:27]
	v_cvt_f32_f16_e32 v26, v63
	v_cvt_pk_f16_f32 v20, v20, v21
	v_cvt_f32_f16_sdwa v21, v63 dst_sel:DWORD dst_unused:UNUSED_PAD src0_sel:WORD_1
	v_pk_mul_f32 v[22:23], v[22:23], v[32:33] op_sel_hi:[1,0]
	v_mul_f32_e32 v24, 0xbfb8aa3b, v26
	v_exp_f32_e32 v24, v24
	v_mul_f32_e32 v25, 0xbfb8aa3b, v21
	v_exp_f32_e32 v25, v25
	s_nop 0
	v_pk_add_f32 v[24:25], v[24:25], 1.0 op_sel_hi:[1,0]
	s_nop 0
	v_div_scale_f32 v27, s[4:5], v25, v25, v21
	v_rcp_f32_e32 v30, v27
	s_nop 0
	v_fma_f32 v31, -v27, v30, 1.0
	v_fmac_f32_e32 v30, v31, v30
	v_div_scale_f32 v31, vcc, v21, v25, v21
	v_mul_f32_e32 v33, v31, v30
	v_fma_f32 v36, -v27, v33, v31
	v_fmac_f32_e32 v33, v36, v30
	v_fma_f32 v27, -v27, v33, v31
	v_div_fmas_f32 v27, v27, v30, v33
	v_div_fixup_f32 v25, v27, v25, v21
	v_div_scale_f32 v21, s[4:5], v24, v24, v26
	v_rcp_f32_e32 v27, v21
	s_nop 0
	v_fma_f32 v30, -v21, v27, 1.0
	v_fmac_f32_e32 v27, v30, v27
	v_div_scale_f32 v30, vcc, v26, v24, v26
	v_mul_f32_e32 v31, v30, v27
	v_fma_f32 v33, -v21, v31, v30
	v_fmac_f32_e32 v31, v33, v27
	v_fma_f32 v21, -v21, v31, v30
	v_div_fmas_f32 v21, v21, v27, v31
	v_div_fixup_f32 v24, v21, v24, v26
	v_pk_mul_f32 v[22:23], v[22:23], v[24:25]
	v_pk_mul_f32 v[16:17], v[16:17], v[32:33] op_sel_hi:[1,0]
	v_cvt_pk_f16_f32 v21, v22, v23
	global_store_dwordx2 v[28:29], v[20:21], off offset:64
	v_pk_mul_f32 v[18:19], v[18:19], v[32:33] op_sel_hi:[1,0]
	v_pk_mul_f32 v[12:13], v[12:13], v[32:33] op_sel_hi:[1,0]
	v_pk_mul_f32 v[14:15], v[14:15], v[32:33] op_sel_hi:[1,0]
	v_pk_mul_f32 v[8:9], v[8:9], v[32:33] op_sel_hi:[1,0]
	v_pk_mul_f32 v[10:11], v[10:11], v[32:33] op_sel_hi:[1,0]
	v_pk_mul_f32 v[4:5], v[4:5], v[32:33] op_sel_hi:[1,0]
	v_pk_mul_f32 v[6:7], v[6:7], v[32:33] op_sel_hi:[1,0]
	v_pk_mul_f32 v[0:1], v[0:1], v[32:33] op_sel_hi:[1,0]
	v_pk_mul_f32 v[2:3], v[2:3], v[32:33] op_sel_hi:[1,0]
	s_waitcnt vmcnt(7)
	v_cvt_f32_f16_sdwa v24, v64 dst_sel:DWORD dst_unused:UNUSED_PAD src0_sel:WORD_1
	v_cvt_f32_f16_e32 v20, v64
	v_mul_f32_e32 v23, 0xbfb8aa3b, v24
	v_mul_f32_e32 v22, 0xbfb8aa3b, v20
	v_exp_f32_e32 v22, v22
	v_exp_f32_e32 v23, v23
	s_nop 0
	v_pk_add_f32 v[22:23], v[22:23], 1.0 op_sel_hi:[1,0]
	s_nop 0
	v_div_scale_f32 v25, s[4:5], v23, v23, v24
	v_rcp_f32_e32 v26, v25
	s_nop 0
	v_fma_f32 v27, -v25, v26, 1.0
	v_fmac_f32_e32 v26, v27, v26
	v_div_scale_f32 v27, vcc, v24, v23, v24
	v_mul_f32_e32 v30, v27, v26
	v_fma_f32 v31, -v25, v30, v27
	v_fmac_f32_e32 v30, v31, v26
	v_fma_f32 v25, -v25, v30, v27
	v_div_fmas_f32 v25, v25, v26, v30
	v_div_fixup_f32 v23, v25, v23, v24
	v_div_scale_f32 v24, s[4:5], v22, v22, v20
	v_rcp_f32_e32 v25, v24
	s_nop 0
	v_fma_f32 v26, -v24, v25, 1.0
	v_fmac_f32_e32 v25, v26, v25
	v_div_scale_f32 v26, vcc, v20, v22, v20
	v_mul_f32_e32 v27, v26, v25
	v_fma_f32 v30, -v24, v27, v26
	v_fmac_f32_e32 v27, v30, v25
	v_fma_f32 v24, -v24, v27, v26
	v_div_fmas_f32 v24, v24, v25, v27
	v_div_fixup_f32 v22, v24, v22, v20
	v_pk_mul_f32 v[16:17], v[16:17], v[22:23]
	v_cvt_f32_f16_e32 v22, v65
	v_cvt_pk_f16_f32 v16, v16, v17
	v_cvt_f32_f16_sdwa v17, v65 dst_sel:DWORD dst_unused:UNUSED_PAD src0_sel:WORD_1
	v_mul_f32_e32 v20, 0xbfb8aa3b, v22
	v_exp_f32_e32 v20, v20
	v_mul_f32_e32 v21, 0xbfb8aa3b, v17
	v_exp_f32_e32 v21, v21
	s_nop 0
	v_pk_add_f32 v[20:21], v[20:21], 1.0 op_sel_hi:[1,0]
	s_nop 0
	v_div_scale_f32 v23, s[4:5], v21, v21, v17
	v_rcp_f32_e32 v24, v23
	s_nop 0
	v_fma_f32 v25, -v23, v24, 1.0
	v_fmac_f32_e32 v24, v25, v24
	v_div_scale_f32 v25, vcc, v17, v21, v17
	v_mul_f32_e32 v26, v25, v24
	v_fma_f32 v27, -v23, v26, v25
	v_fmac_f32_e32 v26, v27, v24
	v_fma_f32 v23, -v23, v26, v25
	v_div_fmas_f32 v23, v23, v24, v26
	v_div_fixup_f32 v21, v23, v21, v17
	v_div_scale_f32 v17, s[4:5], v20, v20, v22
	v_rcp_f32_e32 v23, v17
	s_nop 0
	v_fma_f32 v24, -v17, v23, 1.0
	v_fmac_f32_e32 v23, v24, v23
	v_div_scale_f32 v24, vcc, v22, v20, v22
	v_mul_f32_e32 v25, v24, v23
	v_fma_f32 v26, -v17, v25, v24
	v_fmac_f32_e32 v25, v26, v23
	v_fma_f32 v17, -v17, v25, v24
	v_div_fmas_f32 v17, v17, v23, v25
	v_div_fixup_f32 v20, v17, v20, v22
	v_pk_mul_f32 v[18:19], v[18:19], v[20:21]
	s_nop 0
	v_cvt_pk_f16_f32 v17, v18, v19
	global_store_dwordx2 v[28:29], v[16:17], off offset:96
	s_waitcnt vmcnt(7)
	v_cvt_f32_f16_sdwa v20, v66 dst_sel:DWORD dst_unused:UNUSED_PAD src0_sel:WORD_1
	v_cvt_f32_f16_e32 v16, v66
	v_mul_f32_e32 v19, 0xbfb8aa3b, v20
	v_mul_f32_e32 v18, 0xbfb8aa3b, v16
	v_exp_f32_e32 v18, v18
	v_exp_f32_e32 v19, v19
	s_nop 0
	v_pk_add_f32 v[18:19], v[18:19], 1.0 op_sel_hi:[1,0]
	s_nop 0
	v_div_scale_f32 v21, s[4:5], v19, v19, v20
	v_rcp_f32_e32 v22, v21
	s_nop 0
	v_fma_f32 v23, -v21, v22, 1.0
	v_fmac_f32_e32 v22, v23, v22
	v_div_scale_f32 v23, vcc, v20, v19, v20
	v_mul_f32_e32 v24, v23, v22
	v_fma_f32 v25, -v21, v24, v23
	v_fmac_f32_e32 v24, v25, v22
	v_fma_f32 v21, -v21, v24, v23
	v_div_fmas_f32 v21, v21, v22, v24
	v_div_fixup_f32 v19, v21, v19, v20
	v_div_scale_f32 v20, s[4:5], v18, v18, v16
	v_rcp_f32_e32 v21, v20
	s_nop 0
	v_fma_f32 v22, -v20, v21, 1.0
	v_fmac_f32_e32 v21, v22, v21
	v_div_scale_f32 v22, vcc, v16, v18, v16
	v_mul_f32_e32 v23, v22, v21
	v_fma_f32 v24, -v20, v23, v22
	v_fmac_f32_e32 v23, v24, v21
	v_fma_f32 v20, -v20, v23, v22
	v_div_fmas_f32 v20, v20, v21, v23
	v_div_fixup_f32 v18, v20, v18, v16
	v_pk_mul_f32 v[12:13], v[12:13], v[18:19]
	v_cvt_f32_f16_e32 v18, v67
	v_cvt_pk_f16_f32 v12, v12, v13
	v_cvt_f32_f16_sdwa v13, v67 dst_sel:DWORD dst_unused:UNUSED_PAD src0_sel:WORD_1
	v_mul_f32_e32 v16, 0xbfb8aa3b, v18
	v_exp_f32_e32 v16, v16
	v_mul_f32_e32 v17, 0xbfb8aa3b, v13
	v_exp_f32_e32 v17, v17
	s_nop 0
	v_pk_add_f32 v[16:17], v[16:17], 1.0 op_sel_hi:[1,0]
	s_nop 0
	v_div_scale_f32 v19, s[4:5], v17, v17, v13
	v_rcp_f32_e32 v20, v19
	s_nop 0
	v_fma_f32 v21, -v19, v20, 1.0
	v_fmac_f32_e32 v20, v21, v20
	v_div_scale_f32 v21, vcc, v13, v17, v13
	v_mul_f32_e32 v22, v21, v20
	v_fma_f32 v23, -v19, v22, v21
	v_fmac_f32_e32 v22, v23, v20
	v_fma_f32 v19, -v19, v22, v21
	v_div_fmas_f32 v19, v19, v20, v22
	v_div_fixup_f32 v17, v19, v17, v13
	v_div_scale_f32 v13, s[4:5], v16, v16, v18
	v_rcp_f32_e32 v19, v13
	s_nop 0
	v_fma_f32 v20, -v13, v19, 1.0
	v_fmac_f32_e32 v19, v20, v19
	v_div_scale_f32 v20, vcc, v18, v16, v18
	v_mul_f32_e32 v21, v20, v19
	v_fma_f32 v22, -v13, v21, v20
	v_fmac_f32_e32 v21, v22, v19
	v_fma_f32 v13, -v13, v21, v20
	v_div_fmas_f32 v13, v13, v19, v21
	v_div_fixup_f32 v16, v13, v16, v18
	v_pk_mul_f32 v[14:15], v[14:15], v[16:17]
	s_nop 0
	v_cvt_pk_f16_f32 v13, v14, v15
	global_store_dwordx2 v[28:29], v[12:13], off offset:128
	s_waitcnt vmcnt(7)
	v_cvt_f32_f16_sdwa v16, v68 dst_sel:DWORD dst_unused:UNUSED_PAD src0_sel:WORD_1
	v_cvt_f32_f16_e32 v12, v68
	v_mul_f32_e32 v15, 0xbfb8aa3b, v16
	v_mul_f32_e32 v14, 0xbfb8aa3b, v12
	v_exp_f32_e32 v14, v14
	v_exp_f32_e32 v15, v15
	s_nop 0
	v_pk_add_f32 v[14:15], v[14:15], 1.0 op_sel_hi:[1,0]
	s_nop 0
	v_div_scale_f32 v17, s[4:5], v15, v15, v16
	v_rcp_f32_e32 v18, v17
	s_nop 0
	v_fma_f32 v19, -v17, v18, 1.0
	v_fmac_f32_e32 v18, v19, v18
	v_div_scale_f32 v19, vcc, v16, v15, v16
	v_mul_f32_e32 v20, v19, v18
	v_fma_f32 v21, -v17, v20, v19
	v_fmac_f32_e32 v20, v21, v18
	v_fma_f32 v17, -v17, v20, v19
	v_div_fmas_f32 v17, v17, v18, v20
	v_div_fixup_f32 v15, v17, v15, v16
	v_div_scale_f32 v16, s[4:5], v14, v14, v12
	v_rcp_f32_e32 v17, v16
	s_nop 0
	v_fma_f32 v18, -v16, v17, 1.0
	v_fmac_f32_e32 v17, v18, v17
	v_div_scale_f32 v18, vcc, v12, v14, v12
	v_mul_f32_e32 v19, v18, v17
	v_fma_f32 v20, -v16, v19, v18
	v_fmac_f32_e32 v19, v20, v17
	v_fma_f32 v16, -v16, v19, v18
	v_div_fmas_f32 v16, v16, v17, v19
	v_div_fixup_f32 v14, v16, v14, v12
	v_pk_mul_f32 v[8:9], v[8:9], v[14:15]
	v_cvt_f32_f16_e32 v14, v69
	v_cvt_pk_f16_f32 v8, v8, v9
	v_cvt_f32_f16_sdwa v9, v69 dst_sel:DWORD dst_unused:UNUSED_PAD src0_sel:WORD_1
	v_mul_f32_e32 v12, 0xbfb8aa3b, v14
	v_exp_f32_e32 v12, v12
	v_mul_f32_e32 v13, 0xbfb8aa3b, v9
	v_exp_f32_e32 v13, v13
	s_nop 0
	v_pk_add_f32 v[12:13], v[12:13], 1.0 op_sel_hi:[1,0]
	s_nop 0
	v_div_scale_f32 v15, s[4:5], v13, v13, v9
	v_rcp_f32_e32 v16, v15
	s_nop 0
	v_fma_f32 v17, -v15, v16, 1.0
	v_fmac_f32_e32 v16, v17, v16
	v_div_scale_f32 v17, vcc, v9, v13, v9
	v_mul_f32_e32 v18, v17, v16
	v_fma_f32 v19, -v15, v18, v17
	v_fmac_f32_e32 v18, v19, v16
	v_fma_f32 v15, -v15, v18, v17
	v_div_fmas_f32 v15, v15, v16, v18
	v_div_fixup_f32 v13, v15, v13, v9
	v_div_scale_f32 v9, s[4:5], v12, v12, v14
	v_rcp_f32_e32 v15, v9
	s_nop 0
	v_fma_f32 v16, -v9, v15, 1.0
	v_fmac_f32_e32 v15, v16, v15
	v_div_scale_f32 v16, vcc, v14, v12, v14
	v_mul_f32_e32 v17, v16, v15
	v_fma_f32 v18, -v9, v17, v16
	v_fmac_f32_e32 v17, v18, v15
	v_fma_f32 v9, -v9, v17, v16
	v_div_fmas_f32 v9, v9, v15, v17
	v_div_fixup_f32 v12, v9, v12, v14
	v_pk_mul_f32 v[10:11], v[10:11], v[12:13]
	s_nop 0
	v_cvt_pk_f16_f32 v9, v10, v11
	global_store_dwordx2 v[28:29], v[8:9], off offset:160
	s_waitcnt vmcnt(7)
	v_cvt_f32_f16_sdwa v12, v70 dst_sel:DWORD dst_unused:UNUSED_PAD src0_sel:WORD_1
	v_cvt_f32_f16_e32 v8, v70
	v_mul_f32_e32 v11, 0xbfb8aa3b, v12
	v_mul_f32_e32 v10, 0xbfb8aa3b, v8
	v_exp_f32_e32 v10, v10
	v_exp_f32_e32 v11, v11
	s_nop 0
	v_pk_add_f32 v[10:11], v[10:11], 1.0 op_sel_hi:[1,0]
	s_nop 0
	v_div_scale_f32 v13, s[4:5], v11, v11, v12
	v_rcp_f32_e32 v14, v13
	s_nop 0
	v_fma_f32 v15, -v13, v14, 1.0
	v_fmac_f32_e32 v14, v15, v14
	v_div_scale_f32 v15, vcc, v12, v11, v12
	v_mul_f32_e32 v16, v15, v14
	v_fma_f32 v17, -v13, v16, v15
	v_fmac_f32_e32 v16, v17, v14
	v_fma_f32 v13, -v13, v16, v15
	v_div_fmas_f32 v13, v13, v14, v16
	v_div_fixup_f32 v11, v13, v11, v12
	v_div_scale_f32 v12, s[4:5], v10, v10, v8
	v_rcp_f32_e32 v13, v12
	s_nop 0
	v_fma_f32 v14, -v12, v13, 1.0
	v_fmac_f32_e32 v13, v14, v13
	v_div_scale_f32 v14, vcc, v8, v10, v8
	v_mul_f32_e32 v15, v14, v13
	v_fma_f32 v16, -v12, v15, v14
	v_fmac_f32_e32 v15, v16, v13
	v_fma_f32 v12, -v12, v15, v14
	v_div_fmas_f32 v12, v12, v13, v15
	v_div_fixup_f32 v10, v12, v10, v8
	v_pk_mul_f32 v[4:5], v[4:5], v[10:11]
	v_cvt_f32_f16_e32 v10, v71
	v_cvt_pk_f16_f32 v4, v4, v5
	v_cvt_f32_f16_sdwa v5, v71 dst_sel:DWORD dst_unused:UNUSED_PAD src0_sel:WORD_1
	v_mul_f32_e32 v8, 0xbfb8aa3b, v10
	v_exp_f32_e32 v8, v8
	v_mul_f32_e32 v9, 0xbfb8aa3b, v5
	v_exp_f32_e32 v9, v9
	s_nop 0
	v_pk_add_f32 v[8:9], v[8:9], 1.0 op_sel_hi:[1,0]
	s_nop 0
	v_div_scale_f32 v11, s[4:5], v9, v9, v5
	v_rcp_f32_e32 v12, v11
	s_nop 0
	v_fma_f32 v13, -v11, v12, 1.0
	v_fmac_f32_e32 v12, v13, v12
	v_div_scale_f32 v13, vcc, v5, v9, v5
	v_mul_f32_e32 v14, v13, v12
	v_fma_f32 v15, -v11, v14, v13
	v_fmac_f32_e32 v14, v15, v12
	v_fma_f32 v11, -v11, v14, v13
	v_div_fmas_f32 v11, v11, v12, v14
	v_div_fixup_f32 v9, v11, v9, v5
	v_div_scale_f32 v5, s[4:5], v8, v8, v10
	v_rcp_f32_e32 v11, v5
	s_nop 0
	v_fma_f32 v12, -v5, v11, 1.0
	v_fmac_f32_e32 v11, v12, v11
	v_div_scale_f32 v12, vcc, v10, v8, v10
	v_mul_f32_e32 v13, v12, v11
	v_fma_f32 v14, -v5, v13, v12
	v_fmac_f32_e32 v13, v14, v11
	v_fma_f32 v5, -v5, v13, v12
	v_div_fmas_f32 v5, v5, v11, v13
	v_div_fixup_f32 v8, v5, v8, v10
	v_pk_mul_f32 v[6:7], v[6:7], v[8:9]
	s_nop 0
	v_cvt_pk_f16_f32 v5, v6, v7
	global_store_dwordx2 v[28:29], v[4:5], off offset:192
	s_waitcnt vmcnt(7)
	v_cvt_f32_f16_sdwa v8, v72 dst_sel:DWORD dst_unused:UNUSED_PAD src0_sel:WORD_1
	v_cvt_f32_f16_e32 v4, v72
	v_mul_f32_e32 v7, 0xbfb8aa3b, v8
	v_mul_f32_e32 v6, 0xbfb8aa3b, v4
	v_exp_f32_e32 v6, v6
	v_exp_f32_e32 v7, v7
	s_nop 0
	v_pk_add_f32 v[6:7], v[6:7], 1.0 op_sel_hi:[1,0]
	s_nop 0
	v_div_scale_f32 v9, s[4:5], v7, v7, v8
	v_rcp_f32_e32 v10, v9
	s_nop 0
	v_fma_f32 v11, -v9, v10, 1.0
	v_fmac_f32_e32 v10, v11, v10
	v_div_scale_f32 v11, vcc, v8, v7, v8
	v_mul_f32_e32 v12, v11, v10
	v_fma_f32 v13, -v9, v12, v11
	v_fmac_f32_e32 v12, v13, v10
	v_fma_f32 v9, -v9, v12, v11
	v_div_fmas_f32 v9, v9, v10, v12
	v_div_fixup_f32 v7, v9, v7, v8
	v_div_scale_f32 v8, s[4:5], v6, v6, v4
	v_rcp_f32_e32 v9, v8
	s_nop 0
	v_fma_f32 v10, -v8, v9, 1.0
	v_fmac_f32_e32 v9, v10, v9
	v_div_scale_f32 v10, vcc, v4, v6, v4
	v_mul_f32_e32 v11, v10, v9
	v_fma_f32 v12, -v8, v11, v10
	v_fmac_f32_e32 v11, v12, v9
	v_fma_f32 v8, -v8, v11, v10
	v_div_fmas_f32 v8, v8, v9, v11
	v_div_fixup_f32 v6, v8, v6, v4
	v_pk_mul_f32 v[0:1], v[0:1], v[6:7]
	v_cvt_f32_f16_e32 v6, v73
	v_cvt_pk_f16_f32 v0, v0, v1
	v_cvt_f32_f16_sdwa v1, v73 dst_sel:DWORD dst_unused:UNUSED_PAD src0_sel:WORD_1
	v_mul_f32_e32 v4, 0xbfb8aa3b, v6
	v_exp_f32_e32 v4, v4
	v_mul_f32_e32 v5, 0xbfb8aa3b, v1
	v_exp_f32_e32 v5, v5
	s_nop 0
	v_pk_add_f32 v[4:5], v[4:5], 1.0 op_sel_hi:[1,0]
	s_nop 0
	v_div_scale_f32 v7, s[4:5], v5, v5, v1
	v_rcp_f32_e32 v8, v7
	s_nop 0
	v_fma_f32 v9, -v7, v8, 1.0
	v_fmac_f32_e32 v8, v9, v8
	v_div_scale_f32 v9, vcc, v1, v5, v1
	v_mul_f32_e32 v10, v9, v8
	v_fma_f32 v11, -v7, v10, v9
	v_fmac_f32_e32 v10, v11, v8
	v_fma_f32 v7, -v7, v10, v9
	v_div_fmas_f32 v7, v7, v8, v10
	v_div_fixup_f32 v5, v7, v5, v1
	v_div_scale_f32 v1, s[4:5], v4, v4, v6
	v_rcp_f32_e32 v7, v1
	s_nop 0
	v_fma_f32 v8, -v1, v7, 1.0
	v_fmac_f32_e32 v7, v8, v7
	v_div_scale_f32 v8, vcc, v6, v4, v6
	v_mul_f32_e32 v9, v8, v7
	v_fma_f32 v10, -v1, v9, v8
	v_fmac_f32_e32 v9, v10, v7
	v_fma_f32 v1, -v1, v9, v8
	v_div_fmas_f32 v1, v1, v7, v9
	v_div_fixup_f32 v4, v1, v4, v6
	v_pk_mul_f32 v[2:3], v[2:3], v[4:5]
	s_nop 0
	v_cvt_pk_f16_f32 v1, v2, v3
	global_store_dwordx2 v[28:29], v[0:1], off offset:224

.LBB0_149:
	s_or_b64 exec, exec, s[6:7]
	v_readlane_b32 s0, v255, 47
	s_or_b32 s6, s14, s0
	s_ashr_i32 s7, s6, 31
	s_lshl_b64 s[8:9], s[6:7], 15
	v_readlane_b32 s0, v254, 6
	v_bfe_u32 v0, v8, 4, 2
	s_add_u32 s8, s0, s8
	v_readlane_b32 s0, v254, 7
	v_ashrrev_i32_e32 v1, 2, v8
	s_addc_u32 s9, s0, s9
	s_waitcnt vmcnt(0)
	v_and_b32_e32 v32, -16, v1
	v_bfi_b32 v1, -16, v1, v8
	v_lshlrev_b32_e32 v40, 4, v0
	s_movk_i32 s0, 0x110
	v_and_b32_e32 v34, 15, v8
	v_lshlrev_b32_e32 v168, 3, v0
	v_mad_u64_u32 v[0:1], s[10:11], v1, s0, v[40:41]
	v_mov_b32_e32 v41, v169
	v_lshl_add_u64 v[2:3], s[8:9], 0, v[40:41]
	v_lshlrev_b32_e32 v30, 8, v34
	v_mov_b32_e32 v31, v169
	v_lshl_add_u64 v[4:5], v[2:3], 0, v[30:31]
	s_waitcnt lgkmcnt(0)
	s_barrier
	global_load_dwordx4 v[6:9], v[4:5], off
	global_load_dwordx4 v[58:61], v[4:5], off offset:64
	ds_read_b128 v[14:17], v0 offset:21760
	ds_read_b128 v[62:65], v0 offset:21952
	v_or_b32_e32 v66, 0x5000, v30
	v_mov_b32_e32 v67, v169
	v_lshl_add_u64 v[46:47], v[2:3], 0, v[66:67]
	v_or_b32_e32 v68, 0x6000, v30
	v_mov_b32_e32 v69, v169
	v_lshl_add_u64 v[50:51], v[2:3], 0, v[68:69]
	v_or_b32_e32 v70, 0x7000, v30
	v_mov_b32_e32 v71, v169
	s_mov_b64 s[8:9], 0x80
	s_mov_b32 s5, s1
	v_ashrrev_i32_e32 v33, 31, v32
	v_lshl_add_u64 v[32:33], v[32:33], 0, s[4:5]
	s_lshl_b32 s4, s6, 7
	s_ashr_i32 s5, s4, 31
	s_lshl_b64 s[4:5], s[4:5], 2
	s_add_u32 s38, s88, s4
	s_addc_u32 s39, s89, s5
	s_lshl_b32 s0, s14, 9
	v_readlane_b32 s3, v255, 51
	v_readlane_b32 s4, v254, 4
	s_add_u32 s36, s3, s0
	v_readlane_b32 s0, v255, 52
	v_readlane_b32 s5, v254, 5
	v_or_b32_e32 v32, v32, v34
	s_addc_u32 s37, s0, 0
	v_mov_b64_e32 v[34:35], s[4:5]
	s_movk_i32 s0, 0x3020
	v_mad_u64_u32 v[34:35], s[4:5], v32, s0, v[34:35]
	v_mad_i32_i24 v35, v33, s0, v35
	s_lshl_b32 s0, s14, 8
	v_lshlrev_b64 v[32:33], 12, v[32:33]
	v_lshl_add_u64 v[34:35], v[34:35], 0, s[0:1]
	v_lshl_add_u64 v[32:33], s[20:21], 0, v[32:33]
	s_mov_b64 s[4:5], 0x1c20
	s_movk_i32 s3, 0x3020
	s_waitcnt vmcnt(1) lgkmcnt(1)
	v_mfma_f32_16x16x32_f16 v[18:21], v[6:9], v[14:17], 0
	v_or_b32_e32 v6, 0x1000, v30
	v_mov_b32_e32 v7, v169
	v_lshl_add_u64 v[8:9], v[2:3], 0, v[6:7]
	global_load_dwordx4 v[8:11], v[8:9], off
	s_nop 0
	global_load_dwordx4 v[46:49], v[46:47], off
	s_waitcnt vmcnt(1)
	v_mfma_f32_16x16x32_f16 v[22:25], v[8:11], v[14:17], 0
	v_or_b32_e32 v8, 0x2000, v30
	v_mov_b32_e32 v9, v169
	v_lshl_add_u64 v[10:11], v[2:3], 0, v[8:9]
	global_load_dwordx4 v[10:13], v[10:11], off
	s_waitcnt vmcnt(1)
	v_mfma_f32_16x16x32_f16 v[46:49], v[46:49], v[14:17], 0
	global_load_dwordx4 v[50:53], v[50:51], off
	s_waitcnt vmcnt(1)
	v_mfma_f32_16x16x32_f16 v[26:29], v[10:13], v[14:17], 0
	v_or_b32_e32 v10, 0x3000, v30
	v_mov_b32_e32 v11, v169
	v_lshl_add_u64 v[12:13], v[2:3], 0, v[10:11]
	global_load_dwordx4 v[36:39], v[12:13], off
	v_or_b32_e32 v12, 0x4000, v30
	v_mov_b32_e32 v13, v169
	v_lshl_add_u64 v[42:43], v[2:3], 0, v[12:13]
	v_lshl_add_u64 v[30:31], v[2:3], 0, v[70:71]
	global_load_dwordx4 v[42:45], v[42:43], off
	s_waitcnt vmcnt(2)
	v_mfma_f32_16x16x32_f16 v[50:53], v[50:53], v[14:17], 0
	global_load_dwordx4 v[54:57], v[30:31], off
	v_lshl_add_u64 v[30:31], v[2:3], 0, 64
	s_waitcnt vmcnt(2)
	v_mfma_f32_16x16x32_f16 v[36:39], v[36:39], v[14:17], 0
	s_waitcnt vmcnt(1)
	v_mfma_f32_16x16x32_f16 v[42:45], v[42:45], v[14:17], 0
	s_waitcnt vmcnt(0)
	v_mfma_f32_16x16x32_f16 v[14:17], v[54:57], v[14:17], 0
	ds_read_b128 v[54:57], v0 offset:21824
	s_waitcnt lgkmcnt(0)
	v_mfma_f32_16x16x32_f16 v[18:21], v[58:61], v[54:57], v[18:21]
	v_lshl_add_u64 v[58:59], v[30:31], 0, v[6:7]
	global_load_dwordx4 v[58:61], v[58:59], off
	s_waitcnt vmcnt(0)
	v_mfma_f32_16x16x32_f16 v[22:25], v[58:61], v[54:57], v[22:25]
	v_lshl_add_u64 v[58:59], v[30:31], 0, v[8:9]
	global_load_dwordx4 v[58:61], v[58:59], off
	s_waitcnt vmcnt(0)
	v_mfma_f32_16x16x32_f16 v[26:29], v[58:61], v[54:57], v[26:29]
	v_lshl_add_u64 v[58:59], v[30:31], 0, v[10:11]
	global_load_dwordx4 v[58:61], v[58:59], off
	s_waitcnt vmcnt(0)
	v_mfma_f32_16x16x32_f16 v[36:39], v[58:61], v[54:57], v[36:39]
	v_lshl_add_u64 v[58:59], v[30:31], 0, v[12:13]
	global_load_dwordx4 v[58:61], v[58:59], off
	s_waitcnt vmcnt(0)
	v_mfma_f32_16x16x32_f16 v[42:45], v[58:61], v[54:57], v[42:45]
	v_lshl_add_u64 v[58:59], v[30:31], 0, v[66:67]
	global_load_dwordx4 v[58:61], v[58:59], off
	s_waitcnt vmcnt(0)
	v_mfma_f32_16x16x32_f16 v[46:49], v[58:61], v[54:57], v[46:49]
	v_lshl_add_u64 v[58:59], v[30:31], 0, v[68:69]
	global_load_dwordx4 v[58:61], v[58:59], off
	v_lshl_add_u64 v[30:31], v[30:31], 0, v[70:71]
	s_waitcnt vmcnt(0)
	v_mfma_f32_16x16x32_f16 v[50:53], v[58:61], v[54:57], v[50:53]
	global_load_dwordx4 v[58:61], v[30:31], off
	v_lshl_add_u64 v[30:31], v[2:3], 0, s[8:9]
	s_mov_b64 s[8:9], 0xc0
	v_lshl_add_u64 v[72:73], v[2:3], 0, s[8:9]
	s_waitcnt vmcnt(0)
	v_mfma_f32_16x16x32_f16 v[14:17], v[58:61], v[54:57], v[14:17]
	global_load_dwordx4 v[58:61], v[4:5], off offset:128
	ds_read_b128 v[54:57], v0 offset:21888
	global_load_dwordx4 v[0:3], v[4:5], off offset:192
	s_waitcnt vmcnt(1) lgkmcnt(0)
	v_mfma_f32_16x16x32_f16 v[18:21], v[58:61], v[54:57], v[18:21]
	v_lshl_add_u64 v[58:59], v[30:31], 0, v[6:7]
	global_load_dwordx4 v[58:61], v[58:59], off
	s_waitcnt vmcnt(0)
	v_mfma_f32_16x16x32_f16 v[22:25], v[58:61], v[54:57], v[22:25]
	v_lshl_add_u64 v[58:59], v[30:31], 0, v[8:9]
	global_load_dwordx4 v[58:61], v[58:59], off
	s_waitcnt vmcnt(0)
	v_mfma_f32_16x16x32_f16 v[58:61], v[58:61], v[54:57], v[26:29]
	s_nop 2
	v_lshl_add_u64 v[26:27], v[30:31], 0, v[10:11]
	global_load_dwordx4 v[26:29], v[26:27], off
	s_waitcnt vmcnt(0)
	v_mfma_f32_16x16x32_f16 v[36:39], v[26:29], v[54:57], v[36:39]
	v_lshl_add_u64 v[26:27], v[30:31], 0, v[12:13]
	global_load_dwordx4 v[26:29], v[26:27], off
	s_waitcnt vmcnt(0)
	v_mfma_f32_16x16x32_f16 v[42:45], v[26:29], v[54:57], v[42:45]
	v_lshl_add_u64 v[26:27], v[30:31], 0, v[66:67]
	global_load_dwordx4 v[26:29], v[26:27], off
	s_waitcnt vmcnt(0)
	v_mfma_f32_16x16x32_f16 v[46:49], v[26:29], v[54:57], v[46:49]
	v_lshl_add_u64 v[26:27], v[30:31], 0, v[68:69]
	global_load_dwordx4 v[26:29], v[26:27], off
	s_waitcnt vmcnt(0)
	v_mfma_f32_16x16x32_f16 v[50:53], v[26:29], v[54:57], v[50:53]
	v_lshl_add_u64 v[26:27], v[30:31], 0, v[70:71]
	global_load_dwordx4 v[26:29], v[26:27], off
	s_waitcnt vmcnt(0)
	v_mfma_f32_16x16x32_f16 v[54:57], v[26:29], v[54:57], v[14:17]
	v_mfma_f32_16x16x32_f16 v[28:31], v[0:3], v[62:65], v[18:21]
	v_lshl_add_u64 v[0:1], v[72:73], 0, v[6:7]
	global_load_dwordx4 v[0:3], v[0:1], off
	s_waitcnt vmcnt(0)
	v_mfma_f32_16x16x32_f16 v[24:27], v[0:3], v[62:65], v[22:25]
	v_lshl_add_u64 v[0:1], v[72:73], 0, v[8:9]
	global_load_dwordx4 v[0:3], v[0:1], off
	s_waitcnt vmcnt(0)
	v_mfma_f32_16x16x32_f16 v[20:23], v[0:3], v[62:65], v[58:61]
	v_lshl_add_u64 v[0:1], v[72:73], 0, v[10:11]
	global_load_dwordx4 v[0:3], v[0:1], off
	s_waitcnt vmcnt(0)
	v_mfma_f32_16x16x32_f16 v[16:19], v[0:3], v[62:65], v[36:39]
	v_lshl_add_u64 v[0:1], v[72:73], 0, v[12:13]
	global_load_dwordx4 v[0:3], v[0:1], off
	s_waitcnt vmcnt(0)
	v_mfma_f32_16x16x32_f16 v[12:15], v[0:3], v[62:65], v[42:45]
	v_lshl_add_u64 v[0:1], v[72:73], 0, v[66:67]
	global_load_dwordx4 v[0:3], v[0:1], off
	s_nop 0
	v_lshl_add_u64 v[44:45], v[32:33], 0, s[0:1]
	v_lshl_add_u64 v[32:33], v[34:35], 0, v[168:169]
	s_movk_i32 s0, 0x1000
	v_lshl_add_u64 v[42:43], v[32:33], 0, s[4:5]
	v_add_co_u32_e32 v32, vcc, s0, v32
	s_mov_b32 s0, 0x47ff000
	s_nop 0
	v_addc_co_u32_e32 v33, vcc, 0, v33, vcc
	s_waitcnt vmcnt(0)
	v_mfma_f32_16x16x32_f16 v[8:11], v[0:3], v[62:65], v[46:49]
	v_lshl_add_u64 v[0:1], v[72:73], 0, v[68:69]
	global_load_dwordx4 v[0:3], v[0:1], off
	s_waitcnt vmcnt(0)
	v_mfma_f32_16x16x32_f16 v[4:7], v[0:3], v[62:65], v[50:53]
	v_lshl_add_u64 v[0:1], v[72:73], 0, v[70:71]
	global_load_dwordx4 v[0:3], v[0:1], off
	s_nop 0
	global_load_dwordx2 v[46:47], v[32:33], off offset:3104
	s_nop 0
	global_load_dwordx4 v[32:35], v40, s[38:39]
	global_load_dwordx4 v[36:39], v40, s[36:37]
	global_load_dwordx2 v[132:133], v[42:43], off offset:32
	global_load_dwordx4 v[76:79], v40, s[38:39] offset:64
	global_load_dwordx4 v[80:83], v40, s[36:37] offset:64
	global_load_dwordx2 v[134:135], v[42:43], off offset:64
	global_load_dwordx4 v[84:87], v40, s[38:39] offset:128
	global_load_dwordx4 v[88:91], v40, s[36:37] offset:128
	global_load_dwordx2 v[136:137], v[42:43], off offset:96
	global_load_dwordx4 v[92:95], v40, s[38:39] offset:192
	global_load_dwordx4 v[96:99], v40, s[36:37] offset:192
	global_load_dwordx2 v[138:139], v[42:43], off offset:128
	global_load_dwordx4 v[100:103], v40, s[38:39] offset:256
	global_load_dwordx4 v[104:107], v40, s[36:37] offset:256
	global_load_dwordx2 v[140:141], v[42:43], off offset:160
	global_load_dwordx4 v[108:111], v40, s[38:39] offset:320
	global_load_dwordx4 v[112:115], v40, s[36:37] offset:320
	global_load_dwordx2 v[142:143], v[42:43], off offset:192
	global_load_dwordx4 v[116:119], v40, s[38:39] offset:384
	global_load_dwordx4 v[120:123], v40, s[36:37] offset:384
	global_load_dwordx2 v[144:145], v[42:43], off offset:224
	global_load_dwordx4 v[124:127], v40, s[38:39] offset:448
	global_load_dwordx4 v[128:131], v40, s[36:37] offset:448
	s_waitcnt vmcnt(24)
	v_mfma_f32_16x16x32_f16 v[0:3], v[0:3], v[62:65], v[54:57]
	s_waitcnt vmcnt(23)
	v_cvt_f32_f16_sdwa v41, v46 dst_sel:DWORD dst_unused:UNUSED_PAD src0_sel:WORD_1
	v_cvt_f32_f16_e32 v46, v46
	s_waitcnt vmcnt(22)
	v_pk_add_f32 v[28:29], v[28:29], v[32:33]
	v_pk_add_f32 v[30:31], v[30:31], v[34:35]
	v_mul_f32_e32 v32, 0xbfb8aa3b, v41
	v_mul_f32_e32 v48, 0xbfb8aa3b, v46
	v_exp_f32_e32 v48, v48
	v_exp_f32_e32 v49, v32
	s_waitcnt vmcnt(21)
	v_pk_mul_f32 v[28:29], v[28:29], v[36:37]
	v_pk_mul_f32 v[30:31], v[30:31], v[38:39]
	v_pk_add_f32 v[32:33], v[48:49], 1.0 op_sel_hi:[1,0]
	s_nop 0
	v_div_scale_f32 v36, s[4:5], v33, v33, v41
	v_rcp_f32_e32 v37, v36
	s_nop 0
	v_fma_f32 v48, -v36, v37, 1.0
	v_fmac_f32_e32 v37, v48, v37
	v_div_scale_f32 v48, vcc, v41, v33, v41
	v_mul_f32_e32 v49, v48, v37
	v_fma_f32 v50, -v36, v49, v48
	v_fmac_f32_e32 v49, v50, v37
	v_fma_f32 v36, -v36, v49, v48
	v_div_fmas_f32 v36, v36, v37, v49
	v_div_fixup_f32 v33, v36, v33, v41
	v_div_scale_f32 v36, s[4:5], v32, v32, v46
	v_rcp_f32_e32 v37, v36
	s_nop 0
	v_fma_f32 v41, -v36, v37, 1.0
	v_fmac_f32_e32 v37, v41, v37
	v_div_scale_f32 v41, vcc, v46, v32, v46
	v_mul_f32_e32 v48, v41, v37
	v_fma_f32 v49, -v36, v48, v41
	v_fmac_f32_e32 v48, v49, v37
	v_fma_f32 v36, -v36, v48, v41
	v_div_fmas_f32 v36, v36, v37, v48
	v_div_fixup_f32 v32, v36, v32, v46
	v_pk_mul_f32 v[28:29], v[28:29], v[32:33]
	v_cvt_f32_f16_sdwa v33, v47 dst_sel:DWORD dst_unused:UNUSED_PAD src0_sel:WORD_1
	v_cvt_f32_f16_e32 v36, v47
	v_cvt_pk_f16_f32 v32, v28, v29
	v_mul_f32_e32 v29, 0xbfb8aa3b, v33
	v_mul_f32_e32 v28, 0xbfb8aa3b, v36
	v_exp_f32_e32 v28, v28
	v_exp_f32_e32 v29, v29
	s_nop 0
	v_pk_add_f32 v[28:29], v[28:29], 1.0 op_sel_hi:[1,0]
	s_nop 0
	v_div_scale_f32 v34, s[4:5], v29, v29, v33
	v_rcp_f32_e32 v35, v34
	s_nop 0
	v_fma_f32 v37, -v34, v35, 1.0
	v_fmac_f32_e32 v35, v37, v35
	v_div_scale_f32 v37, vcc, v33, v29, v33
	v_mul_f32_e32 v38, v37, v35
	v_fma_f32 v39, -v34, v38, v37
	v_fmac_f32_e32 v38, v39, v35
	v_fma_f32 v34, -v34, v38, v37
	v_div_fmas_f32 v34, v34, v35, v38
	v_div_fixup_f32 v29, v34, v29, v33
	v_div_scale_f32 v33, s[4:5], v28, v28, v36
	v_rcp_f32_e32 v34, v33
	s_mov_b64 s[4:5], 0x47fff00
	v_fma_f32 v35, -v33, v34, 1.0
	v_fmac_f32_e32 v34, v35, v34
	v_div_scale_f32 v35, vcc, v36, v28, v36
	v_mul_f32_e32 v37, v35, v34
	v_fma_f32 v38, -v33, v37, v35
	v_fmac_f32_e32 v37, v38, v34
	v_fma_f32 v33, -v33, v37, v35
	v_div_fmas_f32 v33, v33, v34, v37
	v_div_fixup_f32 v28, v33, v28, v36
	v_pk_mul_f32 v[28:29], v[30:31], v[28:29]
	v_lshl_add_u64 v[30:31], v[44:45], 0, v[168:169]
	v_cvt_pk_f16_f32 v33, v28, v29
	v_lshl_add_u64 v[28:29], v[30:31], 0, s[4:5]
	v_add_co_u32_e32 v30, vcc, s0, v30
	s_nop 1
	v_addc_co_u32_e32 v31, vcc, 0, v31, vcc
	global_store_dwordx2 v[30:31], v[32:33], off offset:3840
	s_nop 0
	s_waitcnt vmcnt(21)
	v_cvt_f32_f16_sdwa v41, v132 dst_sel:DWORD dst_unused:UNUSED_PAD src0_sel:WORD_1
	v_cvt_f32_f16_e32 v38, v132
	s_waitcnt vmcnt(20)
	v_pk_add_f32 v[24:25], v[24:25], v[76:77]
	v_pk_add_f32 v[26:27], v[26:27], v[78:79]
	v_mul_f32_e32 v30, 0xbfb8aa3b, v41
	v_mul_f32_e32 v44, 0xbfb8aa3b, v38
	v_exp_f32_e32 v44, v44
	v_exp_f32_e32 v45, v30
	s_waitcnt vmcnt(19)
	v_pk_mul_f32 v[24:25], v[24:25], v[80:81]
	v_pk_mul_f32 v[26:27], v[26:27], v[82:83]
	v_pk_add_f32 v[30:31], v[44:45], 1.0 op_sel_hi:[1,0]
	s_nop 0
	v_div_scale_f32 v34, s[4:5], v31, v31, v41
	v_rcp_f32_e32 v35, v34
	s_nop 0
	v_fma_f32 v44, -v34, v35, 1.0
	v_fmac_f32_e32 v35, v44, v35
	v_div_scale_f32 v44, vcc, v41, v31, v41
	v_mul_f32_e32 v45, v44, v35
	v_fma_f32 v46, -v34, v45, v44
	v_fmac_f32_e32 v45, v46, v35
	v_fma_f32 v34, -v34, v45, v44
	v_div_fmas_f32 v34, v34, v35, v45
	v_div_fixup_f32 v31, v34, v31, v41
	v_div_scale_f32 v34, s[4:5], v30, v30, v38
	v_rcp_f32_e32 v35, v34
	s_nop 0
	v_fma_f32 v41, -v34, v35, 1.0
	v_fmac_f32_e32 v35, v41, v35
	v_div_scale_f32 v41, vcc, v38, v30, v38
	v_mul_f32_e32 v44, v41, v35
	v_fma_f32 v45, -v34, v44, v41
	v_fmac_f32_e32 v44, v45, v35
	v_fma_f32 v34, -v34, v44, v41
	v_div_fmas_f32 v34, v34, v35, v44
	v_div_fixup_f32 v30, v34, v30, v38
	v_pk_mul_f32 v[24:25], v[24:25], v[30:31]
	v_cvt_f32_f16_e32 v34, v133
	v_cvt_pk_f16_f32 v24, v24, v25
	v_cvt_f32_f16_sdwa v25, v133 dst_sel:DWORD dst_unused:UNUSED_PAD src0_sel:WORD_1
	v_mul_f32_e32 v30, 0xbfb8aa3b, v34
	v_exp_f32_e32 v30, v30
	v_mul_f32_e32 v31, 0xbfb8aa3b, v25
	v_exp_f32_e32 v31, v31
	s_nop 0
	v_pk_add_f32 v[30:31], v[30:31], 1.0 op_sel_hi:[1,0]
	s_nop 0
	v_div_scale_f32 v32, s[4:5], v31, v31, v25
	v_rcp_f32_e32 v33, v32
	s_nop 0
	v_fma_f32 v35, -v32, v33, 1.0
	v_fmac_f32_e32 v33, v35, v33
	v_div_scale_f32 v35, vcc, v25, v31, v25
	v_mul_f32_e32 v36, v35, v33
	v_fma_f32 v37, -v32, v36, v35
	v_fmac_f32_e32 v36, v37, v33
	v_fma_f32 v32, -v32, v36, v35
	v_div_fmas_f32 v32, v32, v33, v36
	v_div_fixup_f32 v31, v32, v31, v25
	v_div_scale_f32 v25, s[4:5], v30, v30, v34
	v_rcp_f32_e32 v32, v25
	s_nop 0
	v_fma_f32 v33, -v25, v32, 1.0
	v_fmac_f32_e32 v32, v33, v32
	v_div_scale_f32 v33, vcc, v34, v30, v34
	v_mul_f32_e32 v35, v33, v32
	v_fma_f32 v36, -v25, v35, v33
	v_fmac_f32_e32 v35, v36, v32
	v_fma_f32 v25, -v25, v35, v33
	v_div_fmas_f32 v25, v25, v32, v35
	v_div_fixup_f32 v30, v25, v30, v34
	v_pk_mul_f32 v[26:27], v[26:27], v[30:31]
	s_nop 0
	v_cvt_pk_f16_f32 v25, v26, v27
	global_store_dwordx2 v[28:29], v[24:25], off offset:32
	s_nop 0
	s_waitcnt vmcnt(19)
	v_cvt_f32_f16_sdwa v38, v134 dst_sel:DWORD dst_unused:UNUSED_PAD src0_sel:WORD_1
	v_cvt_f32_f16_e32 v34, v134
	s_waitcnt vmcnt(18)
	v_pk_add_f32 v[20:21], v[20:21], v[84:85]
	v_pk_add_f32 v[22:23], v[22:23], v[86:87]
	v_mul_f32_e32 v24, 0xbfb8aa3b, v38
	v_mul_f32_e32 v36, 0xbfb8aa3b, v34
	v_exp_f32_e32 v36, v36
	v_exp_f32_e32 v37, v24
	s_waitcnt vmcnt(17)
	v_pk_mul_f32 v[20:21], v[20:21], v[88:89]
	v_pk_mul_f32 v[22:23], v[22:23], v[90:91]
	v_pk_add_f32 v[24:25], v[36:37], 1.0 op_sel_hi:[1,0]
	s_nop 0
	v_div_scale_f32 v30, s[4:5], v25, v25, v38
	v_rcp_f32_e32 v31, v30
	s_nop 0
	v_fma_f32 v36, -v30, v31, 1.0
	v_fmac_f32_e32 v31, v36, v31
	v_div_scale_f32 v36, vcc, v38, v25, v38
	v_mul_f32_e32 v37, v36, v31
	v_fma_f32 v39, -v30, v37, v36
	v_fmac_f32_e32 v37, v39, v31
	v_fma_f32 v30, -v30, v37, v36
	v_div_fmas_f32 v30, v30, v31, v37
	v_div_fixup_f32 v25, v30, v25, v38
	v_div_scale_f32 v30, s[4:5], v24, v24, v34
	v_rcp_f32_e32 v31, v30
	s_nop 0
	v_fma_f32 v36, -v30, v31, 1.0
	v_fmac_f32_e32 v31, v36, v31
	v_div_scale_f32 v36, vcc, v34, v24, v34
	v_mul_f32_e32 v37, v36, v31
	v_fma_f32 v38, -v30, v37, v36
	v_fmac_f32_e32 v37, v38, v31
	v_fma_f32 v30, -v30, v37, v36
	v_div_fmas_f32 v30, v30, v31, v37
	v_div_fixup_f32 v24, v30, v24, v34
	v_pk_mul_f32 v[20:21], v[20:21], v[24:25]
	v_cvt_f32_f16_e32 v30, v135
	v_cvt_pk_f16_f32 v20, v20, v21
	v_cvt_f32_f16_sdwa v21, v135 dst_sel:DWORD dst_unused:UNUSED_PAD src0_sel:WORD_1
	v_mul_f32_e32 v24, 0xbfb8aa3b, v30
	v_exp_f32_e32 v24, v24
	v_mul_f32_e32 v25, 0xbfb8aa3b, v21
	v_exp_f32_e32 v25, v25
	s_nop 0
	v_pk_add_f32 v[24:25], v[24:25], 1.0 op_sel_hi:[1,0]
	s_nop 0
	v_div_scale_f32 v26, s[4:5], v25, v25, v21
	v_rcp_f32_e32 v27, v26
	s_nop 0
	v_fma_f32 v31, -v26, v27, 1.0
	v_fmac_f32_e32 v27, v31, v27
	v_div_scale_f32 v31, vcc, v21, v25, v21
	v_mul_f32_e32 v32, v31, v27
	v_fma_f32 v33, -v26, v32, v31
	v_fmac_f32_e32 v32, v33, v27
	v_fma_f32 v26, -v26, v32, v31
	v_div_fmas_f32 v26, v26, v27, v32
	v_div_fixup_f32 v25, v26, v25, v21
	v_div_scale_f32 v21, s[4:5], v24, v24, v30
	v_rcp_f32_e32 v26, v21
	s_nop 0
	v_fma_f32 v27, -v21, v26, 1.0
	v_fmac_f32_e32 v26, v27, v26
	v_div_scale_f32 v27, vcc, v30, v24, v30
	v_mul_f32_e32 v31, v27, v26
	v_fma_f32 v32, -v21, v31, v27
	v_fmac_f32_e32 v31, v32, v26
	v_fma_f32 v21, -v21, v31, v27
	v_div_fmas_f32 v21, v21, v26, v31
	v_div_fixup_f32 v24, v21, v24, v30
	v_pk_mul_f32 v[22:23], v[22:23], v[24:25]
	s_nop 0
	v_cvt_pk_f16_f32 v21, v22, v23
	global_store_dwordx2 v[28:29], v[20:21], off offset:64
	s_nop 0
	s_waitcnt vmcnt(17)
	v_cvt_f32_f16_sdwa v34, v136 dst_sel:DWORD dst_unused:UNUSED_PAD src0_sel:WORD_1
	v_cvt_f32_f16_e32 v30, v136
	s_waitcnt vmcnt(16)
	v_pk_add_f32 v[16:17], v[16:17], v[92:93]
	v_pk_add_f32 v[18:19], v[18:19], v[94:95]
	v_mul_f32_e32 v20, 0xbfb8aa3b, v34
	v_mul_f32_e32 v32, 0xbfb8aa3b, v30
	v_exp_f32_e32 v32, v32
	v_exp_f32_e32 v33, v20
	s_waitcnt vmcnt(15)
	v_pk_mul_f32 v[16:17], v[16:17], v[96:97]
	v_pk_mul_f32 v[18:19], v[18:19], v[98:99]
	v_pk_add_f32 v[20:21], v[32:33], 1.0 op_sel_hi:[1,0]
	s_nop 0
	v_div_scale_f32 v24, s[4:5], v21, v21, v34
	v_rcp_f32_e32 v25, v24
	s_nop 0
	v_fma_f32 v32, -v24, v25, 1.0
	v_fmac_f32_e32 v25, v32, v25
	v_div_scale_f32 v32, vcc, v34, v21, v34
	v_mul_f32_e32 v33, v32, v25
	v_fma_f32 v35, -v24, v33, v32
	v_fmac_f32_e32 v33, v35, v25
	v_fma_f32 v24, -v24, v33, v32
	v_div_fmas_f32 v24, v24, v25, v33
	v_div_fixup_f32 v21, v24, v21, v34
	v_div_scale_f32 v24, s[4:5], v20, v20, v30
	v_rcp_f32_e32 v25, v24
	s_nop 0
	v_fma_f32 v32, -v24, v25, 1.0
	v_fmac_f32_e32 v25, v32, v25
	v_div_scale_f32 v32, vcc, v30, v20, v30
	v_mul_f32_e32 v33, v32, v25
	v_fma_f32 v34, -v24, v33, v32
	v_fmac_f32_e32 v33, v34, v25
	v_fma_f32 v24, -v24, v33, v32
	v_div_fmas_f32 v24, v24, v25, v33
	v_div_fixup_f32 v20, v24, v20, v30
	v_pk_mul_f32 v[16:17], v[16:17], v[20:21]
	v_cvt_f32_f16_e32 v24, v137
	v_cvt_pk_f16_f32 v16, v16, v17
	v_cvt_f32_f16_sdwa v17, v137 dst_sel:DWORD dst_unused:UNUSED_PAD src0_sel:WORD_1
	v_mul_f32_e32 v20, 0xbfb8aa3b, v24
	v_exp_f32_e32 v20, v20
	v_mul_f32_e32 v21, 0xbfb8aa3b, v17
	v_exp_f32_e32 v21, v21
	s_nop 0
	v_pk_add_f32 v[20:21], v[20:21], 1.0 op_sel_hi:[1,0]
	s_nop 0
	v_div_scale_f32 v22, s[4:5], v21, v21, v17
	v_rcp_f32_e32 v23, v22
	s_nop 0
	v_fma_f32 v25, -v22, v23, 1.0
	v_fmac_f32_e32 v23, v25, v23
	v_div_scale_f32 v25, vcc, v17, v21, v17
	v_mul_f32_e32 v26, v25, v23
	v_fma_f32 v27, -v22, v26, v25
	v_fmac_f32_e32 v26, v27, v23
	v_fma_f32 v22, -v22, v26, v25
	v_div_fmas_f32 v22, v22, v23, v26
	v_div_fixup_f32 v21, v22, v21, v17
	v_div_scale_f32 v17, s[4:5], v20, v20, v24
	v_rcp_f32_e32 v22, v17
	s_nop 0
	v_fma_f32 v23, -v17, v22, 1.0
	v_fmac_f32_e32 v22, v23, v22
	v_div_scale_f32 v23, vcc, v24, v20, v24
	v_mul_f32_e32 v25, v23, v22
	v_fma_f32 v26, -v17, v25, v23
	v_fmac_f32_e32 v25, v26, v22
	v_fma_f32 v17, -v17, v25, v23
	v_div_fmas_f32 v17, v17, v22, v25
	v_div_fixup_f32 v20, v17, v20, v24
	v_pk_mul_f32 v[18:19], v[18:19], v[20:21]
	s_nop 0
	v_cvt_pk_f16_f32 v17, v18, v19
	global_store_dwordx2 v[28:29], v[16:17], off offset:96
	s_nop 0
	s_waitcnt vmcnt(15)
	v_cvt_f32_f16_sdwa v30, v138 dst_sel:DWORD dst_unused:UNUSED_PAD src0_sel:WORD_1
	v_cvt_f32_f16_e32 v24, v138
	s_waitcnt vmcnt(14)
	v_pk_add_f32 v[12:13], v[12:13], v[100:101]
	v_pk_add_f32 v[14:15], v[14:15], v[102:103]
	v_mul_f32_e32 v16, 0xbfb8aa3b, v30
	v_mul_f32_e32 v26, 0xbfb8aa3b, v24
	v_exp_f32_e32 v26, v26
	v_exp_f32_e32 v27, v16
	s_waitcnt vmcnt(13)
	v_pk_mul_f32 v[12:13], v[12:13], v[104:105]
	v_pk_mul_f32 v[14:15], v[14:15], v[106:107]
	v_pk_add_f32 v[16:17], v[26:27], 1.0 op_sel_hi:[1,0]
	s_nop 0
	v_div_scale_f32 v20, s[4:5], v17, v17, v30
	v_rcp_f32_e32 v21, v20
	s_nop 0
	v_fma_f32 v26, -v20, v21, 1.0
	v_fmac_f32_e32 v21, v26, v21
	v_div_scale_f32 v26, vcc, v30, v17, v30
	v_mul_f32_e32 v27, v26, v21
	v_fma_f32 v31, -v20, v27, v26
	v_fmac_f32_e32 v27, v31, v21
	v_fma_f32 v20, -v20, v27, v26
	v_div_fmas_f32 v20, v20, v21, v27
	v_div_fixup_f32 v17, v20, v17, v30
	v_div_scale_f32 v20, s[4:5], v16, v16, v24
	v_rcp_f32_e32 v21, v20
	s_nop 0
	v_fma_f32 v26, -v20, v21, 1.0
	v_fmac_f32_e32 v21, v26, v21
	v_div_scale_f32 v26, vcc, v24, v16, v24
	v_mul_f32_e32 v27, v26, v21
	v_fma_f32 v30, -v20, v27, v26
	v_fmac_f32_e32 v27, v30, v21
	v_fma_f32 v20, -v20, v27, v26
	v_div_fmas_f32 v20, v20, v21, v27
	v_div_fixup_f32 v16, v20, v16, v24
	v_pk_mul_f32 v[12:13], v[12:13], v[16:17]
	v_cvt_f32_f16_e32 v20, v139
	v_cvt_pk_f16_f32 v12, v12, v13
	v_cvt_f32_f16_sdwa v13, v139 dst_sel:DWORD dst_unused:UNUSED_PAD src0_sel:WORD_1
	v_mul_f32_e32 v16, 0xbfb8aa3b, v20
	v_exp_f32_e32 v16, v16
	v_mul_f32_e32 v17, 0xbfb8aa3b, v13
	v_exp_f32_e32 v17, v17
	s_nop 0
	v_pk_add_f32 v[16:17], v[16:17], 1.0 op_sel_hi:[1,0]
	s_nop 0
	v_div_scale_f32 v18, s[4:5], v17, v17, v13
	v_rcp_f32_e32 v19, v18
	s_nop 0
	v_fma_f32 v21, -v18, v19, 1.0
	v_fmac_f32_e32 v19, v21, v19
	v_div_scale_f32 v21, vcc, v13, v17, v13
	v_mul_f32_e32 v22, v21, v19
	v_fma_f32 v23, -v18, v22, v21
	v_fmac_f32_e32 v22, v23, v19
	v_fma_f32 v18, -v18, v22, v21
	v_div_fmas_f32 v18, v18, v19, v22
	v_div_fixup_f32 v17, v18, v17, v13
	v_div_scale_f32 v13, s[4:5], v16, v16, v20
	v_rcp_f32_e32 v18, v13
	s_nop 0
	v_fma_f32 v19, -v13, v18, 1.0
	v_fmac_f32_e32 v18, v19, v18
	v_div_scale_f32 v19, vcc, v20, v16, v20
	v_mul_f32_e32 v21, v19, v18
	v_fma_f32 v22, -v13, v21, v19
	v_fmac_f32_e32 v21, v22, v18
	v_fma_f32 v13, -v13, v21, v19
	v_div_fmas_f32 v13, v13, v18, v21
	v_div_fixup_f32 v16, v13, v16, v20
	v_pk_mul_f32 v[14:15], v[14:15], v[16:17]
	s_nop 0
	v_cvt_pk_f16_f32 v13, v14, v15
	global_store_dwordx2 v[28:29], v[12:13], off offset:128
	s_nop 0
	s_waitcnt vmcnt(13)
	v_cvt_f32_f16_sdwa v24, v140 dst_sel:DWORD dst_unused:UNUSED_PAD src0_sel:WORD_1
	v_cvt_f32_f16_e32 v20, v140
	s_waitcnt vmcnt(12)
	v_pk_add_f32 v[8:9], v[8:9], v[108:109]
	v_pk_add_f32 v[10:11], v[10:11], v[110:111]
	v_mul_f32_e32 v12, 0xbfb8aa3b, v24
	v_mul_f32_e32 v22, 0xbfb8aa3b, v20
	v_exp_f32_e32 v22, v22
	v_exp_f32_e32 v23, v12
	s_waitcnt vmcnt(11)
	v_pk_mul_f32 v[8:9], v[8:9], v[112:113]
	v_pk_mul_f32 v[10:11], v[10:11], v[114:115]
	v_pk_add_f32 v[12:13], v[22:23], 1.0 op_sel_hi:[1,0]
	s_nop 0
	v_div_scale_f32 v16, s[4:5], v13, v13, v24
	v_rcp_f32_e32 v17, v16
	s_nop 0
	v_fma_f32 v22, -v16, v17, 1.0
	v_fmac_f32_e32 v17, v22, v17
	v_div_scale_f32 v22, vcc, v24, v13, v24
	v_mul_f32_e32 v23, v22, v17
	v_fma_f32 v25, -v16, v23, v22
	v_fmac_f32_e32 v23, v25, v17
	v_fma_f32 v16, -v16, v23, v22
	v_div_fmas_f32 v16, v16, v17, v23
	v_div_fixup_f32 v13, v16, v13, v24
	v_div_scale_f32 v16, s[4:5], v12, v12, v20
	v_rcp_f32_e32 v17, v16
	s_nop 0
	v_fma_f32 v22, -v16, v17, 1.0
	v_fmac_f32_e32 v17, v22, v17
	v_div_scale_f32 v22, vcc, v20, v12, v20
	v_mul_f32_e32 v23, v22, v17
	v_fma_f32 v24, -v16, v23, v22
	v_fmac_f32_e32 v23, v24, v17
	v_fma_f32 v16, -v16, v23, v22
	v_div_fmas_f32 v16, v16, v17, v23
	v_div_fixup_f32 v12, v16, v12, v20
	v_pk_mul_f32 v[8:9], v[8:9], v[12:13]
	v_cvt_f32_f16_e32 v16, v141
	v_cvt_pk_f16_f32 v8, v8, v9
	v_cvt_f32_f16_sdwa v9, v141 dst_sel:DWORD dst_unused:UNUSED_PAD src0_sel:WORD_1
	v_mul_f32_e32 v12, 0xbfb8aa3b, v16
	v_exp_f32_e32 v12, v12
	v_mul_f32_e32 v13, 0xbfb8aa3b, v9
	v_exp_f32_e32 v13, v13
	s_nop 0
	v_pk_add_f32 v[12:13], v[12:13], 1.0 op_sel_hi:[1,0]
	s_nop 0
	v_div_scale_f32 v14, s[4:5], v13, v13, v9
	v_rcp_f32_e32 v15, v14
	s_nop 0
	v_fma_f32 v17, -v14, v15, 1.0
	v_fmac_f32_e32 v15, v17, v15
	v_div_scale_f32 v17, vcc, v9, v13, v9
	v_mul_f32_e32 v18, v17, v15
	v_fma_f32 v19, -v14, v18, v17
	v_fmac_f32_e32 v18, v19, v15
	v_fma_f32 v14, -v14, v18, v17
	v_div_fmas_f32 v14, v14, v15, v18
	v_div_fixup_f32 v13, v14, v13, v9
	v_div_scale_f32 v9, s[4:5], v12, v12, v16
	v_rcp_f32_e32 v14, v9
	s_nop 0
	v_fma_f32 v15, -v9, v14, 1.0
	v_fmac_f32_e32 v14, v15, v14
	v_div_scale_f32 v15, vcc, v16, v12, v16
	v_mul_f32_e32 v17, v15, v14
	v_fma_f32 v18, -v9, v17, v15
	v_fmac_f32_e32 v17, v18, v14
	v_fma_f32 v9, -v9, v17, v15
	v_div_fmas_f32 v9, v9, v14, v17
	v_div_fixup_f32 v12, v9, v12, v16
	v_pk_mul_f32 v[10:11], v[10:11], v[12:13]
	s_nop 0
	v_cvt_pk_f16_f32 v9, v10, v11
	global_store_dwordx2 v[28:29], v[8:9], off offset:160
	s_nop 0
	s_waitcnt vmcnt(11)
	v_cvt_f32_f16_sdwa v20, v142 dst_sel:DWORD dst_unused:UNUSED_PAD src0_sel:WORD_1
	v_cvt_f32_f16_e32 v16, v142
	s_waitcnt vmcnt(10)
	v_pk_add_f32 v[4:5], v[4:5], v[116:117]
	v_pk_add_f32 v[6:7], v[6:7], v[118:119]
	v_mul_f32_e32 v8, 0xbfb8aa3b, v20
	v_mul_f32_e32 v18, 0xbfb8aa3b, v16
	v_exp_f32_e32 v18, v18
	v_exp_f32_e32 v19, v8
	s_waitcnt vmcnt(9)
	v_pk_mul_f32 v[4:5], v[4:5], v[120:121]
	v_pk_mul_f32 v[6:7], v[6:7], v[122:123]
	v_pk_add_f32 v[8:9], v[18:19], 1.0 op_sel_hi:[1,0]
	s_nop 0
	v_div_scale_f32 v12, s[4:5], v9, v9, v20
	v_rcp_f32_e32 v13, v12
	s_nop 0
	v_fma_f32 v18, -v12, v13, 1.0
	v_fmac_f32_e32 v13, v18, v13
	v_div_scale_f32 v18, vcc, v20, v9, v20
	v_mul_f32_e32 v19, v18, v13
	v_fma_f32 v21, -v12, v19, v18
	v_fmac_f32_e32 v19, v21, v13
	v_fma_f32 v12, -v12, v19, v18
	v_div_fmas_f32 v12, v12, v13, v19
	v_div_fixup_f32 v9, v12, v9, v20
	v_div_scale_f32 v12, s[4:5], v8, v8, v16
	v_rcp_f32_e32 v13, v12
	s_nop 0
	v_fma_f32 v18, -v12, v13, 1.0
	v_fmac_f32_e32 v13, v18, v13
	v_div_scale_f32 v18, vcc, v16, v8, v16
	v_mul_f32_e32 v19, v18, v13
	v_fma_f32 v20, -v12, v19, v18
	v_fmac_f32_e32 v19, v20, v13
	v_fma_f32 v12, -v12, v19, v18
	v_div_fmas_f32 v12, v12, v13, v19
	v_div_fixup_f32 v8, v12, v8, v16
	v_pk_mul_f32 v[4:5], v[4:5], v[8:9]
	v_cvt_f32_f16_e32 v12, v143
	v_cvt_pk_f16_f32 v4, v4, v5
	v_cvt_f32_f16_sdwa v5, v143 dst_sel:DWORD dst_unused:UNUSED_PAD src0_sel:WORD_1
	v_mul_f32_e32 v8, 0xbfb8aa3b, v12
	v_exp_f32_e32 v8, v8
	v_mul_f32_e32 v9, 0xbfb8aa3b, v5
	v_exp_f32_e32 v9, v9
	s_nop 0
	v_pk_add_f32 v[8:9], v[8:9], 1.0 op_sel_hi:[1,0]
	s_nop 0
	v_div_scale_f32 v10, s[4:5], v9, v9, v5
	v_rcp_f32_e32 v11, v10
	s_nop 0
	v_fma_f32 v13, -v10, v11, 1.0
	v_fmac_f32_e32 v11, v13, v11
	v_div_scale_f32 v13, vcc, v5, v9, v5
	v_mul_f32_e32 v14, v13, v11
	v_fma_f32 v15, -v10, v14, v13
	v_fmac_f32_e32 v14, v15, v11
	v_fma_f32 v10, -v10, v14, v13
	v_div_fmas_f32 v10, v10, v11, v14
	v_div_fixup_f32 v9, v10, v9, v5
	v_div_scale_f32 v5, s[4:5], v8, v8, v12
	v_rcp_f32_e32 v10, v5
	s_nop 0
	v_fma_f32 v11, -v5, v10, 1.0
	v_fmac_f32_e32 v10, v11, v10
	v_div_scale_f32 v11, vcc, v12, v8, v12
	v_mul_f32_e32 v13, v11, v10
	v_fma_f32 v14, -v5, v13, v11
	v_fmac_f32_e32 v13, v14, v10
	v_fma_f32 v5, -v5, v13, v11
	v_div_fmas_f32 v5, v5, v10, v13
	v_div_fixup_f32 v8, v5, v8, v12
	v_pk_mul_f32 v[6:7], v[6:7], v[8:9]
	s_nop 0
	v_cvt_pk_f16_f32 v5, v6, v7
	global_store_dwordx2 v[28:29], v[4:5], off offset:192
	s_nop 0
	s_waitcnt vmcnt(9)
	v_cvt_f32_f16_sdwa v16, v144 dst_sel:DWORD dst_unused:UNUSED_PAD src0_sel:WORD_1
	v_cvt_f32_f16_e32 v12, v144
	s_waitcnt vmcnt(8)
	v_pk_add_f32 v[0:1], v[0:1], v[124:125]
	v_pk_add_f32 v[2:3], v[2:3], v[126:127]
	v_mul_f32_e32 v4, 0xbfb8aa3b, v16
	v_mul_f32_e32 v14, 0xbfb8aa3b, v12
	v_exp_f32_e32 v14, v14
	v_exp_f32_e32 v15, v4
	s_waitcnt vmcnt(7)
	v_pk_mul_f32 v[0:1], v[0:1], v[128:129]
	v_pk_mul_f32 v[2:3], v[2:3], v[130:131]
	v_pk_add_f32 v[4:5], v[14:15], 1.0 op_sel_hi:[1,0]
	s_nop 0
	v_div_scale_f32 v8, s[4:5], v5, v5, v16
	v_rcp_f32_e32 v9, v8
	s_nop 0
	v_fma_f32 v14, -v8, v9, 1.0
	v_fmac_f32_e32 v9, v14, v9
	v_div_scale_f32 v14, vcc, v16, v5, v16
	v_mul_f32_e32 v15, v14, v9
	v_fma_f32 v17, -v8, v15, v14
	v_fmac_f32_e32 v15, v17, v9
	v_fma_f32 v8, -v8, v15, v14
	v_div_fmas_f32 v8, v8, v9, v15
	v_div_fixup_f32 v5, v8, v5, v16
	v_div_scale_f32 v8, s[4:5], v4, v4, v12
	v_rcp_f32_e32 v9, v8
	s_nop 0
	v_fma_f32 v14, -v8, v9, 1.0
	v_fmac_f32_e32 v9, v14, v9
	v_div_scale_f32 v14, vcc, v12, v4, v12
	v_mul_f32_e32 v15, v14, v9
	v_fma_f32 v16, -v8, v15, v14
	v_fmac_f32_e32 v15, v16, v9
	v_fma_f32 v8, -v8, v15, v14
	v_div_fmas_f32 v8, v8, v9, v15
	v_div_fixup_f32 v4, v8, v4, v12
	v_pk_mul_f32 v[0:1], v[0:1], v[4:5]
	v_cvt_f32_f16_e32 v8, v145
	v_cvt_pk_f16_f32 v0, v0, v1
	v_cvt_f32_f16_sdwa v1, v145 dst_sel:DWORD dst_unused:UNUSED_PAD src0_sel:WORD_1
	v_mul_f32_e32 v4, 0xbfb8aa3b, v8
	v_exp_f32_e32 v4, v4
	v_mul_f32_e32 v5, 0xbfb8aa3b, v1
	v_exp_f32_e32 v5, v5
	s_nop 0
	v_pk_add_f32 v[4:5], v[4:5], 1.0 op_sel_hi:[1,0]
	s_nop 0
	v_div_scale_f32 v6, s[4:5], v5, v5, v1
	v_rcp_f32_e32 v7, v6
	s_nop 0
	v_fma_f32 v9, -v6, v7, 1.0
	v_fmac_f32_e32 v7, v9, v7
	v_div_scale_f32 v9, vcc, v1, v5, v1
	v_mul_f32_e32 v10, v9, v7
	v_fma_f32 v11, -v6, v10, v9
	v_fmac_f32_e32 v10, v11, v7
	v_fma_f32 v6, -v6, v10, v9
	v_div_fmas_f32 v6, v6, v7, v10
	v_div_fixup_f32 v5, v6, v5, v1
	v_div_scale_f32 v1, s[4:5], v4, v4, v8
	v_rcp_f32_e32 v6, v1
	s_mov_b64 s[4:5], 0
	v_fma_f32 v7, -v1, v6, 1.0
	v_fmac_f32_e32 v6, v7, v6
	v_div_scale_f32 v7, vcc, v8, v4, v8
	v_mul_f32_e32 v9, v7, v6
	v_fma_f32 v10, -v1, v9, v7
	v_fmac_f32_e32 v9, v10, v6
	v_fma_f32 v1, -v1, v9, v7
	v_div_fmas_f32 v1, v1, v6, v9
	v_div_fixup_f32 v4, v1, v4, v8
	v_pk_mul_f32 v[2:3], v[2:3], v[4:5]
	s_nop 0
	v_cvt_pk_f16_f32 v1, v2, v3
	global_store_dwordx2 v[28:29], v[0:1], off offset:224
.LBB0_150:
	s_and_b64 vcc, exec, s[4:5]
	s_cbranch_vccz .LBB0_152
	s_add_i32 s0, s25, 0xfffff900
	s_lshr_b32 s8, s0, 4
	s_bfe_u32 s9, s25, 0x20002
	s_lshl_b32 s10, s8, 8
	s_mul_i32 s0, s8, 0x302000
	v_readlane_b32 s12, v254, 4
	s_mul_hi_u32 s4, s10, 0x3020
	v_readlane_b32 s13, v254, 5
	s_add_u32 s5, s12, s0
	s_addc_u32 s4, s13, s4
	s_lshl_b32 s0, s9, 8
	s_add_u32 s5, s5, s0
	s_addc_u32 s4, s4, 0
	s_add_u32 s6, s5, 0x2420
	s_addc_u32 s7, s4, 0
	s_lshl_b32 s8, s8, 2
	s_or_b32 s8, s8, s9
	s_mov_b32 s9, s1
	v_mov_b32_e32 v2, v171
	s_lshl_b64 s[8:9], s[8:9], 16
	v_readlane_b32 s11, v254, 8
	s_add_u32 s8, s11, s8
	v_readlane_b32 s11, v254, 9
	v_ashrrev_i32_e32 v100, 3, v2
	s_addc_u32 s9, s11, s9
	s_lshl_b32 s11, s25, 6
	v_lshlrev_b32_e32 v18, 4, v2
	v_ashrrev_i32_e32 v101, 31, v100
	s_and_b32 s11, s11, 0xc0
	v_and_b32_e32 v84, 0xf0, v18
	v_and_b32_e32 v102, 0x70, v18
	v_lshlrev_b64 v[18:19], 9, v[100:101]
	v_and_b32_e32 v107, 15, v2
	v_ashrrev_i32_e32 v0, 2, v2
	s_or_b32 s10, s11, s10
	v_ashrrev_i32_e32 v8, 4, v2
	v_mov_b32_e32 v103, v169
	v_lshl_add_u64 v[18:19], s[8:9], 0, v[18:19]
	v_and_b32_e32 v0, -16, v0
	v_or_b32_e32 v1, s10, v107
	v_mov_b64_e32 v[10:11], s[6:7]
	s_movk_i32 s10, 0x3020
	v_add_u32_e32 v9, 16, v8
	v_add_u32_e32 v97, 32, v8
	v_add_u32_e32 v95, 48, v8
	v_lshl_add_u64 v[86:87], v[18:19], 0, v[102:103]
	v_bfe_u32 v94, v2, 4, 2
	v_add_u32_e32 v174, v1, v0
	v_mad_i64_i32 v[0:1], s[6:7], v8, s10, v[10:11]
	v_mov_b32_e32 v85, v169
	v_mad_i64_i32 v[2:3], s[6:7], v9, s10, v[10:11]
	s_waitcnt vmcnt(0)
	v_mad_i64_i32 v[12:13], s[6:7], v97, s10, v[10:11]
	v_mad_i64_i32 v[10:11], s[6:7], v95, s10, v[10:11]
	v_add_co_u32_e32 v24, vcc, s97, v86
	s_mov_b64 s[2:3], 0x8000
	v_lshl_add_u64 v[0:1], v[0:1], 0, v[84:85]
	v_lshl_add_u64 v[4:5], v[2:3], 0, v[84:85]
	v_lshl_add_u64 v[12:13], v[12:13], 0, v[84:85]
	v_lshl_add_u64 v[14:15], v[10:11], 0, v[84:85]
	v_addc_co_u32_e32 v25, vcc, 0, v87, vcc
	v_lshl_add_u64 v[90:91], v[86:87], 0, s[2:3]
	s_mov_b32 s3, 0x8000
	s_barrier
	global_load_dwordx4 v[0:3], v[0:1], off
	s_nop 0
	global_load_dwordx4 v[4:7], v[4:5], off
	s_nop 0
	global_load_dwordx4 v[10:13], v[12:13], off
	s_nop 0
	global_load_dwordx4 v[14:17], v[14:15], off
	s_add_u32 s6, s5, 0xc2c20
	global_load_dwordx4 v[18:21], v[86:87], off
	global_load_dwordx4 v[40:43], v[24:25], off
	v_add_co_u32_e32 v24, vcc, s3, v86
	s_mov_b64 s[2:3], 0xc000
	s_nop 0
	v_addc_co_u32_e32 v25, vcc, 0, v87, vcc
	v_lshl_add_u64 v[98:99], v[86:87], 0, s[2:3]
	s_mov_b32 s3, 0xc000
	global_load_dwordx4 v[44:47], v[24:25], off
	v_add_co_u32_e32 v24, vcc, s3, v86
	s_addc_u32 s7, s4, 0
	s_nop 0
	v_addc_co_u32_e32 v25, vcc, 0, v87, vcc
	global_load_dwordx4 v[48:51], v[24:25], off
	v_mov_b64_e32 v[24:25], s[6:7]
	v_mad_i64_i32 v[26:27], s[6:7], v8, s10, v[24:25]
	v_lshl_add_u64 v[26:27], v[26:27], 0, v[84:85]
	v_mad_i64_i32 v[28:29], s[6:7], v9, s10, v[24:25]
	v_lshl_add_u64 v[28:29], v[28:29], 0, v[84:85]
	global_load_dwordx4 v[52:55], v[26:27], off
	global_load_dwordx4 v[56:59], v[28:29], off
	v_mad_i64_i32 v[26:27], s[6:7], v97, s10, v[24:25]
	v_mov_b64_e32 v[22:23], s[12:13]
	v_lshl_add_u64 v[26:27], v[26:27], 0, v[84:85]
	v_mad_i64_i32 v[24:25], s[6:7], v95, s10, v[24:25]
	v_lshl_add_u64 v[88:89], v[86:87], 0, s[84:85]
	v_lshl_add_u64 v[24:25], v[24:25], 0, v[84:85]
	global_load_dwordx4 v[60:63], v[26:27], off
	global_load_dwordx4 v[64:67], v[24:25], off
	global_load_dwordx4 v[68:71], v[86:87], off offset:128
	global_load_dwordx4 v[72:75], v[88:89], off offset:128
	global_load_dwordx4 v[76:79], v[90:91], off offset:128
	global_load_dwordx4 v[80:83], v[98:99], off offset:128
	v_mad_i64_i32 v[22:23], s[6:7], v174, s10, v[22:23]
	v_lshlrev_b32_e32 v104, 4, v94
	v_mov_b32_e32 v105, v169
	v_lshl_add_u64 v[176:177], v[22:23], 0, s[0:1]
	v_lshl_add_u64 v[22:23], v[176:177], 0, v[104:105]
	v_add_co_u32_e32 v24, vcc, s33, v22
	s_mov_b64 s[2:3], 0x2020
	s_nop 0
	v_addc_co_u32_e32 v25, vcc, 0, v23, vcc
	global_load_dwordx4 v[36:39], v[24:25], off offset:32
	v_lshl_add_u64 v[22:23], v[22:23], 0, s[2:3]
	global_load_dwordx4 v[32:35], v[22:23], off offset:64
	global_load_dwordx4 v[28:31], v[22:23], off offset:128
	global_load_dwordx4 v[24:27], v[22:23], off offset:192
	s_movk_i32 s3, 0x110
	s_movk_i32 s8, 0x90
	v_mad_u64_u32 v[92:93], s[6:7], v8, s3, v[84:85]
	v_mad_u64_u32 v[22:23], s[6:7], v100, s8, v[102:103]
	v_add_u32_e32 v93, 0x8800, v22
	s_waitcnt vmcnt(19)
	ds_write_b128 v92, v[0:3]
	s_waitcnt vmcnt(18)
	ds_write_b128 v92, v[4:7] offset:4352
	s_waitcnt vmcnt(17)
	ds_write_b128 v92, v[10:13] offset:8704
	s_waitcnt vmcnt(16)
	ds_write_b128 v92, v[14:17] offset:13056
	s_waitcnt vmcnt(15)
	ds_write_b128 v22, v[18:21] offset:34816
	s_waitcnt vmcnt(14)
	ds_write_b128 v22, v[40:43] offset:39424
	s_waitcnt vmcnt(13)
	ds_write_b128 v22, v[44:47] offset:44032
	s_waitcnt vmcnt(12)
	ds_write_b128 v22, v[48:51] offset:48640
	s_waitcnt lgkmcnt(0)
	s_barrier
	s_waitcnt vmcnt(11)
	ds_write_b128 v92, v[52:55] offset:17408
	s_waitcnt vmcnt(10)
	ds_write_b128 v92, v[56:59] offset:21760
	s_waitcnt vmcnt(9)
	ds_write_b128 v92, v[60:63] offset:26112
	s_waitcnt vmcnt(8)
	ds_write_b128 v92, v[64:67] offset:30464
	s_waitcnt vmcnt(7)
	ds_write_b128 v22, v[68:71] offset:53248
	s_waitcnt vmcnt(6)
	ds_write_b128 v22, v[72:75] offset:57856
	s_waitcnt vmcnt(5)
	ds_write_b128 v22, v[76:79] offset:62464
	s_waitcnt vmcnt(4)
	ds_write_b128 v93, v[80:83] offset:32256
	v_mad_u32_u24 v129, v107, s3, v104
	ds_read_b128 v[0:3], v129
	ds_read_b128 v[4:7], v129 offset:64
	s_waitcnt vmcnt(3) lgkmcnt(1)
	v_mfma_f32_16x16x32_f16 v[0:3], v[0:3], v[36:39], 0
	ds_read_b128 v[10:13], v129 offset:128
	ds_read_b128 v[14:17], v129 offset:4480
	ds_read_b128 v[18:21], v129 offset:4544
	s_waitcnt vmcnt(2) lgkmcnt(3)
	v_mfma_f32_16x16x32_f16 v[0:3], v[4:7], v[32:35], v[0:3]
	ds_read_b128 v[4:7], v129 offset:192
	v_mbcnt_hi_u32_b32 v23, -1, v214
	v_xor_b32_e32 v40, 16, v23
	s_waitcnt vmcnt(1) lgkmcnt(3)
	v_mfma_f32_16x16x32_f16 v[0:3], v[10:13], v[28:31], v[0:3]
	ds_read_b128 v[10:13], v129 offset:4352
	s_add_u32 s6, s5, 0x183420
	s_addc_u32 s7, s4, 0
	s_waitcnt vmcnt(0) lgkmcnt(1)
	v_mfma_f32_16x16x32_f16 v[0:3], v[4:7], v[24:27], v[0:3]
	ds_read_b128 v[4:7], v129 offset:4416
	v_mov_b64_e32 v[52:53], s[6:7]
	ds_read_b128 v[44:47], v129 offset:13248
	s_waitcnt lgkmcnt(2)
	v_mfma_f32_16x16x32_f16 v[10:13], v[10:13], v[36:39], 0
	s_mov_b32 s11, 0xf149f2ca
	v_mad_i64_i32 v[50:51], s[6:7], v9, s10, v[52:53]
	s_waitcnt lgkmcnt(1)
	v_mfma_f32_16x16x32_f16 v[4:7], v[4:7], v[32:35], v[10:13]
	v_lshl_add_u64 v[50:51], v[50:51], 0, v[84:85]
	s_mov_b32 s9, 0x3db504f3
	v_lshlrev_b32_e32 v168, 3, v94
	s_nop 0
	v_and_b32_e32 v10, 64, v23
	v_add_u32_e32 v41, 64, v10
	ds_read_b128 v[10:13], v129 offset:8704
	v_mfma_f32_16x16x32_f16 v[4:7], v[14:17], v[28:31], v[4:7]
	ds_read_b128 v[14:17], v129 offset:8768
	v_cmp_lt_i32_e32 vcc, v40, v41
	v_lshl_add_u64 v[176:177], v[176:177], 0, v[168:169]
	v_mfma_f32_16x16x32_f16 v[18:21], v[18:21], v[24:27], v[4:7]
	v_cndmask_b32_e32 v40, v23, v40, vcc
	v_lshlrev_b32_e32 v173, 2, v40
	v_xor_b32_e32 v40, 32, v23
	s_nop 0
	ds_read_b128 v[4:7], v129 offset:8832
	s_waitcnt lgkmcnt(2)
	v_mfma_f32_16x16x32_f16 v[10:13], v[10:13], v[36:39], 0
	v_cmp_lt_i32_e32 vcc, v40, v41
	v_ashrrev_i32_e32 v175, 31, v174
	v_lshlrev_b64 v[174:175], 12, v[174:175]
	v_cndmask_b32_e32 v23, v23, v40, vcc
	ds_read_b128 v[40:43], v129 offset:8896
	s_waitcnt lgkmcnt(2)
	v_mfma_f32_16x16x32_f16 v[10:13], v[14:17], v[32:35], v[10:13]
	v_lshlrev_b32_e32 v225, 2, v23
	v_sub_u32_e32 v23, v104, v168
	v_mad_u32_u24 v100, v107, s8, v23
	s_waitcnt lgkmcnt(1)
	v_mfma_f32_16x16x32_f16 v[4:7], v[4:7], v[28:31], v[10:13]
	v_add_u32_e32 v131, 0x9800, v100
	v_add_u32_e32 v132, 0xa000, v100
	v_add_u32_e32 v133, 0xa800, v100
	ds_read_b128 v[10:13], v129 offset:13056
	s_waitcnt lgkmcnt(1)
	v_mfma_f32_16x16x32_f16 v[14:17], v[40:43], v[24:27], v[4:7]
	v_mad_i64_i32 v[40:41], s[6:7], v8, s10, v[52:53]
	v_lshl_add_u64 v[48:49], v[40:41], 0, v[84:85]
	s_nop 0
	ds_read_b128 v[4:7], v129 offset:13120
	ds_read_b128 v[40:43], v129 offset:13184
	s_waitcnt lgkmcnt(2)
	v_mfma_f32_16x16x32_f16 v[10:13], v[10:13], v[36:39], 0
	v_add_u32_e32 v134, 0xb000, v100
	v_add_u32_e32 v135, 0xb800, v100
	v_add_u32_e32 v23, 0x8800, v100
	s_waitcnt lgkmcnt(1)
	v_mfma_f32_16x16x32_f16 v[10:13], v[4:7], v[32:35], v[10:13]
	global_load_dwordx4 v[4:7], v[48:49], off
	s_nop 0
	global_load_dwordx4 v[48:51], v[50:51], off
	v_add_u32_e32 v136, 0xc000, v100
	v_add_u32_e32 v130, 0x9000, v100
	s_waitcnt lgkmcnt(0)
	v_mfma_f32_16x16x32_f16 v[10:13], v[40:43], v[28:31], v[10:13]
	v_mul_f32_e32 v42, 0x3db504f3, v0
	v_mul_f32_e32 v43, 0x3db504f3, v1
	v_max3_f32 v42, v42, s11, v43
	v_mfma_f32_16x16x32_f16 v[10:13], v[44:47], v[24:27], v[10:13]
	v_mul_f32_e32 v43, 0x3db504f3, v2
	v_mul_f32_e32 v44, 0x3db504f3, v3
	v_max3_f32 v42, v42, v43, v44
	v_mul_f32_e32 v43, 0x3db504f3, v18
	v_mul_f32_e32 v44, 0x3db504f3, v19
	v_max3_f32 v42, v42, v43, v44
	v_mul_f32_e32 v43, 0x3db504f3, v20
	v_mul_f32_e32 v44, 0x3db504f3, v21
	v_max3_f32 v42, v42, v43, v44
	v_mul_f32_e32 v43, 0x3db504f3, v14
	v_mul_f32_e32 v44, 0x3db504f3, v15
	v_max3_f32 v42, v42, v43, v44
	v_mul_f32_e32 v43, 0x3db504f3, v16
	v_mul_f32_e32 v44, 0x3db504f3, v17
	v_max3_f32 v42, v42, v43, v44
	v_mul_f32_e32 v43, 0x3db504f3, v10
	v_mul_f32_e32 v44, 0x3db504f3, v11
	v_max3_f32 v42, v42, v43, v44
	v_mul_f32_e32 v43, 0x3db504f3, v12
	v_mul_f32_e32 v44, 0x3db504f3, v13
	v_max3_f32 v44, v42, v43, v44
	ds_bpermute_b32 v45, v173, v44
	v_mad_i64_i32 v[40:41], s[6:7], v97, s10, v[52:53]
	v_lshl_add_u64 v[40:41], v[40:41], 0, v[84:85]
	v_mad_i64_i32 v[42:43], s[6:7], v95, s10, v[52:53]
	v_lshl_add_u64 v[42:43], v[42:43], 0, v[84:85]
	global_load_dwordx4 v[60:63], v[40:41], off
	global_load_dwordx4 v[64:67], v[42:43], off
	s_waitcnt lgkmcnt(0)
	v_max_f32_e32 v40, v45, v45
	v_max_f32_e32 v40, v44, v40
	ds_bpermute_b32 v41, v225, v40
	global_load_dwordx4 v[68:71], v[86:87], off offset:256
	global_load_dwordx4 v[72:75], v[88:89], off offset:256
	global_load_dwordx4 v[76:79], v[90:91], off offset:256
	global_load_dwordx4 v[80:83], v[98:99], off offset:256
	ds_read2_b64 v[52:55], v131 offset0:64 offset1:68
	ds_read2_b64 v[56:59], v132 offset0:96 offset1:100
	ds_read2_b64 v[44:47], v130 offset0:32 offset1:36
	s_waitcnt lgkmcnt(3)
	v_max3_f32 v101, v40, v41, s11
	v_fma_f32 v0, v0, s9, -v101
	v_mul_f32_e32 v0, 0x3fb8aa3b, v0
	v_exp_f32_e32 v137, v0
	v_fma_f32 v0, v1, s9, -v101
	v_mul_f32_e32 v0, 0x3fb8aa3b, v0
	v_exp_f32_e32 v138, v0
	v_fma_f32 v0, v2, s9, -v101
	v_mul_f32_e32 v0, 0x3fb8aa3b, v0
	v_exp_f32_e32 v96, v0
	v_fma_f32 v0, v3, s9, -v101
	v_mul_f32_e32 v0, 0x3fb8aa3b, v0
	v_exp_f32_e32 v94, v0
	v_fma_f32 v0, v18, s9, -v101
	v_mul_f32_e32 v0, 0x3fb8aa3b, v0
	v_exp_f32_e32 v108, v0
	v_fma_f32 v0, v19, s9, -v101
	v_mul_f32_e32 v0, 0x3fb8aa3b, v0
	v_exp_f32_e32 v104, v0
	v_fma_f32 v0, v20, s9, -v101
	v_mul_f32_e32 v0, 0x3fb8aa3b, v0
	v_exp_f32_e32 v110, v0
	v_fma_f32 v0, v21, s9, -v101
	v_mul_f32_e32 v0, 0x3fb8aa3b, v0
	v_sub_f32_e32 v40, 0xf149f2ca, v101
	v_exp_f32_e32 v106, v0
	v_fma_f32 v0, v14, s9, -v101
	v_mul_f32_e32 v40, 0x3fb8aa3b, v40
	v_mul_f32_e32 v0, 0x3fb8aa3b, v0
	v_exp_f32_e32 v112, v0
	v_exp_f32_e32 v0, v40
	v_fma_f32 v1, v15, s9, -v101
	v_fma_f32 v14, v16, s9, -v101
	v_mul_f32_e32 v1, 0x3fb8aa3b, v1
	v_mul_f32_e32 v0, 0, v0
	v_mul_f32_e32 v14, 0x3fb8aa3b, v14
	v_exp_f32_e32 v114, v1
	v_mov_b32_e32 v1, v0
	v_mov_b32_e32 v2, v0
	v_mov_b32_e32 v3, v0
	v_cvt_pk_f16_f32 v43, v110, v106
	v_cvt_pk_f16_f32 v42, v108, v104
	v_cvt_pk_f16_f32 v41, v96, v94
	v_cvt_pk_f16_f32 v40, v137, v138
	v_exp_f32_e32 v116, v14
	v_fma_f32 v14, v17, s9, -v101
	v_mul_f32_e32 v102, 0x3fb8aa3b, v14
	s_waitcnt lgkmcnt(2)
	v_mfma_f32_16x16x32_f16 v[14:17], v[52:55], v[40:43], v[0:3]
	ds_read2_b64 v[52:55], v133 offset0:128 offset1:132
	v_fma_f32 v10, v10, s9, -v101
	v_mul_f32_e32 v10, 0x3fb8aa3b, v10
	s_waitcnt lgkmcnt(2)
	v_mfma_f32_16x16x32_f16 v[140:143], v[56:59], v[40:43], v[0:3]
	ds_read2_b64 v[56:59], v134 offset0:160 offset1:164
	ds_read2_b64 v[18:21], v23 offset1:4
	v_exp_f32_e32 v120, v10
	s_waitcnt lgkmcnt(2)
	v_mfma_f32_16x16x32_f16 v[144:147], v[52:55], v[40:43], v[0:3]
	ds_read2_b64 v[52:55], v135 offset0:192 offset1:196
	v_fma_f32 v10, v11, s9, -v101
	v_mul_f32_e32 v103, 0x3fb8aa3b, v10
	v_fma_f32 v10, v12, s9, -v101
	v_mul_f32_e32 v10, 0x3fb8aa3b, v10
	v_exp_f32_e32 v118, v10
	v_fma_f32 v10, v13, s9, -v101
	s_waitcnt lgkmcnt(2)
	v_mfma_f32_16x16x32_f16 v[148:151], v[56:59], v[40:43], v[0:3]
	ds_read2_b64 v[56:59], v136 offset0:224 offset1:228
	v_mul_f32_e32 v105, 0x3fb8aa3b, v10
	v_exp_f32_e32 v122, v105
	s_waitcnt lgkmcnt(1)
	v_mfma_f32_16x16x32_f16 v[10:13], v[52:55], v[40:43], v[0:3]
	ds_read2_b64 v[52:55], v23 offset0:8 offset1:12
	v_exp_f32_e32 v124, v103
	v_exp_f32_e32 v126, v102
	v_mfma_f32_16x16x32_f16 v[18:21], v[18:21], v[40:43], v[0:3]
	v_cvt_pk_f16_f32 v159, v118, v122
	v_cvt_pk_f16_f32 v158, v120, v124
	v_cvt_pk_f16_f32 v157, v116, v126
	v_cvt_pk_f16_f32 v156, v112, v114
	s_waitcnt lgkmcnt(1)
	v_mfma_f32_16x16x32_f16 v[152:155], v[56:59], v[40:43], v[0:3]
	s_add_u32 s6, s5, 0x243c20
	s_addc_u32 s7, s4, 0
	v_add_u32_e32 v189, 0xf800, v100
	s_waitcnt lgkmcnt(0)
	v_mfma_f32_16x16x32_f16 v[56:59], v[52:55], v[156:159], v[18:21]
	v_add_u32_e32 v187, 0xf000, v100
	v_add_co_u32_e32 v222, vcc, s33, v176
	s_nop 0
	ds_read2_b64 v[18:21], v130 offset0:40 offset1:44
	v_mfma_f32_16x16x32_f16 v[44:47], v[44:47], v[40:43], v[0:3]
	v_addc_co_u32_e32 v223, vcc, 0, v177, vcc
	v_lshl_add_u64 v[174:175], s[20:21], 0, v[174:175]
	s_waitcnt lgkmcnt(0)
	v_mfma_f32_16x16x32_f16 v[52:55], v[18:21], v[156:159], v[44:47]
	ds_read2_b64 v[18:21], v131 offset0:72 offset1:76
	v_lshl_add_u64 v[174:175], v[174:175], 0, s[0:1]
	s_mov_b32 s0, 0x4800000
	s_waitcnt lgkmcnt(0)
	v_mfma_f32_16x16x32_f16 v[44:47], v[18:21], v[156:159], v[14:17]
	s_nop 2
	ds_read2_b64 v[14:17], v132 offset0:104 offset1:108
	s_movk_i32 s3, 0x3020
	s_mov_b32 s2, 0xf149f2ca
	s_waitcnt lgkmcnt(0)
	v_mfma_f32_16x16x32_f16 v[40:43], v[14:17], v[156:159], v[140:143]
	ds_read2_b64 v[14:17], v133 offset0:136 offset1:140
	s_nop 1
	ds_read2_b64 v[140:143], v135 offset0:200 offset1:204
	s_waitcnt lgkmcnt(1)
	v_mfma_f32_16x16x32_f16 v[18:21], v[14:17], v[156:159], v[144:147]
	ds_read2_b64 v[14:17], v134 offset0:168 offset1:172
	s_waitcnt lgkmcnt(1)
	v_mfma_f32_16x16x32_f16 v[10:13], v[140:143], v[156:159], v[10:13]
	ds_read2_b64 v[140:143], v136 offset0:232 offset1:236
	s_waitcnt lgkmcnt(0)
	s_barrier
	s_waitcnt vmcnt(7)
	ds_write_b128 v92, v[4:7]
	s_waitcnt vmcnt(6)
	ds_write_b128 v92, v[48:51] offset:4352
	s_waitcnt vmcnt(5)
	ds_write_b128 v92, v[60:63] offset:8704
	s_waitcnt vmcnt(4)
	ds_write_b128 v92, v[64:67] offset:13056
	s_waitcnt vmcnt(3)
	ds_write_b128 v22, v[68:71] offset:34816
	s_waitcnt vmcnt(2)
	ds_write_b128 v22, v[72:75] offset:39424
	s_waitcnt vmcnt(1)
	ds_write_b128 v22, v[76:79] offset:44032
	s_waitcnt vmcnt(0)
	ds_write_b128 v22, v[80:83] offset:48640
	ds_read_b128 v[2:5], v129 offset:17408
	ds_read_b128 v[60:63], v129 offset:17472
	s_waitcnt lgkmcnt(1)
	v_mfma_f32_16x16x32_f16 v[2:5], v[2:5], v[36:39], 0
	ds_read_b128 v[64:67], v129 offset:17536
	ds_read_b128 v[68:71], v129 offset:30656
	v_mov_b64_e32 v[72:73], s[6:7]
	s_waitcnt lgkmcnt(2)
	v_mfma_f32_16x16x32_f16 v[2:5], v[60:63], v[32:35], v[2:5]
	ds_read_b128 v[60:63], v129 offset:17600
	v_mad_i64_i32 v[6:7], s[4:5], v8, s10, v[72:73]
	s_waitcnt lgkmcnt(2)
	v_mfma_f32_16x16x32_f16 v[2:5], v[64:67], v[28:31], v[2:5]
	ds_read_b128 v[64:67], v129 offset:21760
	v_mad_i64_i32 v[8:9], s[4:5], v9, s10, v[72:73]
	s_waitcnt lgkmcnt(1)
	v_mfma_f32_16x16x32_f16 v[80:83], v[60:63], v[24:27], v[2:5]
	v_lshl_add_u64 v[6:7], v[6:7], 0, v[84:85]
	v_lshl_add_u64 v[8:9], v[8:9], 0, v[84:85]
	s_nop 1
	ds_read_b128 v[2:5], v129 offset:21824
	s_waitcnt lgkmcnt(1)
	v_mfma_f32_16x16x32_f16 v[60:63], v[64:67], v[36:39], 0
	ds_read_b128 v[64:67], v129 offset:21888
	v_mul_f32_e32 v1, 0x3db504f3, v80
	s_waitcnt lgkmcnt(1)
	v_mfma_f32_16x16x32_f16 v[2:5], v[2:5], v[32:35], v[60:63]
	s_nop 3
	ds_read_b128 v[60:63], v129 offset:21952
	s_waitcnt lgkmcnt(1)
	v_mfma_f32_16x16x32_f16 v[2:5], v[64:67], v[28:31], v[2:5]
	ds_read_b128 v[64:67], v129 offset:26112
	v_mfma_f32_16x16x32_f16 v[48:51], v[140:143], v[156:159], v[152:155]
	s_waitcnt lgkmcnt(1)
	v_mfma_f32_16x16x32_f16 v[140:143], v[60:63], v[24:27], v[2:5]
	s_nop 3
	ds_read_b128 v[2:5], v129 offset:26176
	s_waitcnt lgkmcnt(1)
	v_mfma_f32_16x16x32_f16 v[60:63], v[64:67], v[36:39], 0
	ds_read_b128 v[64:67], v129 offset:26240
	s_waitcnt lgkmcnt(1)
	v_mfma_f32_16x16x32_f16 v[2:5], v[2:5], v[32:35], v[60:63]
	s_nop 4
	ds_read_b128 v[60:63], v129 offset:26304
	s_waitcnt lgkmcnt(1)
	v_mfma_f32_16x16x32_f16 v[2:5], v[64:67], v[28:31], v[2:5]
	ds_read_b128 v[64:67], v129 offset:30464
	s_waitcnt lgkmcnt(1)
	v_mfma_f32_16x16x32_f16 v[144:147], v[60:63], v[24:27], v[2:5]
	ds_read_b128 v[60:63], v129 offset:30592
	s_nop 3
	ds_read_b128 v[2:5], v129 offset:30528
	s_waitcnt lgkmcnt(2)
	v_mfma_f32_16x16x32_f16 v[64:67], v[64:67], v[36:39], 0
	s_waitcnt lgkmcnt(0)
	v_mfma_f32_16x16x32_f16 v[64:67], v[2:5], v[32:35], v[64:67]
	global_load_dwordx4 v[2:5], v[6:7], off
	s_nop 0
	global_load_dwordx4 v[6:9], v[8:9], off
	v_mfma_f32_16x16x32_f16 v[60:63], v[60:63], v[28:31], v[64:67]
	v_mfma_f32_16x16x32_f16 v[68:71], v[68:71], v[24:27], v[60:63]
	s_nop 2
	v_mad_i64_i32 v[64:65], s[4:5], v97, s10, v[72:73]
	v_lshl_add_u64 v[64:65], v[64:65], 0, v[84:85]
	s_nop 1
	v_mul_f32_e32 v60, 0x3db504f3, v81
	v_max3_f32 v1, v1, s11, v60
	v_mul_f32_e32 v60, 0x3db504f3, v82
	v_mul_f32_e32 v61, 0x3db504f3, v83
	v_max3_f32 v1, v1, v60, v61
	v_mul_f32_e32 v60, 0x3db504f3, v140
	v_mul_f32_e32 v61, 0x3db504f3, v141
	v_max3_f32 v1, v1, v60, v61
	v_mul_f32_e32 v60, 0x3db504f3, v142
	v_mul_f32_e32 v61, 0x3db504f3, v143
	v_max3_f32 v1, v1, v60, v61
	v_mul_f32_e32 v60, 0x3db504f3, v144
	v_mul_f32_e32 v61, 0x3db504f3, v145
	v_max3_f32 v1, v1, v60, v61
	v_mul_f32_e32 v60, 0x3db504f3, v146
	v_mul_f32_e32 v61, 0x3db504f3, v147
	v_max3_f32 v1, v1, v60, v61
	v_mul_f32_e32 v60, 0x3db504f3, v68
	v_mul_f32_e32 v61, 0x3db504f3, v69
	v_max3_f32 v1, v1, v60, v61
	v_mul_f32_e32 v60, 0x3db504f3, v70
	v_mul_f32_e32 v61, 0x3db504f3, v71
	v_max3_f32 v1, v1, v60, v61
	ds_bpermute_b32 v74, v173, v1
	v_mad_i64_i32 v[60:61], s[4:5], v95, s10, v[72:73]
	v_lshl_add_u64 v[66:67], v[60:61], 0, v[84:85]
	global_load_dwordx4 v[60:63], v[64:65], off
	s_nop 0
	global_load_dwordx4 v[64:67], v[66:67], off
	s_waitcnt lgkmcnt(0)
	v_max_f32_e32 v72, v74, v74
	v_max_f32_e32 v1, v1, v72
	ds_bpermute_b32 v95, v225, v1
	global_load_dwordx4 v[72:75], v[86:87], off offset:384
	global_load_dwordx4 v[76:79], v[88:89], off offset:384
	s_nop 0
	global_load_dwordx4 v[84:87], v[90:91], off offset:384
	s_nop 0
	global_load_dwordx4 v[88:91], v[98:99], off offset:384
	v_mfma_f32_16x16x32_f16 v[14:17], v[14:17], v[156:159], v[148:151]
	s_waitcnt lgkmcnt(0)
	v_max3_f32 v139, v101, v1, v95
	v_fma_f32 v80, v80, s9, -v139
	v_mul_f32_e32 v80, 0x3fb8aa3b, v80
	v_exp_f32_e32 v97, v80
	v_fma_f32 v80, v81, s9, -v139
	v_mul_f32_e32 v80, 0x3fb8aa3b, v80
	v_exp_f32_e32 v95, v80
	v_fma_f32 v80, v82, s9, -v139
	v_mul_f32_e32 v80, 0x3fb8aa3b, v80
	v_exp_f32_e32 v109, v80
	v_fma_f32 v80, v83, s9, -v139
	v_mul_f32_e32 v80, 0x3fb8aa3b, v80
	v_exp_f32_e32 v105, v80
	v_fma_f32 v80, v140, s9, -v139
	v_mul_f32_e32 v80, 0x3fb8aa3b, v80
	v_exp_f32_e32 v111, v80
	v_fma_f32 v80, v141, s9, -v139
	v_mul_f32_e32 v80, 0x3fb8aa3b, v80
	v_exp_f32_e32 v107, v80
	v_fma_f32 v80, v142, s9, -v139
	v_mul_f32_e32 v80, 0x3fb8aa3b, v80
	v_exp_f32_e32 v113, v80
	v_fma_f32 v80, v143, s9, -v139
	v_mul_f32_e32 v80, 0x3fb8aa3b, v80
	v_exp_f32_e32 v115, v80
	v_fma_f32 v80, v144, s9, -v139
	v_mul_f32_e32 v80, 0x3fb8aa3b, v80
	v_exp_f32_e32 v117, v80
	v_fma_f32 v80, v145, s9, -v139
	v_mul_f32_e32 v80, 0x3fb8aa3b, v80
	v_exp_f32_e32 v127, v80
	v_fma_f32 v80, v146, s9, -v139
	v_mul_f32_e32 v80, 0x3fb8aa3b, v80
	v_exp_f32_e32 v121, v80
	v_fma_f32 v80, v147, s9, -v139
	v_mul_f32_e32 v80, 0x3fb8aa3b, v80
	v_add_u32_e32 v140, 0xd000, v100
	v_exp_f32_e32 v125, v80
	ds_read2_b64 v[80:83], v140 offset1:4
	v_sub_f32_e32 v1, v101, v139
	v_mul_f32_e32 v1, 0x3fb8aa3b, v1
	v_exp_f32_e32 v128, v1
	v_add_u32_e32 v141, 0xd800, v100
	ds_read2_b64 v[148:151], v141 offset0:32 offset1:36
	v_cvt_pk_f16_f32 v147, v113, v115
	v_pk_mul_f32 v[58:59], v[58:59], v[128:129] op_sel_hi:[1,0]
	v_pk_mul_f32 v[56:57], v[56:57], v[128:129] op_sel_hi:[1,0]
	v_cvt_pk_f16_f32 v146, v111, v107
	v_cvt_pk_f16_f32 v145, v109, v105
	v_cvt_pk_f16_f32 v144, v97, v95
	v_add_u32_e32 v142, 0xe000, v100
	v_fma_f32 v68, v68, s9, -v139
	s_waitcnt lgkmcnt(1)
	v_mfma_f32_16x16x32_f16 v[56:59], v[80:83], v[144:147], v[56:59]
	ds_read2_b64 v[80:83], v142 offset0:64 offset1:68
	v_mul_f32_e32 v68, 0x3fb8aa3b, v68
	v_exp_f32_e32 v119, v68
	v_fma_f32 v68, v69, s9, -v139
	v_mul_f32_e32 v68, 0x3fb8aa3b, v68
	v_exp_f32_e32 v123, v68
	v_fma_f32 v68, v70, s9, -v139
	v_pk_mul_f32 v[54:55], v[54:55], v[128:129] op_sel_hi:[1,0]
	v_pk_mul_f32 v[52:53], v[52:53], v[128:129] op_sel_hi:[1,0]
	v_add_u32_e32 v143, 0xe800, v100
	ds_read2_b64 v[98:101], v189 offset0:160 offset1:164
	v_add_u32_e32 v191, 0x3000, v140
	v_mul_f32_e32 v1, 0x3fb8aa3b, v68
	s_waitcnt lgkmcnt(2)
	v_mfma_f32_16x16x32_f16 v[52:55], v[148:151], v[144:147], v[52:55]
	ds_read2_b64 v[148:151], v143 offset0:96 offset1:100
	v_fma_f32 v102, v71, s9, -v139
	ds_read2_b64 v[68:71], v191 offset0:192 offset1:196
	v_pk_mul_f32 v[46:47], v[46:47], v[128:129] op_sel_hi:[1,0]
	v_pk_mul_f32 v[44:45], v[44:45], v[128:129] op_sel_hi:[1,0]
	v_pk_mul_f32 v[16:17], v[16:17], v[128:129] op_sel_hi:[1,0]
	v_pk_mul_f32 v[14:15], v[14:15], v[128:129] op_sel_hi:[1,0]
	s_waitcnt lgkmcnt(3)
	v_mfma_f32_16x16x32_f16 v[44:47], v[80:83], v[144:147], v[44:47]
	ds_read2_b64 v[80:83], v187 offset0:128 offset1:132
	v_add_u32_e32 v193, 0x3800, v140
	v_pk_mul_f32 v[42:43], v[42:43], v[128:129] op_sel_hi:[1,0]
	v_pk_mul_f32 v[40:41], v[40:41], v[128:129] op_sel_hi:[1,0]
	s_waitcnt lgkmcnt(3)
	v_mfma_f32_16x16x32_f16 v[98:101], v[98:101], v[144:147], v[14:17]
	v_mul_f32_e64 v12, v12, v128
	v_mul_f32_e64 v13, v13, v128
	v_pk_mul_f32 v[10:11], v[10:11], v[128:129] op_sel_hi:[1,0]
	v_pk_mul_f32 v[20:21], v[20:21], v[128:129] op_sel_hi:[1,0]
	ds_read2_b64 v[14:17], v193 offset0:224 offset1:228
	s_waitcnt lgkmcnt(3)
	v_mfma_f32_16x16x32_f16 v[40:43], v[148:151], v[144:147], v[40:43]
	v_mul_f32_e64 v18, v18, v128
	v_mul_f32_e64 v19, v19, v128
	v_exp_f32_e32 v1, v1
	v_pk_mul_f32 v[50:51], v[50:51], v[128:129] op_sel_hi:[1,0]
	s_waitcnt lgkmcnt(2)
	v_mfma_f32_16x16x32_f16 v[148:151], v[68:71], v[144:147], v[10:13]
	v_mul_f32_e64 v48, v48, v128
	v_mul_f32_e64 v49, v49, v128
	s_nop 0
	ds_read2_b64 v[10:13], v140 offset0:8 offset1:12
	s_waitcnt lgkmcnt(2)
	v_mfma_f32_16x16x32_f16 v[18:21], v[80:83], v[144:147], v[18:21]
	v_mul_f32_e32 v80, 0x3fb8aa3b, v102
	v_exp_f32_e32 v152, v80
	s_waitcnt lgkmcnt(1)
	v_mfma_f32_16x16x32_f16 v[48:51], v[14:17], v[144:147], v[48:51]
	v_cvt_pk_f16_f32 v146, v119, v123
	v_cvt_pk_f16_f32 v147, v1, v152
	v_cvt_pk_f16_f32 v145, v121, v125
	v_cvt_pk_f16_f32 v144, v117, v127
	s_waitcnt lgkmcnt(0)
	s_nop 0
	v_mfma_f32_16x16x32_f16 v[80:83], v[10:13], v[144:147], v[56:59]
	ds_read2_b64 v[10:13], v141 offset0:40 offset1:44
	s_waitcnt lgkmcnt(0)
	v_mfma_f32_16x16x32_f16 v[68:71], v[10:13], v[144:147], v[52:55]
	ds_read2_b64 v[10:13], v142 offset0:72 offset1:76
	s_waitcnt lgkmcnt(0)
	v_mfma_f32_16x16x32_f16 v[56:59], v[10:13], v[144:147], v[44:47]
	ds_read2_b64 v[10:13], v143 offset0:104 offset1:108
	s_waitcnt lgkmcnt(0)
	v_mfma_f32_16x16x32_f16 v[44:47], v[10:13], v[144:147], v[40:43]
	ds_read2_b64 v[10:13], v187 offset0:136 offset1:140
	s_waitcnt lgkmcnt(0)
	v_mfma_f32_16x16x32_f16 v[16:19], v[10:13], v[144:147], v[18:21]
	ds_read2_b64 v[10:13], v189 offset0:168 offset1:172
	ds_read2_b64 v[40:43], v191 offset0:200 offset1:204
	ds_read2_b64 v[52:55], v193 offset0:232 offset1:236
	s_waitcnt lgkmcnt(0)
	s_barrier
	s_waitcnt vmcnt(7)
	ds_write_b128 v92, v[2:5] offset:17408
	s_waitcnt vmcnt(6)
	ds_write_b128 v92, v[6:9] offset:21760
	s_waitcnt vmcnt(5)
	ds_write_b128 v92, v[60:63] offset:26112
	s_waitcnt vmcnt(4)
	ds_write_b128 v92, v[64:67] offset:30464
	s_waitcnt vmcnt(3)
	ds_write_b128 v22, v[72:75] offset:53248
	s_waitcnt vmcnt(2)
	ds_write_b128 v22, v[76:79] offset:57856
	s_waitcnt vmcnt(1)
	ds_write_b128 v22, v[84:87] offset:62464
	s_waitcnt vmcnt(0)
	ds_write_b128 v93, v[88:91] offset:32256
	ds_read_b128 v[2:5], v129
	v_mfma_f32_16x16x32_f16 v[8:11], v[10:13], v[144:147], v[98:101]
	ds_read_b128 v[12:15], v129 offset:64
	ds_read_b128 v[60:63], v129 offset:128
	ds_read_b128 v[64:67], v129 offset:4480
	s_waitcnt lgkmcnt(3)
	v_mfma_f32_16x16x32_f16 v[2:5], v[2:5], v[36:39], 0
	ds_read_b128 v[72:75], v129 offset:8896
	v_add_f32_e32 v6, 0, v137
	v_add_f32_e32 v6, v138, v6
	s_waitcnt lgkmcnt(3)
	v_mfma_f32_16x16x32_f16 v[2:5], v[12:15], v[32:35], v[2:5]
	ds_read_b128 v[12:15], v129 offset:192
	v_mov_b32_e32 v7, v169
	v_pk_add_f32 v[6:7], v[96:97], v[6:7]
	s_waitcnt lgkmcnt(3)
	v_mfma_f32_16x16x32_f16 v[2:5], v[60:63], v[28:31], v[2:5]
	ds_read_b128 v[60:63], v129 offset:4352
	s_waitcnt lgkmcnt(1)
	v_mfma_f32_16x16x32_f16 v[12:15], v[12:15], v[24:27], v[2:5]
	s_nop 4
	ds_read_b128 v[2:5], v129 offset:4416
	s_waitcnt lgkmcnt(1)
	v_mfma_f32_16x16x32_f16 v[60:63], v[60:63], v[36:39], 0
	s_waitcnt lgkmcnt(0)
	v_mfma_f32_16x16x32_f16 v[2:5], v[2:5], v[32:35], v[60:63]
	s_nop 5
	ds_read_b128 v[60:63], v129 offset:4544
	v_mfma_f32_16x16x32_f16 v[2:5], v[64:67], v[28:31], v[2:5]
	ds_read_b128 v[64:67], v129 offset:8704
	s_waitcnt lgkmcnt(1)
	v_mfma_f32_16x16x32_f16 v[100:103], v[60:63], v[24:27], v[2:5]
	s_nop 4
	ds_read_b128 v[2:5], v129 offset:8768
	s_waitcnt lgkmcnt(1)
	v_mfma_f32_16x16x32_f16 v[60:63], v[64:67], v[36:39], 0
	ds_read_b128 v[64:67], v129 offset:8832
	s_waitcnt lgkmcnt(1)
	v_mfma_f32_16x16x32_f16 v[2:5], v[2:5], v[32:35], v[60:63]
	s_nop 4
	ds_read_b128 v[60:63], v129 offset:13056
	s_waitcnt lgkmcnt(1)
	v_mfma_f32_16x16x32_f16 v[2:5], v[64:67], v[28:31], v[2:5]
	ds_read_b128 v[64:67], v129 offset:13120
	v_mfma_f32_16x16x32_f16 v[96:99], v[72:75], v[24:27], v[2:5]
	ds_read_b128 v[72:75], v129 offset:13248
	s_nop 4
	v_pk_add_f32 v[2:3], v[94:95], v[6:7]
	s_waitcnt lgkmcnt(2)
	v_mfma_f32_16x16x32_f16 v[60:63], v[60:63], v[36:39], 0
	v_add_f32_e64 v6, v108, v2
	v_add_f32_e64 v7, v109, v3
	ds_read_b128 v[2:5], v129 offset:13184
	v_pk_add_f32 v[6:7], v[104:105], v[6:7]
	s_waitcnt lgkmcnt(2)
	v_mfma_f32_16x16x32_f16 v[60:63], v[64:67], v[32:35], v[60:63]
	v_add_f32_e64 v6, v110, v6
	v_add_f32_e64 v7, v111, v7
	v_pk_add_f32 v[6:7], v[106:107], v[6:7]
	s_waitcnt lgkmcnt(0)
	v_mfma_f32_16x16x32_f16 v[2:5], v[2:5], v[28:31], v[60:63]
	v_add_f32_e64 v6, v112, v6
	v_add_f32_e64 v7, v113, v7
	v_pk_add_f32 v[6:7], v[114:115], v[6:7]
	v_mfma_f32_16x16x32_f16 v[88:91], v[72:75], v[24:27], v[2:5]
	v_add_f32_e64 v6, v116, v6
	v_add_f32_e64 v7, v117, v7
	v_pk_add_f32 v[6:7], v[126:127], v[6:7]
	s_nop 0
	v_mul_f32_e32 v2, 0x3db504f3, v12
	v_mul_f32_e32 v3, 0x3db504f3, v13
	v_max3_f32 v2, v2, s11, v3
	v_mul_f32_e32 v3, 0x3db504f3, v14
	v_mul_f32_e32 v4, 0x3db504f3, v15
	v_max3_f32 v2, v2, v3, v4
	v_mul_f32_e32 v3, 0x3db504f3, v100
	v_mul_f32_e32 v4, 0x3db504f3, v101
	v_max3_f32 v2, v2, v3, v4
	v_mul_f32_e32 v3, 0x3db504f3, v102
	v_mul_f32_e32 v4, 0x3db504f3, v103
	v_max3_f32 v2, v2, v3, v4
	v_mul_f32_e32 v3, 0x3db504f3, v96
	v_mul_f32_e32 v4, 0x3db504f3, v97
	v_max3_f32 v2, v2, v3, v4
	v_mul_f32_e32 v3, 0x3db504f3, v98
	v_mul_f32_e32 v4, 0x3db504f3, v99
	v_max3_f32 v2, v2, v3, v4
	v_mul_f32_e32 v3, 0x3db504f3, v88
	v_mul_f32_e32 v4, 0x3db504f3, v89
	v_max3_f32 v2, v2, v3, v4
	v_mul_f32_e32 v3, 0x3db504f3, v90
	v_mul_f32_e32 v4, 0x3db504f3, v91
	v_max3_f32 v20, v2, v3, v4
	ds_bpermute_b32 v21, v173, v20
	v_pk_add_f32 v[6:7], v[120:121], v[6:7]
	s_waitcnt lgkmcnt(0)
	v_max_f32_e32 v21, v21, v21
	v_max_f32_e32 v22, v20, v21
	v_pk_add_f32 v[2:3], v[124:125], v[6:7]
	v_mfma_f32_16x16x32_f16 v[4:7], v[40:43], v[144:147], v[148:151]
	ds_bpermute_b32 v40, v225, v22
	v_pk_add_f32 v[2:3], v[118:119], v[2:3]
	s_waitcnt lgkmcnt(0)
	v_max3_f32 v114, v139, v22, v40
	v_fma_f32 v12, v12, s9, -v114
	v_pk_add_f32 v[2:3], v[122:123], v[2:3]
	v_mul_f32_e32 v12, 0x3fb8aa3b, v12
	v_pk_add_f32 v[20:21], v[0:1], v[2:3]
	v_exp_f32_e32 v115, v12
	v_fma_f32 v12, v13, s9, -v114
	v_add_f32_e32 v113, v21, v152
	v_mul_f32_e32 v12, 0x3fb8aa3b, v12
	v_fmac_f32_e32 v113, v20, v128
	v_exp_f32_e32 v128, v12
	v_sub_f32_e32 v12, v139, v114
	v_mul_f32_e32 v138, 0x3fb8aa3b, v12
	v_add_f32_e32 v12, 0, v115
	v_add_f32_e32 v112, v128, v12
	v_fma_f32 v12, v14, s9, -v114
	v_mul_f32_e32 v12, 0x3fb8aa3b, v12
	v_exp_f32_e32 v178, v12
	v_fma_f32 v12, v15, s9, -v114
	v_mul_f32_e32 v12, 0x3fb8aa3b, v12
	v_exp_f32_e32 v180, v12
	v_fma_f32 v12, v100, s9, -v114
	v_mul_f32_e32 v12, 0x3fb8aa3b, v12
	v_mfma_f32_16x16x32_f16 v[0:3], v[52:55], v[144:147], v[48:51]
	v_exp_f32_e32 v182, v12
	ds_read2_b64 v[104:107], v23 offset1:4
	ds_read2_b64 v[116:119], v130 offset0:32 offset1:36
	ds_read2_b64 v[92:95], v131 offset0:64 offset1:68
	ds_read2_b64 v[76:79], v132 offset0:96 offset1:100
	ds_read2_b64 v[64:67], v133 offset0:128 offset1:132
	ds_read2_b64 v[52:55], v134 offset0:160 offset1:164
	ds_read2_b64 v[40:43], v135 offset0:192 offset1:196
	ds_read2_b64 v[12:15], v136 offset0:224 offset1:228
	ds_read2_b64 v[120:123], v23 offset0:8 offset1:12
	ds_read2_b64 v[124:127], v130 offset0:40 offset1:44
	ds_read2_b64 v[108:111], v131 offset0:72 offset1:76
	ds_read2_b64 v[84:87], v132 offset0:104 offset1:108
	ds_read2_b64 v[72:75], v133 offset0:136 offset1:140
	ds_read2_b64 v[60:63], v134 offset0:168 offset1:172
	ds_read2_b64 v[48:51], v135 offset0:200 offset1:204
	ds_read2_b64 v[20:23], v136 offset0:232 offset1:236
	s_waitcnt lgkmcnt(0)
	s_barrier
	ds_read_b128 v[130:133], v129 offset:17408
	ds_read_b128 v[134:137], v129 offset:17472
	v_fma_f32 v100, v101, s9, -v114
	v_mul_f32_e32 v100, 0x3fb8aa3b, v100
	v_exp_f32_e32 v184, v100
	v_fma_f32 v100, v102, s9, -v114
	v_mul_f32_e32 v100, 0x3fb8aa3b, v100
	v_exp_f32_e32 v186, v100
	v_fma_f32 v139, v103, s9, -v114
	ds_read_b128 v[100:103], v129 offset:17536
	ds_read_b128 v[144:147], v129 offset:17600
	s_waitcnt lgkmcnt(3)
	v_mfma_f32_16x16x32_f16 v[130:133], v[130:133], v[36:39], 0
	v_fma_f32 v96, v96, s9, -v114
	v_mul_f32_e32 v96, 0x3fb8aa3b, v96
	v_exp_f32_e32 v190, v96
	s_waitcnt lgkmcnt(2)
	v_mfma_f32_16x16x32_f16 v[130:133], v[134:137], v[32:35], v[130:133]
	ds_read_b128 v[134:137], v129 offset:21760
	v_fma_f32 v96, v97, s9, -v114
	v_mul_f32_e32 v96, 0x3fb8aa3b, v96
	s_waitcnt lgkmcnt(2)
	v_mfma_f32_16x16x32_f16 v[100:103], v[100:103], v[28:31], v[130:133]
	v_mul_f32_e32 v139, 0x3fb8aa3b, v139
	v_exp_f32_e32 v194, v96
	v_fma_f32 v96, v98, s9, -v114
	ds_read_b128 v[130:133], v129 offset:21824
	s_waitcnt lgkmcnt(2)
	v_mfma_f32_16x16x32_f16 v[144:147], v[144:147], v[24:27], v[100:103]
	v_exp_f32_e32 v188, v139
	v_mul_f32_e32 v96, 0x3fb8aa3b, v96
	v_fma_f32 v139, v99, s9, -v114
	ds_read_b128 v[100:103], v129 offset:21888
	ds_read_b128 v[148:151], v129 offset:21952
	s_waitcnt lgkmcnt(3)
	v_mfma_f32_16x16x32_f16 v[134:137], v[134:137], v[36:39], 0
	v_exp_f32_e32 v192, v96
	v_fma_f32 v88, v88, s9, -v114
	v_mul_f32_e32 v88, 0x3fb8aa3b, v88
	s_waitcnt lgkmcnt(2)
	v_mfma_f32_16x16x32_f16 v[130:133], v[130:133], v[32:35], v[134:137]
	v_exp_f32_e32 v198, v88
	v_fma_f32 v88, v89, s9, -v114
	v_mul_f32_e32 v88, 0x3fb8aa3b, v88
	ds_read_b128 v[134:137], v129 offset:26112
	s_waitcnt lgkmcnt(2)
	v_mfma_f32_16x16x32_f16 v[96:99], v[100:103], v[28:31], v[130:133]
	v_mul_f32_e32 v100, 0x3fb8aa3b, v139
	v_exp_f32_e32 v196, v100
	ds_read_b128 v[100:103], v129 offset:26176
	ds_read_b128 v[130:133], v129 offset:26240
	s_waitcnt lgkmcnt(2)
	v_mfma_f32_16x16x32_f16 v[134:137], v[134:137], v[36:39], 0
	v_exp_f32_e32 v200, v88
	v_fma_f32 v88, v90, s9, -v114
	v_mul_f32_e32 v88, 0x3fb8aa3b, v88
	s_waitcnt lgkmcnt(1)
	v_mfma_f32_16x16x32_f16 v[100:103], v[100:103], v[32:35], v[134:137]
	v_exp_f32_e32 v202, v88
	v_fma_f32 v139, v91, s9, -v114
	ds_read_b128 v[88:91], v129 offset:30592
	ds_read_b128 v[134:137], v129 offset:30464
	v_mfma_f32_16x16x32_f16 v[96:99], v[148:151], v[24:27], v[96:99]
	ds_read_b128 v[148:151], v129 offset:26304
	s_waitcnt lgkmcnt(3)
	v_mfma_f32_16x16x32_f16 v[100:103], v[130:133], v[28:31], v[100:103]
	ds_read_b128 v[130:133], v129 offset:30528
	s_waitcnt lgkmcnt(2)
	v_mfma_f32_16x16x32_f16 v[134:137], v[134:137], v[36:39], 0
	v_exp_f32_e32 v38, v138
	v_mul_f32_e32 v36, 0x3fb8aa3b, v139
	v_exp_f32_e32 v204, v36
	s_waitcnt lgkmcnt(1)
	v_mfma_f32_16x16x32_f16 v[100:103], v[148:151], v[24:27], v[100:103]
	ds_read_b128 v[148:151], v129 offset:30656
	v_pk_mul_f32 v[36:37], v[82:83], v[38:39] op_sel_hi:[1,0]
	v_mul_f32_e32 v206, v113, v38
	s_waitcnt lgkmcnt(1)
	v_mfma_f32_16x16x32_f16 v[32:35], v[130:133], v[32:35], v[134:137]
	v_mov_b32_e32 v113, v169
	v_mfma_f32_16x16x32_f16 v[30:33], v[88:91], v[28:31], v[32:35]
	v_cvt_pk_f16_f32 v29, v186, v188
	v_cvt_pk_f16_f32 v28, v182, v184
	s_waitcnt lgkmcnt(0)
	v_mfma_f32_16x16x32_f16 v[152:155], v[148:151], v[24:27], v[30:33]
	v_mul_f32_e32 v24, 0x3db504f3, v144
	v_mul_f32_e32 v25, 0x3db504f3, v145
	v_max3_f32 v24, v24, s11, v25
	v_mul_f32_e32 v25, 0x3db504f3, v146
	v_mul_f32_e32 v26, 0x3db504f3, v147
	v_max3_f32 v24, v24, v25, v26
	v_mul_f32_e32 v25, 0x3db504f3, v96
	v_mul_f32_e32 v26, 0x3db504f3, v97
	v_max3_f32 v24, v24, v25, v26
	v_mul_f32_e32 v25, 0x3db504f3, v98
	v_mul_f32_e32 v26, 0x3db504f3, v99
	v_max3_f32 v24, v24, v25, v26
	v_mul_f32_e32 v25, 0x3db504f3, v100
	v_mul_f32_e32 v26, 0x3db504f3, v101
	v_max3_f32 v24, v24, v25, v26
	v_mul_f32_e32 v25, 0x3db504f3, v102
	v_mul_f32_e32 v26, 0x3db504f3, v103
	v_max3_f32 v24, v24, v25, v26
	v_mul_f32_e32 v25, 0x3db504f3, v152
	v_mul_f32_e32 v26, 0x3db504f3, v153
	v_max3_f32 v24, v24, v25, v26
	v_mul_f32_e32 v25, 0x3db504f3, v154
	v_mul_f32_e32 v26, 0x3db504f3, v155
	v_max3_f32 v24, v24, v25, v26
	ds_bpermute_b32 v25, v173, v24
	v_pk_mul_f32 v[34:35], v[80:81], v[38:39] op_sel_hi:[1,0]
	v_cvt_pk_f16_f32 v27, v178, v180
	v_cvt_pk_f16_f32 v26, v115, v128
	v_cvt_pk_f16_f32 v33, v202, v204
	s_waitcnt lgkmcnt(0)
	v_max_f32_e32 v25, v25, v25
	v_max_f32_e32 v24, v24, v25
	ds_bpermute_b32 v25, v225, v24
	v_mfma_f32_16x16x32_f16 v[34:37], v[104:107], v[26:29], v[34:37]
	v_cvt_pk_f16_f32 v32, v198, v200
	v_cvt_pk_f16_f32 v31, v192, v196
	v_cvt_pk_f16_f32 v30, v190, v194
	s_waitcnt lgkmcnt(0)
	v_max3_f32 v39, v114, v24, v25
	v_sub_f32_e32 v24, v114, v39
	v_mul_f32_e32 v224, 0x3fb8aa3b, v24
	v_fma_f32 v24, v144, s9, -v39
	v_mul_f32_e32 v24, 0x3fb8aa3b, v24
	v_exp_f32_e32 v179, v24
	v_fma_f32 v24, v145, s9, -v39
	v_mul_f32_e32 v24, 0x3fb8aa3b, v24
	v_exp_f32_e32 v181, v24
	v_fma_f32 v24, v146, s9, -v39
	v_mul_f32_e32 v24, 0x3fb8aa3b, v24
	v_exp_f32_e32 v183, v24
	v_fma_f32 v24, v147, s9, -v39
	v_mul_f32_e32 v24, 0x3fb8aa3b, v24
	v_mfma_f32_16x16x32_f16 v[156:159], v[120:123], v[30:33], v[34:37]
	v_exp_f32_e32 v185, v24
	v_pk_add_f32 v[24:25], v[178:179], v[112:113]
	ds_read2_b64 v[210:213], v140 offset1:4
	ds_read2_b64 v[160:163], v141 offset0:32 offset1:36
	ds_read2_b64 v[144:147], v142 offset0:64 offset1:68
	ds_read2_b64 v[136:139], v143 offset0:96 offset1:100
	ds_read2_b64 v[128:131], v187 offset0:128 offset1:132
	ds_read2_b64 v[112:115], v189 offset0:160 offset1:164
	ds_read2_b64 v[88:91], v191 offset0:192 offset1:196
	ds_read2_b64 v[34:37], v193 offset0:224 offset1:228
	ds_read2_b64 v[226:229], v140 offset0:8 offset1:12
	ds_read2_b64 v[164:167], v141 offset0:40 offset1:44
	ds_read2_b64 v[148:151], v142 offset0:72 offset1:76
	ds_read2_b64 v[140:143], v143 offset0:104 offset1:108
	ds_read2_b64 v[132:135], v187 offset0:136 offset1:140
	ds_read2_b64 v[120:123], v189 offset0:168 offset1:172
	ds_read2_b64 v[104:107], v191 offset0:200 offset1:204
	ds_read2_b64 v[80:83], v193 offset0:232 offset1:236
	s_waitcnt lgkmcnt(0)
	s_barrier
	global_load_dwordx2 v[222:223], v[222:223], off offset:3104
	v_fma_f32 v96, v96, s9, -v39
	v_mul_f32_e32 v96, 0x3fb8aa3b, v96
	v_exp_f32_e32 v187, v96
	v_fma_f32 v96, v97, s9, -v39
	v_mul_f32_e32 v96, 0x3fb8aa3b, v96
	v_exp_f32_e32 v189, v96
	v_fma_f32 v96, v98, s9, -v39
	v_mul_f32_e32 v96, 0x3fb8aa3b, v96
	v_exp_f32_e32 v191, v96
	v_fma_f32 v96, v99, s9, -v39
	v_mul_f32_e32 v96, 0x3fb8aa3b, v96
	v_exp_f32_e32 v195, v96
	v_fma_f32 v96, v100, s9, -v39
	v_mul_f32_e32 v96, 0x3fb8aa3b, v96
	v_exp_f32_e32 v193, v96
	v_fma_f32 v96, v101, s9, -v39
	v_mul_f32_e32 v96, 0x3fb8aa3b, v96
	v_exp_f32_e32 v197, v96
	v_fma_f32 v96, v102, s9, -v39
	v_pk_add_f32 v[24:25], v[180:181], v[24:25]
	v_mul_f32_e32 v96, 0x3fb8aa3b, v96
	v_pk_add_f32 v[24:25], v[182:183], v[24:25]
	v_exp_f32_e32 v199, v96
	v_fma_f32 v96, v103, s9, -v39
	v_pk_add_f32 v[24:25], v[184:185], v[24:25]
	v_mul_f32_e32 v96, 0x3fb8aa3b, v96
	v_exp_f32_e32 v201, v96
	v_fma_f32 v96, v152, s9, -v39
	v_pk_add_f32 v[24:25], v[186:187], v[24:25]
	v_mul_f32_e32 v96, 0x3fb8aa3b, v96
	v_pk_add_f32 v[24:25], v[188:189], v[24:25]
	v_exp_f32_e32 v203, v96
	v_fma_f32 v96, v153, s9, -v39
	v_pk_add_f32 v[24:25], v[190:191], v[24:25]
	v_mul_f32_e32 v96, 0x3fb8aa3b, v96
	v_pk_add_f32 v[24:25], v[194:195], v[24:25]
	v_exp_f32_e32 v205, v96
	v_fma_f32 v96, v154, s9, -v39
	v_pk_add_f32 v[24:25], v[192:193], v[24:25]
	v_mul_f32_e32 v96, 0x3fb8aa3b, v96
	v_fma_f32 v39, v155, s9, -v39
	v_pk_add_f32 v[24:25], v[196:197], v[24:25]
	v_exp_f32_e32 v207, v96
	v_mul_f32_e32 v39, 0x3fb8aa3b, v39
	v_pk_add_f32 v[24:25], v[198:199], v[24:25]
	v_exp_f32_e32 v39, v39
	v_pk_add_f32 v[24:25], v[200:201], v[24:25]
	v_exp_f32_e32 v152, v224
	v_pk_add_f32 v[24:25], v[202:203], v[24:25]
	v_cvt_pk_f16_f32 v99, v191, v195
	v_pk_add_f32 v[24:25], v[204:205], v[24:25]
	v_pk_mul_f32 v[102:103], v[158:159], v[152:153] op_sel_hi:[1,0]
	v_pk_add_f32 v[24:25], v[206:207], v[24:25]
	v_pk_mul_f32 v[100:101], v[156:157], v[152:153] op_sel_hi:[1,0]
	v_add_f32_e32 v25, v25, v39
	v_fmac_f32_e32 v25, v24, v152
	ds_bpermute_b32 v24, v173, v25
	v_cvt_pk_f16_f32 v98, v187, v189
	v_cvt_pk_f16_f32 v97, v183, v185
	v_cvt_pk_f16_f32 v96, v179, v181
	s_waitcnt lgkmcnt(0)
	v_add_f32_e32 v24, v25, v24
	ds_bpermute_b32 v25, v225, v24
	v_mfma_f32_16x16x32_f16 v[154:157], v[210:213], v[96:99], v[100:103]
	s_waitcnt lgkmcnt(0)
	v_add_f32_e32 v24, v24, v25
	v_div_scale_f32 v25, s[4:5], v24, v24, 1.0
	v_cvt_pk_f16_f32 v103, v207, v39
	v_rcp_f32_e32 v39, v25
	v_cvt_pk_f16_f32 v102, v203, v205
	v_cvt_pk_f16_f32 v101, v199, v201
	v_cvt_pk_f16_f32 v100, v193, v197
	v_fma_f32 v153, -v25, v39, 1.0
	v_fmac_f32_e32 v39, v153, v39
	v_div_scale_f32 v153, vcc, 1.0, v24, 1.0
	v_mfma_f32_16x16x32_f16 v[156:159], v[226:229], v[100:103], v[154:157]
	s_waitcnt vmcnt(0)
	v_cvt_f32_f16_sdwa v173, v222 dst_sel:DWORD dst_unused:UNUSED_PAD src0_sel:WORD_1
	v_cvt_f32_f16_e32 v183, v223
	v_mul_f32_e32 v154, v153, v39
	v_fma_f32 v155, -v25, v154, v153
	v_fmac_f32_e32 v154, v155, v39
	v_fma_f32 v25, -v25, v154, v153
	v_cvt_f32_f16_e32 v153, v222
	v_div_fmas_f32 v25, v25, v39, v154
	v_div_fixup_f32 v24, v25, v24, 1.0
	v_mul_f32_e32 v39, 0xbfb8aa3b, v153
	v_exp_f32_e32 v154, v39
	v_mul_f32_e32 v39, 0xbfb8aa3b, v173
	v_exp_f32_e32 v155, v39
	s_nop 0
	v_pk_add_f32 v[178:179], v[154:155], 1.0 op_sel_hi:[1,0]
	s_nop 0
	v_div_scale_f32 v25, s[4:5], v179, v179, v173
	v_rcp_f32_e32 v39, v25
	s_mov_b64 s[4:5], 0x2c20
	v_lshl_add_u64 v[154:155], v[176:177], 0, s[4:5]
	v_pk_mul_f32 v[156:157], v[156:157], v[24:25] op_sel_hi:[1,0]
	v_fma_f32 v176, -v25, v39, 1.0
	v_fmac_f32_e32 v39, v176, v39
	v_div_scale_f32 v176, vcc, v173, v179, v173
	v_mul_f32_e32 v177, v176, v39
	v_fma_f32 v180, -v25, v177, v176
	v_fmac_f32_e32 v177, v180, v39
	v_fma_f32 v25, -v25, v177, v176
	v_div_scale_f32 v176, s[4:5], v178, v178, v153
	v_rcp_f32_e32 v182, v176
	v_div_fmas_f32 v25, v25, v39, v177
	v_div_fixup_f32 v177, v25, v179, v173
	v_fma_f32 v25, -v176, v182, 1.0
	v_fmac_f32_e32 v182, v25, v182
	v_div_scale_f32 v25, vcc, v153, v178, v153
	v_mul_f32_e32 v39, v25, v182
	v_fma_f32 v173, -v176, v39, v25
	v_fmac_f32_e32 v39, v173, v182
	v_cvt_f32_f16_sdwa v173, v223 dst_sel:DWORD dst_unused:UNUSED_PAD src0_sel:WORD_1
	v_fma_f32 v25, -v176, v39, v25
	v_mul_f32_e32 v176, 0xbfb8aa3b, v183
	v_exp_f32_e32 v180, v176
	v_mul_f32_e32 v176, 0xbfb8aa3b, v173
	v_exp_f32_e32 v181, v176
	v_div_fmas_f32 v25, v25, v182, v39
	v_div_fixup_f32 v176, v25, v178, v153
	v_pk_mul_f32 v[156:157], v[156:157], v[176:177]
	v_pk_add_f32 v[178:179], v[180:181], 1.0 op_sel_hi:[1,0]
	v_cvt_pk_f16_f32 v156, v156, v157
	v_div_scale_f32 v25, s[4:5], v179, v179, v173
	v_rcp_f32_e32 v39, v25
	v_pk_mul_f32 v[158:159], v[158:159], v[24:25] op_sel_hi:[1,0]
	v_fma_f32 v153, -v25, v39, 1.0
	v_fmac_f32_e32 v39, v153, v39
	v_div_scale_f32 v153, vcc, v173, v179, v173
	v_mul_f32_e32 v157, v153, v39
	v_fma_f32 v176, -v25, v157, v153
	v_fmac_f32_e32 v157, v176, v39
	v_fma_f32 v25, -v25, v157, v153
	v_div_scale_f32 v153, s[4:5], v178, v178, v183
	v_rcp_f32_e32 v176, v153
	v_div_fmas_f32 v25, v25, v39, v157
	v_div_fixup_f32 v177, v25, v179, v173
	v_fma_f32 v25, -v153, v176, 1.0
	v_fmac_f32_e32 v176, v25, v176
	v_div_scale_f32 v25, vcc, v183, v178, v183
	v_mul_f32_e32 v39, v25, v176
	v_fma_f32 v157, -v153, v39, v25
	v_fmac_f32_e32 v39, v157, v176
	v_fma_f32 v25, -v153, v39, v25
	v_div_fmas_f32 v25, v25, v176, v39
	v_div_fixup_f32 v176, v25, v178, v183
	v_pk_mul_f32 v[158:159], v[158:159], v[176:177]
	v_pk_mul_f32 v[70:71], v[70:71], v[38:39] op_sel_hi:[1,0]
	v_cvt_pk_f16_f32 v157, v158, v159
	v_lshl_add_u64 v[158:159], v[174:175], 0, v[168:169]
	v_add_co_u32_e32 v174, vcc, s0, v158
	v_pk_mul_f32 v[68:69], v[68:69], v[38:39] op_sel_hi:[1,0]
	s_nop 0
	v_addc_co_u32_e32 v175, vcc, 0, v159, vcc
	global_load_dwordx2 v[176:177], v[154:155], off offset:32
	global_load_dwordx2 v[178:179], v[154:155], off offset:64
	global_load_dwordx2 v[180:181], v[154:155], off offset:96
	global_load_dwordx2 v[182:183], v[154:155], off offset:128
	global_load_dwordx2 v[184:185], v[154:155], off offset:160
	global_load_dwordx2 v[186:187], v[154:155], off offset:192
	global_load_dwordx2 v[188:189], v[154:155], off offset:224
	global_store_dwordx2 v[174:175], v[156:157], off offset:768
	v_mfma_f32_16x16x32_f16 v[68:71], v[116:119], v[26:29], v[68:71]
	s_waitcnt vmcnt(7)
	v_cvt_f32_f16_e32 v25, v176
	v_cvt_f32_f16_sdwa v39, v176 dst_sel:DWORD dst_unused:UNUSED_PAD src0_sel:WORD_1
	v_mfma_f32_16x16x32_f16 v[68:71], v[124:127], v[30:33], v[68:71]
	v_cvt_f32_f16_e32 v156, v177
	v_mul_f32_e32 v116, 0xbfb8aa3b, v25
	v_mul_f32_e32 v117, 0xbfb8aa3b, v39
	v_exp_f32_e32 v116, v116
	v_exp_f32_e32 v117, v117
	s_nop 2
	v_pk_mul_f32 v[70:71], v[70:71], v[152:153] op_sel_hi:[1,0]
	v_pk_mul_f32 v[68:69], v[68:69], v[152:153] op_sel_hi:[1,0]
	v_cvt_f32_f16_sdwa v157, v177 dst_sel:DWORD dst_unused:UNUSED_PAD src0_sel:WORD_1
	v_pk_add_f32 v[124:125], v[116:117], 1.0 op_sel_hi:[1,0]
	v_mfma_f32_16x16x32_f16 v[68:71], v[160:163], v[96:99], v[68:71]
	v_div_scale_f32 v126, s[4:5], v125, v125, v39
	v_rcp_f32_e32 v127, v126
	v_mfma_f32_16x16x32_f16 v[116:119], v[164:167], v[100:103], v[68:71]
	s_mov_b64 s[4:5], 0x4800300
	s_nop 3
	v_lshl_add_u64 v[68:69], v[158:159], 0, s[4:5]
	s_nop 1
	v_pk_mul_f32 v[70:71], v[116:117], v[24:25] op_sel_hi:[1,0]
	v_fma_f32 v116, -v126, v127, 1.0
	v_fmac_f32_e32 v127, v116, v127
	v_div_scale_f32 v116, vcc, v39, v125, v39
	v_mul_f32_e32 v117, v116, v127
	v_fma_f32 v153, -v126, v117, v116
	v_fmac_f32_e32 v117, v153, v127
	v_fma_f32 v116, -v126, v117, v116
	v_div_scale_f32 v126, s[4:5], v124, v124, v25
	v_rcp_f32_e32 v153, v126
	v_div_fmas_f32 v116, v116, v127, v117
	v_div_fixup_f32 v117, v116, v125, v39
	v_fma_f32 v39, -v126, v153, 1.0
	v_fmac_f32_e32 v153, v39, v153
	v_div_scale_f32 v39, vcc, v25, v124, v25
	v_mul_f32_e32 v116, v39, v153
	v_fma_f32 v125, -v126, v116, v39
	v_fmac_f32_e32 v116, v125, v153
	v_mul_f32_e32 v125, 0xbfb8aa3b, v156
	v_fma_f32 v39, -v126, v116, v39
	v_exp_f32_e32 v126, v125
	v_mul_f32_e32 v125, 0xbfb8aa3b, v157
	v_exp_f32_e32 v127, v125
	v_div_fmas_f32 v39, v39, v153, v116
	v_div_fixup_f32 v116, v39, v124, v25
	v_pk_mul_f32 v[70:71], v[70:71], v[116:117]
	v_pk_add_f32 v[124:125], v[126:127], 1.0 op_sel_hi:[1,0]
	v_cvt_pk_f16_f32 v70, v70, v71
	v_div_scale_f32 v25, s[4:5], v125, v125, v157
	v_rcp_f32_e32 v39, v25
	v_pk_mul_f32 v[116:117], v[118:119], v[24:25] op_sel_hi:[1,0]
	v_fma_f32 v71, -v25, v39, 1.0
	v_fmac_f32_e32 v39, v71, v39
	v_div_scale_f32 v71, vcc, v157, v125, v157
	v_mul_f32_e32 v118, v71, v39
	v_fma_f32 v119, -v25, v118, v71
	v_fmac_f32_e32 v118, v119, v39
	v_fma_f32 v25, -v25, v118, v71
	v_div_scale_f32 v71, s[4:5], v124, v124, v156
	v_rcp_f32_e32 v126, v71
	v_div_fmas_f32 v25, v25, v39, v118
	v_div_fixup_f32 v119, v25, v125, v157
	v_fma_f32 v25, -v71, v126, 1.0
	v_fmac_f32_e32 v126, v25, v126
	v_div_scale_f32 v25, vcc, v156, v124, v156
	v_mul_f32_e32 v39, v25, v126
	v_fma_f32 v118, -v71, v39, v25
	v_fmac_f32_e32 v39, v118, v126
	v_fma_f32 v25, -v71, v39, v25
	v_div_fmas_f32 v25, v25, v126, v39
	v_div_fixup_f32 v118, v25, v124, v156
	v_pk_mul_f32 v[116:117], v[116:117], v[118:119]
	v_pk_mul_f32 v[58:59], v[58:59], v[38:39] op_sel_hi:[1,0]
	v_cvt_pk_f16_f32 v71, v116, v117
	global_store_dwordx2 v[68:69], v[70:71], off offset:32
	v_pk_mul_f32 v[56:57], v[56:57], v[38:39] op_sel_hi:[1,0]
	s_waitcnt vmcnt(7)
	v_cvt_f32_f16_e32 v25, v178
	v_cvt_f32_f16_sdwa v39, v178 dst_sel:DWORD dst_unused:UNUSED_PAD src0_sel:WORD_1
	v_mfma_f32_16x16x32_f16 v[56:59], v[92:95], v[26:29], v[56:59]
	v_mul_f32_e32 v70, 0xbfb8aa3b, v25
	v_exp_f32_e32 v92, v70
	v_mul_f32_e32 v70, 0xbfb8aa3b, v39
	v_exp_f32_e32 v93, v70
	v_mfma_f32_16x16x32_f16 v[56:59], v[108:111], v[30:33], v[56:59]
	v_cvt_f32_f16_sdwa v110, v179 dst_sel:DWORD dst_unused:UNUSED_PAD src0_sel:WORD_1
	v_pk_add_f32 v[92:93], v[92:93], 1.0 op_sel_hi:[1,0]
	s_nop 0
	v_div_scale_f32 v70, s[4:5], v93, v93, v39
	v_rcp_f32_e32 v94, v70
	s_nop 2
	v_pk_mul_f32 v[58:59], v[58:59], v[152:153] op_sel_hi:[1,0]
	v_pk_mul_f32 v[56:57], v[56:57], v[152:153] op_sel_hi:[1,0]
	v_fma_f32 v95, -v70, v94, 1.0
	v_fmac_f32_e32 v94, v95, v94
	v_div_scale_f32 v95, vcc, v39, v93, v39
	v_mul_f32_e32 v108, v95, v94
	v_fma_f32 v109, -v70, v108, v95
	v_fmac_f32_e32 v108, v109, v94
	v_fma_f32 v70, -v70, v108, v95
	v_div_scale_f32 v95, s[4:5], v92, v92, v25
	v_rcp_f32_e32 v109, v95
	v_div_fmas_f32 v70, v70, v94, v108
	v_div_fixup_f32 v93, v70, v93, v39
	v_cvt_f32_f16_e32 v108, v179
	v_fma_f32 v39, -v95, v109, 1.0
	v_fmac_f32_e32 v109, v39, v109
	v_div_scale_f32 v39, vcc, v25, v92, v25
	v_mfma_f32_16x16x32_f16 v[56:59], v[144:147], v[96:99], v[56:59]
	v_mul_f32_e32 v94, v39, v109
	v_fma_f32 v70, -v95, v94, v39
	v_fmac_f32_e32 v94, v70, v109
	v_mul_f32_e32 v70, 0xbfb8aa3b, v108
	v_mul_f32_e32 v71, 0xbfb8aa3b, v110
	v_exp_f32_e32 v70, v70
	v_exp_f32_e32 v71, v71
	v_mfma_f32_16x16x32_f16 v[56:59], v[148:151], v[100:103], v[56:59]
	v_fma_f32 v39, -v95, v94, v39
	v_div_fmas_f32 v39, v39, v109, v94
	v_pk_add_f32 v[70:71], v[70:71], 1.0 op_sel_hi:[1,0]
	v_div_fixup_f32 v92, v39, v92, v25
	s_nop 3
	v_pk_mul_f32 v[56:57], v[56:57], v[24:25] op_sel_hi:[1,0]
	v_div_scale_f32 v25, s[4:5], v71, v71, v110
	v_rcp_f32_e32 v39, v25
	v_pk_mul_f32 v[56:57], v[56:57], v[92:93]
	v_pk_mul_f32 v[58:59], v[58:59], v[24:25] op_sel_hi:[1,0]
	v_cvt_pk_f16_f32 v56, v56, v57
	v_fma_f32 v57, -v25, v39, 1.0
	v_fmac_f32_e32 v39, v57, v39
	v_div_scale_f32 v57, vcc, v110, v71, v110
	v_mul_f32_e32 v92, v57, v39
	v_fma_f32 v93, -v25, v92, v57
	v_fmac_f32_e32 v92, v93, v39
	v_fma_f32 v25, -v25, v92, v57
	v_div_scale_f32 v57, s[4:5], v70, v70, v108
	v_rcp_f32_e32 v93, v57
	v_div_fmas_f32 v25, v25, v39, v92
	v_div_fixup_f32 v71, v25, v71, v110
	v_fma_f32 v25, -v57, v93, 1.0
	v_fmac_f32_e32 v93, v25, v93
	v_div_scale_f32 v25, vcc, v108, v70, v108
	v_mul_f32_e32 v39, v25, v93
	v_fma_f32 v92, -v57, v39, v25
	v_fmac_f32_e32 v39, v92, v93
	v_fma_f32 v25, -v57, v39, v25
	v_div_fmas_f32 v25, v25, v93, v39
	v_div_fixup_f32 v70, v25, v70, v108
	v_pk_mul_f32 v[58:59], v[58:59], v[70:71]
	v_pk_mul_f32 v[46:47], v[46:47], v[38:39] op_sel_hi:[1,0]
	v_cvt_pk_f16_f32 v57, v58, v59
	global_store_dwordx2 v[68:69], v[56:57], off offset:64
	v_pk_mul_f32 v[44:45], v[44:45], v[38:39] op_sel_hi:[1,0]
	s_waitcnt vmcnt(7)
	v_cvt_f32_f16_e32 v25, v180
	v_cvt_f32_f16_sdwa v39, v180 dst_sel:DWORD dst_unused:UNUSED_PAD src0_sel:WORD_1
	v_mfma_f32_16x16x32_f16 v[44:47], v[76:79], v[26:29], v[44:47]
	v_cvt_f32_f16_sdwa v78, v181 dst_sel:DWORD dst_unused:UNUSED_PAD src0_sel:WORD_1
	v_mul_f32_e32 v56, 0xbfb8aa3b, v25
	v_exp_f32_e32 v58, v56
	v_mul_f32_e32 v56, 0xbfb8aa3b, v39
	v_exp_f32_e32 v59, v56
	v_mfma_f32_16x16x32_f16 v[44:47], v[84:87], v[30:33], v[44:47]
	v_add_f32_e64 v58, v58, 1.0
	v_add_f32_e64 v59, v59, 1.0
	v_div_scale_f32 v56, s[4:5], v59, v59, v39
	v_rcp_f32_e32 v70, v56
	s_nop 3
	v_pk_mul_f32 v[46:47], v[46:47], v[152:153] op_sel_hi:[1,0]
	v_pk_mul_f32 v[44:45], v[44:45], v[152:153] op_sel_hi:[1,0]
	v_fma_f32 v71, -v56, v70, 1.0
	v_fmac_f32_e32 v70, v71, v70
	v_div_scale_f32 v71, vcc, v39, v59, v39
	v_mul_f32_e32 v76, v71, v70
	v_fma_f32 v77, -v56, v76, v71
	v_fmac_f32_e32 v76, v77, v70
	v_fma_f32 v56, -v56, v76, v71
	v_div_scale_f32 v71, s[4:5], v58, v58, v25
	v_rcp_f32_e32 v77, v71
	v_div_fmas_f32 v56, v56, v70, v76
	v_div_fixup_f32 v59, v56, v59, v39
	v_cvt_f32_f16_e32 v76, v181
	v_fma_f32 v39, -v71, v77, 1.0
	v_fmac_f32_e32 v77, v39, v77
	v_div_scale_f32 v39, vcc, v25, v58, v25
	v_mfma_f32_16x16x32_f16 v[44:47], v[136:139], v[96:99], v[44:47]
	v_mul_f32_e32 v70, v39, v77
	v_fma_f32 v56, -v71, v70, v39
	v_fmac_f32_e32 v70, v56, v77
	v_mul_f32_e32 v56, 0xbfb8aa3b, v76
	v_mul_f32_e32 v57, 0xbfb8aa3b, v78
	v_exp_f32_e32 v56, v56
	v_exp_f32_e32 v57, v57
	v_mfma_f32_16x16x32_f16 v[44:47], v[140:143], v[100:103], v[44:47]
	v_fma_f32 v39, -v71, v70, v39
	v_div_fmas_f32 v39, v39, v77, v70
	v_pk_add_f32 v[56:57], v[56:57], 1.0 op_sel_hi:[1,0]
	v_div_fixup_f32 v58, v39, v58, v25
	s_nop 3
	v_pk_mul_f32 v[44:45], v[44:45], v[24:25] op_sel_hi:[1,0]
	v_div_scale_f32 v25, s[4:5], v57, v57, v78
	v_rcp_f32_e32 v39, v25
	v_pk_mul_f32 v[44:45], v[44:45], v[58:59]
	v_pk_mul_f32 v[46:47], v[46:47], v[24:25] op_sel_hi:[1,0]
	v_cvt_pk_f16_f32 v44, v44, v45
	v_fma_f32 v45, -v25, v39, 1.0
	v_fmac_f32_e32 v39, v45, v39
	v_div_scale_f32 v45, vcc, v78, v57, v78
	v_mul_f32_e32 v58, v45, v39
	v_fma_f32 v59, -v25, v58, v45
	v_fmac_f32_e32 v58, v59, v39
	v_fma_f32 v25, -v25, v58, v45
	v_div_scale_f32 v45, s[4:5], v56, v56, v76
	v_rcp_f32_e32 v59, v45
	v_div_fmas_f32 v25, v25, v39, v58
	v_div_fixup_f32 v57, v25, v57, v78
	v_fma_f32 v25, -v45, v59, 1.0
	v_fmac_f32_e32 v59, v25, v59
	v_div_scale_f32 v25, vcc, v76, v56, v76
	v_mul_f32_e32 v39, v25, v59
	v_fma_f32 v58, -v45, v39, v25
	v_fmac_f32_e32 v39, v58, v59
	v_fma_f32 v25, -v45, v39, v25
	v_div_fmas_f32 v25, v25, v59, v39
	v_div_fixup_f32 v56, v25, v56, v76
	v_pk_mul_f32 v[46:47], v[46:47], v[56:57]
	v_pk_mul_f32 v[18:19], v[18:19], v[38:39] op_sel_hi:[1,0]
	v_cvt_pk_f16_f32 v45, v46, v47
	global_store_dwordx2 v[68:69], v[44:45], off offset:96
	v_pk_mul_f32 v[16:17], v[16:17], v[38:39] op_sel_hi:[1,0]
	s_waitcnt vmcnt(7)
	v_cvt_f32_f16_e32 v25, v182
	v_cvt_f32_f16_sdwa v39, v182 dst_sel:DWORD dst_unused:UNUSED_PAD src0_sel:WORD_1
	v_mfma_f32_16x16x32_f16 v[16:19], v[64:67], v[26:29], v[16:19]
	v_cvt_f32_f16_sdwa v64, v183 dst_sel:DWORD dst_unused:UNUSED_PAD src0_sel:WORD_1
	v_mul_f32_e32 v44, 0xbfb8aa3b, v25
	v_exp_f32_e32 v46, v44
	v_mul_f32_e32 v44, 0xbfb8aa3b, v39
	v_exp_f32_e32 v47, v44
	v_mfma_f32_16x16x32_f16 v[16:19], v[72:75], v[30:33], v[16:19]
	v_add_f32_e64 v46, v46, 1.0
	v_add_f32_e64 v47, v47, 1.0
	v_div_scale_f32 v44, s[4:5], v47, v47, v39
	v_rcp_f32_e32 v56, v44
	s_nop 3
	v_pk_mul_f32 v[18:19], v[18:19], v[152:153] op_sel_hi:[1,0]
	v_pk_mul_f32 v[16:17], v[16:17], v[152:153] op_sel_hi:[1,0]
	v_fma_f32 v57, -v44, v56, 1.0
	v_fmac_f32_e32 v56, v57, v56
	v_div_scale_f32 v57, vcc, v39, v47, v39
	v_mul_f32_e32 v58, v57, v56
	v_fma_f32 v59, -v44, v58, v57
	v_fmac_f32_e32 v58, v59, v56
	v_fma_f32 v44, -v44, v58, v57
	v_div_scale_f32 v57, s[4:5], v46, v46, v25
	v_rcp_f32_e32 v59, v57
	v_div_fmas_f32 v44, v44, v56, v58
	v_div_fixup_f32 v47, v44, v47, v39
	v_cvt_f32_f16_e32 v58, v183
	v_fma_f32 v39, -v57, v59, 1.0
	v_fmac_f32_e32 v59, v39, v59
	v_div_scale_f32 v39, vcc, v25, v46, v25
	v_mfma_f32_16x16x32_f16 v[16:19], v[128:131], v[96:99], v[16:19]
	v_mul_f32_e32 v56, v39, v59
	v_fma_f32 v44, -v57, v56, v39
	v_fmac_f32_e32 v56, v44, v59
	v_mul_f32_e32 v44, 0xbfb8aa3b, v58
	v_mul_f32_e32 v45, 0xbfb8aa3b, v64
	v_exp_f32_e32 v44, v44
	v_exp_f32_e32 v45, v45
	v_mfma_f32_16x16x32_f16 v[16:19], v[132:135], v[100:103], v[16:19]
	v_fma_f32 v39, -v57, v56, v39
	v_div_fmas_f32 v39, v39, v59, v56
	v_pk_add_f32 v[44:45], v[44:45], 1.0 op_sel_hi:[1,0]
	v_div_fixup_f32 v46, v39, v46, v25
	s_nop 3
	v_pk_mul_f32 v[16:17], v[16:17], v[24:25] op_sel_hi:[1,0]
	v_div_scale_f32 v25, s[4:5], v45, v45, v64
	v_rcp_f32_e32 v39, v25
	v_pk_mul_f32 v[16:17], v[16:17], v[46:47]
	v_pk_mul_f32 v[18:19], v[18:19], v[24:25] op_sel_hi:[1,0]
	v_cvt_pk_f16_f32 v16, v16, v17
	v_fma_f32 v17, -v25, v39, 1.0
	v_fmac_f32_e32 v39, v17, v39
	v_div_scale_f32 v17, vcc, v64, v45, v64
	v_mul_f32_e32 v46, v17, v39
	v_fma_f32 v47, -v25, v46, v17
	v_fmac_f32_e32 v46, v47, v39
	v_fma_f32 v17, -v25, v46, v17
	v_div_scale_f32 v25, s[4:5], v44, v44, v58
	v_rcp_f32_e32 v47, v25
	v_div_fmas_f32 v17, v17, v39, v46
	v_div_fixup_f32 v45, v17, v45, v64
	v_fma_f32 v17, -v25, v47, 1.0
	v_fmac_f32_e32 v47, v17, v47
	v_div_scale_f32 v17, vcc, v58, v44, v58
	v_mul_f32_e32 v39, v17, v47
	v_fma_f32 v46, -v25, v39, v17
	v_fmac_f32_e32 v39, v46, v47
	v_fma_f32 v17, -v25, v39, v17
	v_div_fmas_f32 v17, v17, v47, v39
	v_div_fixup_f32 v44, v17, v44, v58
	v_pk_mul_f32 v[18:19], v[18:19], v[44:45]
	v_pk_mul_f32 v[10:11], v[10:11], v[38:39] op_sel_hi:[1,0]
	v_cvt_pk_f16_f32 v17, v18, v19
	global_store_dwordx2 v[68:69], v[16:17], off offset:128
	v_pk_mul_f32 v[8:9], v[8:9], v[38:39] op_sel_hi:[1,0]
	s_waitcnt vmcnt(7)
	v_cvt_f32_f16_e32 v25, v184
	v_cvt_f32_f16_sdwa v16, v184 dst_sel:DWORD dst_unused:UNUSED_PAD src0_sel:WORD_1
	v_mfma_f32_16x16x32_f16 v[8:11], v[52:55], v[26:29], v[8:11]
	v_mul_f32_e32 v18, 0xbfb8aa3b, v25
	v_mul_f32_e32 v19, 0xbfb8aa3b, v16
	v_exp_f32_e32 v18, v18
	v_exp_f32_e32 v19, v19
	v_mfma_f32_16x16x32_f16 v[8:11], v[60:63], v[30:33], v[8:11]
	v_add_f32_e64 v18, v18, 1.0
	v_add_f32_e64 v19, v19, 1.0
	v_div_scale_f32 v39, s[4:5], v19, v19, v16
	v_rcp_f32_e32 v44, v39
	s_nop 3
	v_pk_mul_f32 v[10:11], v[10:11], v[152:153] op_sel_hi:[1,0]
	v_pk_mul_f32 v[8:9], v[8:9], v[152:153] op_sel_hi:[1,0]
	v_fma_f32 v45, -v39, v44, 1.0
	v_fmac_f32_e32 v44, v45, v44
	v_div_scale_f32 v45, vcc, v16, v19, v16
	v_mul_f32_e32 v46, v45, v44
	v_fma_f32 v47, -v39, v46, v45
	v_fmac_f32_e32 v46, v47, v44
	v_fma_f32 v39, -v39, v46, v45
	v_div_scale_f32 v45, s[4:5], v18, v18, v25
	v_rcp_f32_e32 v47, v45
	v_div_fmas_f32 v39, v39, v44, v46
	v_div_fixup_f32 v19, v39, v19, v16
	v_cvt_f32_f16_e32 v46, v185
	v_fma_f32 v16, -v45, v47, 1.0
	v_fmac_f32_e32 v47, v16, v47
	v_div_scale_f32 v16, vcc, v25, v18, v25
	v_mul_f32_e32 v39, v16, v47
	v_fma_f32 v44, -v45, v39, v16
	v_fmac_f32_e32 v39, v44, v47
	v_cvt_f32_f16_sdwa v44, v185 dst_sel:DWORD dst_unused:UNUSED_PAD src0_sel:WORD_1
	v_mfma_f32_16x16x32_f16 v[8:11], v[112:115], v[96:99], v[8:11]
	v_fma_f32 v45, -v45, v39, v16
	v_mul_f32_e32 v16, 0xbfb8aa3b, v46
	v_mul_f32_e32 v17, 0xbfb8aa3b, v44
	v_exp_f32_e32 v16, v16
	v_exp_f32_e32 v17, v17
	v_mfma_f32_16x16x32_f16 v[8:11], v[120:123], v[100:103], v[8:11]
	v_div_fmas_f32 v39, v45, v47, v39
	v_div_fixup_f32 v18, v39, v18, v25
	v_pk_add_f32 v[16:17], v[16:17], 1.0 op_sel_hi:[1,0]
	s_nop 4
	v_pk_mul_f32 v[8:9], v[8:9], v[24:25] op_sel_hi:[1,0]
	v_div_scale_f32 v25, s[4:5], v17, v17, v44
	v_rcp_f32_e32 v39, v25
	v_pk_mul_f32 v[8:9], v[8:9], v[18:19]
	v_pk_mul_f32 v[10:11], v[10:11], v[24:25] op_sel_hi:[1,0]
	v_cvt_pk_f16_f32 v8, v8, v9
	v_fma_f32 v9, -v25, v39, 1.0
	v_fmac_f32_e32 v39, v9, v39
	v_div_scale_f32 v9, vcc, v44, v17, v44
	v_mul_f32_e32 v18, v9, v39
	v_fma_f32 v19, -v25, v18, v9
	v_fmac_f32_e32 v18, v19, v39
	v_div_scale_f32 v19, s[4:5], v16, v16, v46
	v_fma_f32 v9, -v25, v18, v9
	v_rcp_f32_e32 v25, v19
	v_div_fmas_f32 v9, v9, v39, v18
	v_div_fixup_f32 v17, v9, v17, v44
	v_fma_f32 v9, -v19, v25, 1.0
	v_fmac_f32_e32 v25, v9, v25
	v_div_scale_f32 v9, vcc, v46, v16, v46
	v_mul_f32_e32 v18, v9, v25
	v_fma_f32 v39, -v19, v18, v9
	v_fmac_f32_e32 v18, v39, v25
	v_fma_f32 v9, -v19, v18, v9
	v_div_fmas_f32 v9, v9, v25, v18
	v_div_fixup_f32 v16, v9, v16, v46
	v_pk_mul_f32 v[10:11], v[10:11], v[16:17]
	v_pk_mul_f32 v[6:7], v[6:7], v[38:39] op_sel_hi:[1,0]
	v_cvt_pk_f16_f32 v9, v10, v11
	global_store_dwordx2 v[68:69], v[8:9], off offset:160
	v_pk_mul_f32 v[4:5], v[4:5], v[38:39] op_sel_hi:[1,0]
	s_waitcnt vmcnt(7)
	v_cvt_f32_f16_e32 v16, v186
	v_mfma_f32_16x16x32_f16 v[4:7], v[40:43], v[26:29], v[4:7]
	v_cvt_f32_f16_sdwa v8, v186 dst_sel:DWORD dst_unused:UNUSED_PAD src0_sel:WORD_1
	v_mul_f32_e32 v10, 0xbfb8aa3b, v16
	v_mfma_f32_16x16x32_f16 v[4:7], v[48:51], v[30:33], v[4:7]
	v_mul_f32_e32 v11, 0xbfb8aa3b, v8
	v_exp_f32_e32 v10, v10
	v_exp_f32_e32 v11, v11
	s_nop 0
	v_pk_add_f32 v[10:11], v[10:11], 1.0 op_sel_hi:[1,0]
	s_nop 2
	v_pk_mul_f32 v[6:7], v[6:7], v[152:153] op_sel_hi:[1,0]
	v_pk_mul_f32 v[4:5], v[4:5], v[152:153] op_sel_hi:[1,0]
	v_div_scale_f32 v17, s[4:5], v11, v11, v8
	s_nop 0
	v_mfma_f32_16x16x32_f16 v[4:7], v[88:91], v[96:99], v[4:7]
	v_rcp_f32_e32 v18, v17
	s_nop 0
	v_fma_f32 v19, -v17, v18, 1.0
	v_mfma_f32_16x16x32_f16 v[4:7], v[104:107], v[100:103], v[4:7]
	v_fmac_f32_e32 v18, v19, v18
	v_div_scale_f32 v19, vcc, v8, v11, v8
	s_nop 5
	v_pk_mul_f32 v[4:5], v[4:5], v[24:25] op_sel_hi:[1,0]
	v_mul_f32_e32 v25, v19, v18
	v_fma_f32 v39, -v17, v25, v19
	v_fmac_f32_e32 v25, v39, v18
	v_fma_f32 v17, -v17, v25, v19
	v_div_scale_f32 v19, s[4:5], v10, v10, v16
	v_rcp_f32_e32 v39, v19
	v_div_fmas_f32 v17, v17, v18, v25
	v_div_fixup_f32 v11, v17, v11, v8
	v_cvt_f32_f16_e32 v25, v187
	v_fma_f32 v8, -v19, v39, 1.0
	v_fmac_f32_e32 v39, v8, v39
	v_div_scale_f32 v8, vcc, v16, v10, v16
	v_mul_f32_e32 v17, v8, v39
	v_fma_f32 v18, -v19, v17, v8
	v_fmac_f32_e32 v17, v18, v39
	v_cvt_f32_f16_sdwa v18, v187 dst_sel:DWORD dst_unused:UNUSED_PAD src0_sel:WORD_1
	v_fma_f32 v19, -v19, v17, v8
	v_mul_f32_e32 v8, 0xbfb8aa3b, v25
	v_exp_f32_e32 v8, v8
	v_mul_f32_e32 v9, 0xbfb8aa3b, v18
	v_exp_f32_e32 v9, v9
	v_div_fmas_f32 v17, v19, v39, v17
	v_div_fixup_f32 v10, v17, v10, v16
	v_pk_mul_f32 v[4:5], v[4:5], v[10:11]
	v_pk_add_f32 v[8:9], v[8:9], 1.0 op_sel_hi:[1,0]
	v_cvt_pk_f16_f32 v4, v4, v5
	v_div_scale_f32 v16, s[4:5], v9, v9, v18
	v_rcp_f32_e32 v17, v16
	v_pk_mul_f32 v[6:7], v[6:7], v[24:25] op_sel_hi:[1,0]
	v_pk_mul_f32 v[2:3], v[2:3], v[38:39] op_sel_hi:[1,0]
	v_pk_mul_f32 v[0:1], v[0:1], v[38:39] op_sel_hi:[1,0]
	v_fma_f32 v5, -v16, v17, 1.0
	v_fmac_f32_e32 v17, v5, v17
	v_div_scale_f32 v5, vcc, v18, v9, v18
	v_mul_f32_e32 v10, v5, v17
	v_fma_f32 v11, -v16, v10, v5
	v_fmac_f32_e32 v10, v11, v17
	v_div_scale_f32 v11, s[4:5], v8, v8, v25
	v_fma_f32 v5, -v16, v10, v5
	v_rcp_f32_e32 v16, v11
	v_div_fmas_f32 v5, v5, v17, v10
	v_div_fixup_f32 v9, v5, v9, v18
	v_mfma_f32_16x16x32_f16 v[0:3], v[12:15], v[26:29], v[0:3]
	v_fma_f32 v5, -v11, v16, 1.0
	v_fmac_f32_e32 v16, v5, v16
	v_div_scale_f32 v5, vcc, v25, v8, v25
	v_mul_f32_e32 v10, v5, v16
	v_fma_f32 v17, -v11, v10, v5
	v_fmac_f32_e32 v10, v17, v16
	v_fma_f32 v5, -v11, v10, v5
	v_div_fmas_f32 v5, v5, v16, v10
	v_div_fixup_f32 v8, v5, v8, v25
	v_pk_mul_f32 v[6:7], v[6:7], v[8:9]
	v_mfma_f32_16x16x32_f16 v[0:3], v[20:23], v[30:33], v[0:3]
	v_cvt_pk_f16_f32 v5, v6, v7
	global_store_dwordx2 v[68:69], v[4:5], off offset:192
	s_waitcnt vmcnt(7)
	v_cvt_f32_f16_e32 v8, v188
	v_cvt_f32_f16_sdwa v4, v188 dst_sel:DWORD dst_unused:UNUSED_PAD src0_sel:WORD_1
	s_nop 1
	v_pk_mul_f32 v[2:3], v[2:3], v[152:153] op_sel_hi:[1,0]
	v_pk_mul_f32 v[0:1], v[0:1], v[152:153] op_sel_hi:[1,0]
	v_mul_f32_e32 v6, 0xbfb8aa3b, v8
	v_mul_f32_e32 v7, 0xbfb8aa3b, v4
	v_exp_f32_e32 v6, v6
	v_exp_f32_e32 v7, v7
	v_mfma_f32_16x16x32_f16 v[0:3], v[34:37], v[96:99], v[0:3]
	v_add_f32_e64 v6, v6, 1.0
	v_add_f32_e64 v7, v7, 1.0
	v_div_scale_f32 v9, s[4:5], v7, v7, v4
	v_rcp_f32_e32 v10, v9
	v_mfma_f32_16x16x32_f16 v[0:3], v[80:83], v[100:103], v[0:3]
	v_fma_f32 v11, -v9, v10, 1.0
	v_fmac_f32_e32 v10, v11, v10
	v_div_scale_f32 v11, vcc, v4, v7, v4
	v_mul_f32_e32 v12, v11, v10
	v_fma_f32 v13, -v9, v12, v11
	v_fmac_f32_e32 v12, v13, v10
	v_fma_f32 v9, -v9, v12, v11
	v_div_scale_f32 v11, s[4:5], v6, v6, v8
	v_rcp_f32_e32 v13, v11
	v_div_fmas_f32 v9, v9, v10, v12
	v_div_fixup_f32 v7, v9, v7, v4
	v_cvt_f32_f16_e32 v12, v189
	v_fma_f32 v4, -v11, v13, 1.0
	v_fmac_f32_e32 v13, v4, v13
	v_div_scale_f32 v4, vcc, v8, v6, v8
	v_mul_f32_e32 v9, v4, v13
	v_fma_f32 v10, -v11, v9, v4
	v_fmac_f32_e32 v9, v10, v13
	v_cvt_f32_f16_sdwa v10, v189 dst_sel:DWORD dst_unused:UNUSED_PAD src0_sel:WORD_1
	v_fma_f32 v11, -v11, v9, v4
	v_mul_f32_e32 v4, 0xbfb8aa3b, v12
	v_exp_f32_e32 v4, v4
	v_mul_f32_e32 v5, 0xbfb8aa3b, v10
	v_exp_f32_e32 v5, v5
	v_div_fmas_f32 v9, v11, v13, v9
	v_div_fixup_f32 v6, v9, v6, v8
	v_pk_mul_f32 v[0:1], v[0:1], v[24:25] op_sel_hi:[1,0]
	v_pk_add_f32 v[4:5], v[4:5], 1.0 op_sel_hi:[1,0]
	v_pk_mul_f32 v[0:1], v[0:1], v[6:7]
	v_div_scale_f32 v8, s[4:5], v5, v5, v10
	v_rcp_f32_e32 v9, v8
	v_cvt_pk_f16_f32 v0, v0, v1
	v_pk_mul_f32 v[2:3], v[2:3], v[24:25] op_sel_hi:[1,0]
	v_fma_f32 v1, -v8, v9, 1.0
	v_fmac_f32_e32 v9, v1, v9
	v_div_scale_f32 v1, vcc, v10, v5, v10
	v_mul_f32_e32 v6, v1, v9
	v_fma_f32 v7, -v8, v6, v1
	v_fmac_f32_e32 v6, v7, v9
	v_div_scale_f32 v7, s[4:5], v4, v4, v12
	v_fma_f32 v1, -v8, v6, v1
	v_rcp_f32_e32 v8, v7
	v_div_fmas_f32 v1, v1, v9, v6
	v_div_fixup_f32 v5, v1, v5, v10
	v_fma_f32 v1, -v7, v8, 1.0
	v_fmac_f32_e32 v8, v1, v8
	v_div_scale_f32 v1, vcc, v12, v4, v12
	v_mul_f32_e32 v6, v1, v8
	v_fma_f32 v9, -v7, v6, v1
	v_fmac_f32_e32 v6, v9, v8
	v_fma_f32 v1, -v7, v6, v1
	v_div_fmas_f32 v1, v1, v8, v6
	v_div_fixup_f32 v4, v1, v4, v12
	v_pk_mul_f32 v[2:3], v[2:3], v[4:5]
	s_nop 0
	v_cvt_pk_f16_f32 v1, v2, v3
	global_store_dwordx2 v[68:69], v[0:1], off offset:224

.LBB0_153:
	s_andn2_b64 vcc, exec, s[4:5]
	s_cbranch_vccnz .LBB0_155
	s_add_i32 s0, s25, 0xfffffb00
	s_lshr_b32 s0, s0, 4
	s_lshr_b32 s4, s25, 2
	s_bfe_u32 s8, s25, 0x20002
	s_lshl_b32 s9, s0, 8
	s_bfe_u32 s6, s4, 0x10001
	s_mul_i32 s4, s0, 0x302000
	v_readlane_b32 s10, v254, 4
	s_mul_hi_u32 s5, s9, 0x3020
	v_readlane_b32 s11, v254, 5
	s_add_u32 s4, s10, s4
	s_addc_u32 s5, s11, s5
	s_lshl_b32 s7, s6, 8
	s_add_u32 s4, s4, s7
	s_addc_u32 s5, s5, 0
	s_lshl_b32 s0, s0, 1
	s_or_b32 s0, s0, s6
	s_lshl_b64 s[6:7], s[0:1], 16
	v_readlane_b32 s0, v254, 10
	s_add_u32 s6, s0, s6
	v_readlane_b32 s0, v254, 11
	s_addc_u32 s7, s0, s7
	s_lshl_b32 s0, s25, 6
	s_waitcnt vmcnt(0)
	v_mov_b32_e32 v20, v171
	s_and_b32 s0, s0, 0xc0
	s_or_b32 s0, s0, s9
	v_and_b32_e32 v56, 15, v20
	v_ashrrev_i32_e32 v0, 2, v20
	v_and_b32_e32 v0, -16, v0
	v_or_b32_e32 v1, s0, v56
	v_add_u32_e32 v94, v1, v0
	v_mov_b64_e32 v[0:1], s[10:11]
	s_movk_i32 s9, 0x3020
	v_bfe_u32 v2, v20, 4, 2
	v_mad_i64_i32 v[0:1], s[10:11], v94, s9, v[0:1]
	s_lshl_b32 s0, s8, 8
	v_lshl_add_u64 v[92:93], v[0:1], 0, s[0:1]
	v_lshlrev_b32_e32 v16, 4, v2
	v_mov_b32_e32 v17, v169
	v_ashrrev_i32_e32 v50, 3, v20
	v_lshl_add_u64 v[0:1], v[92:93], 0, v[16:17]
	v_ashrrev_i32_e32 v101, 4, v20
	v_mov_b64_e32 v[30:31], s[4:5]
	v_lshlrev_b32_e32 v17, 4, v20
	v_ashrrev_i32_e32 v51, 31, v50
	v_mad_i64_i32 v[18:19], s[10:11], v101, s9, v[30:31]
	v_and_b32_e32 v84, 0xf0, v17
	v_mov_b32_e32 v85, v169
	v_add_u32_e32 v103, 16, v101
	v_lshlrev_b64 v[34:35], 9, v[50:51]
	v_lshl_add_u64 v[18:19], v[18:19], 0, v[84:85]
	v_mad_i64_i32 v[22:23], s[10:11], v103, s9, v[30:31]
	v_add_u32_e32 v105, 32, v101
	v_and_b32_e32 v52, 0x70, v17
	v_mov_b32_e32 v53, v169
	v_lshl_add_u64 v[34:35], s[6:7], 0, v[34:35]
	s_barrier
	v_lshlrev_b32_e32 v168, 3, v2
	global_load_dwordx4 v[12:15], v[0:1], off
	global_load_dwordx4 v[8:11], v[0:1], off offset:64
	global_load_dwordx4 v[4:7], v[0:1], off offset:128
	s_nop 0
	global_load_dwordx4 v[0:3], v[0:1], off offset:192
	v_lshl_add_u64 v[22:23], v[22:23], 0, v[84:85]
	global_load_dwordx4 v[18:21], v[18:19], off offset:1024
	v_mad_i64_i32 v[26:27], s[10:11], v105, s9, v[30:31]
	v_add_u32_e32 v107, 48, v101
	v_lshl_add_u64 v[86:87], v[34:35], 0, v[52:53]
	global_load_dwordx4 v[22:25], v[22:23], off offset:1024
	v_lshl_add_u64 v[26:27], v[26:27], 0, v[84:85]
	v_mad_i64_i32 v[30:31], s[10:11], v107, s9, v[30:31]
	v_add_co_u32_e32 v38, vcc, s97, v86
	s_mov_b64 s[2:3], 0x8000
	global_load_dwordx4 v[26:29], v[26:27], off offset:1024
	v_lshl_add_u64 v[30:31], v[30:31], 0, v[84:85]
	v_addc_co_u32_e32 v39, vcc, 0, v87, vcc
	v_lshl_add_u64 v[90:91], v[86:87], 0, s[2:3]
	s_mov_b32 s3, 0x8000
	global_load_dwordx4 v[30:33], v[30:31], off offset:1024
	v_add_co_u32_e32 v42, vcc, s3, v86
	s_mov_b64 s[2:3], 0xc000
	global_load_dwordx4 v[34:37], v[86:87], off
	v_addc_co_u32_e32 v43, vcc, 0, v87, vcc
	v_lshl_add_u64 v[112:113], v[86:87], 0, s[2:3]
	s_mov_b32 s3, 0xc000
	global_load_dwordx4 v[38:41], v[38:39], off
	v_add_co_u32_e32 v46, vcc, s3, v86
	global_load_dwordx4 v[42:45], v[42:43], off
	s_nop 0
	v_addc_co_u32_e32 v47, vcc, 0, v87, vcc
	global_load_dwordx4 v[46:49], v[46:47], off
	s_movk_i32 s3, 0x110
	s_movk_i32 s10, 0x90
	v_mad_u64_u32 v[98:99], s[6:7], v101, s3, v[84:85]
	v_mad_u64_u32 v[96:97], s[6:7], v50, s10, v[52:53]
	s_add_u32 s6, s4, 0xc0c00
	s_addc_u32 s7, s5, 0
	s_waitcnt vmcnt(7)
	ds_write_b128 v98, v[18:21]
	s_waitcnt vmcnt(6)
	ds_write_b128 v98, v[22:25] offset:4352
	s_waitcnt vmcnt(5)
	ds_write_b128 v98, v[26:29] offset:8704
	s_waitcnt vmcnt(4)
	ds_write_b128 v98, v[30:33] offset:13056
	s_waitcnt vmcnt(3)
	ds_write_b128 v96, v[34:37] offset:34816
	s_waitcnt vmcnt(2)
	ds_write_b128 v96, v[38:41] offset:39424
	s_waitcnt vmcnt(1)
	ds_write_b128 v96, v[42:45] offset:44032
	s_waitcnt vmcnt(0)
	ds_write_b128 v96, v[46:49] offset:48640
	v_mov_b64_e32 v[30:31], s[6:7]
	v_mad_i64_i32 v[18:19], s[6:7], v101, s9, v[30:31]
	v_mad_i64_i32 v[22:23], s[6:7], v103, s9, v[30:31]
	v_mad_i64_i32 v[26:27], s[6:7], v105, s9, v[30:31]
	v_mad_i64_i32 v[30:31], s[6:7], v107, s9, v[30:31]
	v_lshl_add_u64 v[18:19], v[18:19], 0, v[84:85]
	v_lshl_add_u64 v[22:23], v[22:23], 0, v[84:85]
	v_lshl_add_u64 v[26:27], v[26:27], 0, v[84:85]
	v_lshl_add_u64 v[30:31], v[30:31], 0, v[84:85]
	v_lshl_add_u64 v[88:89], v[86:87], 0, s[84:85]
	global_load_dwordx4 v[18:21], v[18:19], off
	v_mbcnt_hi_u32_b32 v17, -1, v214
	global_load_dwordx4 v[22:25], v[22:23], off
	v_and_b32_e32 v51, 64, v17
	global_load_dwordx4 v[26:29], v[26:27], off
	s_nop 0
	global_load_dwordx4 v[30:33], v[30:31], off
	s_nop 0
	global_load_dwordx4 v[34:37], v[86:87], off offset:128
	global_load_dwordx4 v[38:41], v[88:89], off offset:128
	global_load_dwordx4 v[42:45], v[90:91], off offset:128
	global_load_dwordx4 v[46:49], v[112:113], off offset:128
	v_xor_b32_e32 v50, 16, v17
	v_add_u32_e32 v51, 64, v51
	v_cmp_lt_i32_e32 vcc, v50, v51
	s_add_u32 s6, s4, 0x181400
	s_addc_u32 s7, s5, 0
	v_cndmask_b32_e32 v50, v17, v50, vcc
	v_add_u32_e32 v99, 0x8800, v96
	s_waitcnt lgkmcnt(0)
	s_barrier
	v_lshlrev_b32_e32 v132, 2, v50
	v_xor_b32_e32 v50, 32, v17
	s_waitcnt vmcnt(7)
	ds_write_b128 v98, v[18:21] offset:17408
	s_waitcnt vmcnt(6)
	ds_write_b128 v98, v[22:25] offset:21760
	s_waitcnt vmcnt(5)
	ds_write_b128 v98, v[26:29] offset:26112
	s_waitcnt vmcnt(4)
	ds_write_b128 v98, v[30:33] offset:30464
	s_waitcnt vmcnt(3)
	ds_write_b128 v96, v[34:37] offset:53248
	s_waitcnt vmcnt(2)
	ds_write_b128 v96, v[38:41] offset:57856
	s_waitcnt vmcnt(1)
	ds_write_b128 v96, v[42:45] offset:62464
	s_waitcnt vmcnt(0)
	ds_write_b128 v99, v[46:49] offset:32256
	v_mov_b64_e32 v[18:19], s[6:7]
	v_cmp_lt_i32_e32 vcc, v50, v51
	v_mad_i64_i32 v[20:21], s[6:7], v101, s9, v[18:19]
	v_mad_i64_i32 v[24:25], s[6:7], v103, s9, v[18:19]
	v_mad_i64_i32 v[28:29], s[6:7], v105, s9, v[18:19]
	v_mad_i64_i32 v[18:19], s[6:7], v107, s9, v[18:19]
	v_cndmask_b32_e32 v17, v17, v50, vcc
	v_lshl_add_u64 v[20:21], v[20:21], 0, v[84:85]
	v_lshl_add_u64 v[24:25], v[24:25], 0, v[84:85]
	v_lshl_add_u64 v[28:29], v[28:29], 0, v[84:85]
	v_lshl_add_u64 v[18:19], v[18:19], 0, v[84:85]
	v_mad_u32_u24 v97, v56, s3, v16
	v_lshlrev_b32_e32 v133, 2, v17
	v_sub_u32_e32 v57, v16, v168
	global_load_dwordx4 v[20:23], v[20:21], off
	s_mov_b32 s7, 0xf149f2ca
	global_load_dwordx4 v[24:27], v[24:25], off
	s_mov_b32 s6, 0x3db504f3
	global_load_dwordx4 v[28:31], v[28:29], off
	s_nop 0
	global_load_dwordx4 v[32:35], v[18:19], off
	global_load_dwordx4 v[36:39], v[86:87], off offset:256
	global_load_dwordx4 v[40:43], v[88:89], off offset:256
	global_load_dwordx4 v[44:47], v[90:91], off offset:256
	global_load_dwordx4 v[48:51], v[112:113], off offset:256
	ds_read_b128 v[16:19], v97
	ds_read_b128 v[52:55], v97 offset:64
	s_waitcnt lgkmcnt(1)
	v_mfma_f32_16x16x32_f16 v[16:19], v[16:19], v[12:15], 0
	ds_read_b128 v[58:61], v97 offset:4416
	ds_read_b128 v[62:65], v97 offset:8768
	ds_read_b128 v[66:69], v97 offset:13120
	s_waitcnt lgkmcnt(3)
	v_mfma_f32_16x16x32_f16 v[16:19], v[52:55], v[8:11], v[16:19]
	ds_read_b128 v[52:55], v97 offset:128
	v_mad_u32_u24 v142, v56, s10, v57
	v_add_u32_e32 v134, 0x8800, v142
	s_waitcnt lgkmcnt(0)
	v_mfma_f32_16x16x32_f16 v[16:19], v[52:55], v[4:7], v[16:19]
	ds_read_b128 v[52:55], v97 offset:192
	v_add_u32_e32 v135, 0x9000, v142
	v_add_u32_e32 v136, 0x9800, v142
	s_waitcnt lgkmcnt(0)
	v_mfma_f32_16x16x32_f16 v[16:19], v[52:55], v[0:3], v[16:19]
	ds_read_b128 v[52:55], v97 offset:4352
	v_add_u32_e32 v137, 0xa000, v142
	v_add_u32_e32 v138, 0xa800, v142
	s_waitcnt lgkmcnt(0)
	v_mfma_f32_16x16x32_f16 v[52:55], v[52:55], v[12:15], 0
	v_add_u32_e32 v139, 0xb000, v142
	v_add_u32_e32 v140, 0xb800, v142
	v_add_u32_e32 v141, 0xc000, v142
	v_mfma_f32_16x16x32_f16 v[52:55], v[58:61], v[8:11], v[52:55]
	ds_read_b128 v[58:61], v97 offset:4480
	ds_read2_b64 v[72:75], v138 offset0:128 offset1:132
	ds_read2_b64 v[76:79], v139 offset0:160 offset1:164
	s_waitcnt lgkmcnt(2)
	v_mfma_f32_16x16x32_f16 v[52:55], v[58:61], v[4:7], v[52:55]
	ds_read_b128 v[58:61], v97 offset:4544
	ds_read2_b64 v[80:83], v140 offset0:192 offset1:196
	ds_read2_b64 v[144:147], v141 offset0:224 offset1:228
	s_waitcnt lgkmcnt(2)
	v_mfma_f32_16x16x32_f16 v[52:55], v[58:61], v[0:3], v[52:55]
	ds_read_b128 v[58:61], v97 offset:8704
	s_add_u32 s4, s4, 0x241c00
	s_addc_u32 s5, s5, 0
	s_waitcnt lgkmcnt(0)
	v_mfma_f32_16x16x32_f16 v[58:61], v[58:61], v[12:15], 0
	v_mov_b32_e32 v131, v169
	v_readlane_b32 s44, v253, 32
	v_readlane_b32 s45, v253, 33
	v_mfma_f32_16x16x32_f16 v[58:61], v[62:65], v[8:11], v[58:61]
	ds_read_b128 v[62:65], v97 offset:8832
	v_ashrrev_i32_e32 v95, 31, v94
	s_movk_i32 s3, 0x3020
	s_waitcnt lgkmcnt(0)
	v_mfma_f32_16x16x32_f16 v[58:61], v[62:65], v[4:7], v[58:61]
	ds_read_b128 v[62:65], v97 offset:8896
	s_mov_b32 s2, 0xf149f2ca
	v_readlane_b32 s46, v253, 34
	s_waitcnt lgkmcnt(0)
	v_mfma_f32_16x16x32_f16 v[58:61], v[62:65], v[0:3], v[58:61]
	ds_read_b128 v[62:65], v97 offset:13056
	v_readlane_b32 s47, v253, 35
	v_readlane_b32 s48, v253, 36
	s_waitcnt lgkmcnt(0)
	v_mfma_f32_16x16x32_f16 v[62:65], v[62:65], v[12:15], 0
	v_readlane_b32 s49, v253, 37
	v_readlane_b32 s50, v253, 38
	v_readlane_b32 s51, v253, 39
	v_mfma_f32_16x16x32_f16 v[62:65], v[66:69], v[8:11], v[62:65]
	ds_read_b128 v[66:69], v97 offset:13184
	v_readlane_b32 s52, v253, 40
	v_readlane_b32 s53, v253, 41
	s_waitcnt lgkmcnt(0)
	v_mfma_f32_16x16x32_f16 v[62:65], v[66:69], v[4:7], v[62:65]
	ds_read_b128 v[66:69], v97 offset:13248
	v_readlane_b32 s54, v253, 42
	v_readlane_b32 s55, v253, 43
	s_waitcnt lgkmcnt(0)
	v_mfma_f32_16x16x32_f16 v[62:65], v[66:69], v[0:3], v[62:65]
	v_mul_f32_e32 v66, 0x3db504f3, v16
	v_mul_f32_e32 v67, 0x3db504f3, v17
	v_max3_f32 v66, v66, s7, v67
	v_mul_f32_e32 v67, 0x3db504f3, v18
	v_mul_f32_e32 v68, 0x3db504f3, v19
	v_max3_f32 v66, v66, v67, v68
	v_mul_f32_e32 v67, 0x3db504f3, v52
	v_mul_f32_e32 v68, 0x3db504f3, v53
	v_max3_f32 v66, v66, v67, v68
	v_mul_f32_e32 v67, 0x3db504f3, v54
	v_mul_f32_e32 v68, 0x3db504f3, v55
	v_max3_f32 v66, v66, v67, v68
	v_mul_f32_e32 v67, 0x3db504f3, v58
	v_mul_f32_e32 v68, 0x3db504f3, v59
	v_max3_f32 v66, v66, v67, v68
	v_mul_f32_e32 v67, 0x3db504f3, v60
	v_mul_f32_e32 v68, 0x3db504f3, v61
	v_max3_f32 v66, v66, v67, v68
	v_mul_f32_e32 v67, 0x3db504f3, v62
	v_mul_f32_e32 v68, 0x3db504f3, v63
	v_max3_f32 v66, v66, v67, v68
	v_mul_f32_e32 v67, 0x3db504f3, v64
	v_mul_f32_e32 v68, 0x3db504f3, v65
	v_max3_f32 v66, v66, v67, v68
	ds_bpermute_b32 v67, v132, v66
	v_readlane_b32 s56, v253, 44
	v_readlane_b32 s57, v253, 45
	v_readlane_b32 s58, v253, 46
	v_readlane_b32 s59, v253, 47
	s_waitcnt lgkmcnt(0)
	v_max_f32_e32 v67, v67, v67
	v_max_f32_e32 v66, v66, v67
	ds_bpermute_b32 v67, v133, v66
	s_waitcnt lgkmcnt(0)
	v_max3_f32 v109, v66, v67, s7
	v_fma_f32 v16, v16, s6, -v109
	v_mul_f32_e32 v16, 0x3fb8aa3b, v16
	v_fma_f32 v17, v17, s6, -v109
	v_exp_f32_e32 v67, v16
	v_mul_f32_e32 v17, 0x3fb8aa3b, v17
	v_exp_f32_e32 v68, v17
	v_sub_f32_e32 v66, 0xf149f2ca, v109
	v_add_f32_e32 v16, 0, v67
	v_mul_f32_e32 v66, 0x3fb8aa3b, v66
	v_add_f32_e32 v130, v68, v16
	v_fma_f32 v16, v18, s6, -v109
	v_mul_f32_e32 v16, 0x3fb8aa3b, v16
	v_exp_f32_e32 v114, v16
	v_fma_f32 v16, v19, s6, -v109
	v_mul_f32_e32 v16, 0x3fb8aa3b, v16
	v_exp_f32_e32 v116, v16
	v_fma_f32 v16, v52, s6, -v109
	v_mul_f32_e32 v16, 0x3fb8aa3b, v16
	v_exp_f32_e32 v118, v16
	v_fma_f32 v16, v53, s6, -v109
	v_mul_f32_e32 v16, 0x3fb8aa3b, v16
	v_exp_f32_e32 v120, v16
	v_fma_f32 v16, v54, s6, -v109
	v_mul_f32_e32 v16, 0x3fb8aa3b, v16
	v_exp_f32_e32 v122, v16
	v_fma_f32 v16, v55, s6, -v109
	v_mul_f32_e32 v16, 0x3fb8aa3b, v16
	v_exp_f32_e32 v124, v16
	v_fma_f32 v16, v58, s6, -v109
	v_mul_f32_e32 v16, 0x3fb8aa3b, v16
	v_exp_f32_e32 v126, v16
	v_fma_f32 v16, v59, s6, -v109
	v_mul_f32_e32 v16, 0x3fb8aa3b, v16
	v_exp_f32_e32 v128, v16
	v_fma_f32 v16, v60, s6, -v109
	v_mul_f32_e32 v16, 0x3fb8aa3b, v16
	v_exp_f32_e32 v100, v16
	v_fma_f32 v16, v61, s6, -v109
	v_mul_f32_e32 v16, 0x3fb8aa3b, v16
	v_exp_f32_e32 v102, v16
	v_fma_f32 v16, v62, s6, -v109
	v_mul_f32_e32 v16, 0x3fb8aa3b, v16
	v_exp_f32_e32 v104, v16
	v_fma_f32 v16, v63, s6, -v109
	v_mul_f32_e32 v16, 0x3fb8aa3b, v16
	v_exp_f32_e32 v106, v16
	v_fma_f32 v16, v64, s6, -v109
	v_mul_f32_e32 v16, 0x3fb8aa3b, v16
	v_exp_f32_e32 v108, v16
	v_fma_f32 v16, v65, s6, -v109
	v_mul_f32_e32 v16, 0x3fb8aa3b, v16
	v_exp_f32_e32 v110, v16
	v_exp_f32_e32 v16, v66
	v_cvt_pk_f16_f32 v60, v67, v68
	ds_read2_b64 v[52:55], v134 offset1:4
	ds_read2_b64 v[56:59], v135 offset0:32 offset1:36
	ds_read2_b64 v[64:67], v136 offset0:64 offset1:68
	ds_read2_b64 v[68:71], v137 offset0:96 offset1:100
	v_mul_f32_e32 v16, 0, v16
	v_mov_b32_e32 v17, v16
	v_mov_b32_e32 v18, v16
	v_mov_b32_e32 v19, v16
	v_cvt_pk_f16_f32 v63, v122, v124
	v_cvt_pk_f16_f32 v62, v118, v120
	v_cvt_pk_f16_f32 v61, v114, v116
	v_cvt_pk_f16_f32 v151, v108, v110
	v_cvt_pk_f16_f32 v150, v104, v106
	s_waitcnt lgkmcnt(3)
	v_mfma_f32_16x16x32_f16 v[52:55], v[52:55], v[60:63], v[16:19]
	v_cvt_pk_f16_f32 v149, v100, v102
	v_cvt_pk_f16_f32 v148, v126, v128
	s_waitcnt lgkmcnt(2)
	v_mfma_f32_16x16x32_f16 v[56:59], v[56:59], v[60:63], v[16:19]
	s_waitcnt lgkmcnt(1)
	v_mfma_f32_16x16x32_f16 v[64:67], v[64:67], v[60:63], v[16:19]
	s_waitcnt lgkmcnt(0)
	v_mfma_f32_16x16x32_f16 v[68:71], v[68:71], v[60:63], v[16:19]
	v_mfma_f32_16x16x32_f16 v[72:75], v[72:75], v[60:63], v[16:19]
	v_mfma_f32_16x16x32_f16 v[76:79], v[76:79], v[60:63], v[16:19]
	v_mfma_f32_16x16x32_f16 v[80:83], v[80:83], v[60:63], v[16:19]
	v_mfma_f32_16x16x32_f16 v[144:147], v[144:147], v[60:63], v[16:19]
	ds_read2_b64 v[60:63], v134 offset0:8 offset1:12
	s_waitcnt lgkmcnt(0)
	v_mfma_f32_16x16x32_f16 v[52:55], v[60:63], v[148:151], v[52:55]
	ds_read2_b64 v[60:63], v135 offset0:40 offset1:44
	s_waitcnt lgkmcnt(0)
	v_mfma_f32_16x16x32_f16 v[56:59], v[60:63], v[148:151], v[56:59]
	ds_read2_b64 v[60:63], v136 offset0:72 offset1:76
	s_waitcnt lgkmcnt(0)
	v_mfma_f32_16x16x32_f16 v[60:63], v[60:63], v[148:151], v[64:67]
	s_nop 2
	ds_read2_b64 v[64:67], v137 offset0:104 offset1:108
	s_waitcnt lgkmcnt(0)
	v_mfma_f32_16x16x32_f16 v[64:67], v[64:67], v[148:151], v[68:71]
	s_nop 2
	ds_read2_b64 v[68:71], v138 offset0:136 offset1:140
	s_waitcnt lgkmcnt(0)
	v_mfma_f32_16x16x32_f16 v[68:71], v[68:71], v[148:151], v[72:75]
	s_nop 2
	ds_read2_b64 v[72:75], v139 offset0:168 offset1:172
	s_waitcnt lgkmcnt(0)
	v_mfma_f32_16x16x32_f16 v[72:75], v[72:75], v[148:151], v[76:79]
	s_nop 2
	ds_read2_b64 v[76:79], v140 offset0:200 offset1:204
	s_waitcnt lgkmcnt(0)
	v_mfma_f32_16x16x32_f16 v[76:79], v[76:79], v[148:151], v[80:83]
	s_nop 2
	ds_read2_b64 v[80:83], v141 offset0:232 offset1:236
	s_waitcnt lgkmcnt(0)
	s_barrier
	s_waitcnt vmcnt(7)
	ds_write_b128 v98, v[20:23]
	s_waitcnt vmcnt(6)
	ds_write_b128 v98, v[24:27] offset:4352
	s_waitcnt vmcnt(5)
	ds_write_b128 v98, v[28:31] offset:8704
	s_waitcnt vmcnt(4)
	ds_write_b128 v98, v[32:35] offset:13056
	s_waitcnt vmcnt(3)
	ds_write_b128 v96, v[36:39] offset:34816
	s_waitcnt vmcnt(2)
	ds_write_b128 v96, v[40:43] offset:39424
	s_waitcnt vmcnt(1)
	ds_write_b128 v96, v[44:47] offset:44032
	s_waitcnt vmcnt(0)
	ds_write_b128 v96, v[48:51] offset:48640
	v_mov_b64_e32 v[30:31], s[4:5]
	v_mad_i64_i32 v[18:19], s[4:5], v101, s9, v[30:31]
	v_mad_i64_i32 v[22:23], s[4:5], v103, s9, v[30:31]
	v_mad_i64_i32 v[26:27], s[4:5], v105, s9, v[30:31]
	v_mad_i64_i32 v[30:31], s[4:5], v107, s9, v[30:31]
	v_lshl_add_u64 v[18:19], v[18:19], 0, v[84:85]
	v_lshl_add_u64 v[22:23], v[22:23], 0, v[84:85]
	v_lshl_add_u64 v[26:27], v[26:27], 0, v[84:85]
	v_lshl_add_u64 v[30:31], v[30:31], 0, v[84:85]
	global_load_dwordx4 v[18:21], v[18:19], off
	v_mfma_f32_16x16x32_f16 v[80:83], v[80:83], v[148:151], v[144:147]
	global_load_dwordx4 v[22:25], v[22:23], off
	v_readlane_b32 s4, v255, 47
	global_load_dwordx4 v[26:29], v[26:27], off
	s_nop 0
	global_load_dwordx4 v[30:33], v[30:31], off
	s_nop 0
	global_load_dwordx4 v[34:37], v[86:87], off offset:384
	global_load_dwordx4 v[38:41], v[88:89], off offset:384
	global_load_dwordx4 v[42:45], v[90:91], off offset:384
	global_load_dwordx4 v[46:49], v[112:113], off offset:384
	ds_read_b128 v[84:87], v97 offset:17408
	ds_read_b128 v[88:91], v97 offset:17472
	s_waitcnt lgkmcnt(1)
	v_mfma_f32_16x16x32_f16 v[84:87], v[84:87], v[12:15], 0
	ds_read_b128 v[144:147], v97 offset:21824
	ds_read_b128 v[148:151], v97 offset:26176
	ds_read_b128 v[152:155], v97 offset:30528
	s_waitcnt lgkmcnt(3)
	v_mfma_f32_16x16x32_f16 v[84:87], v[88:91], v[8:11], v[84:87]
	ds_read_b128 v[88:91], v97 offset:17536
	s_or_b32 s4, s8, s4
	s_ashr_i32 s5, s4, 31
	s_waitcnt lgkmcnt(0)
	v_mfma_f32_16x16x32_f16 v[84:87], v[88:91], v[4:7], v[84:87]
	ds_read_b128 v[88:91], v97 offset:17600
	s_lshl_b64 s[4:5], s[4:5], 2
	s_add_u32 s4, s44, s4
	s_waitcnt lgkmcnt(0)
	v_mfma_f32_16x16x32_f16 v[84:87], v[88:91], v[0:3], v[84:87]
	ds_read_b128 v[88:91], v97 offset:21760
	s_addc_u32 s5, s45, s5
	s_nop 5
	v_mul_f32_e32 v17, 0x3db504f3, v84
	s_waitcnt lgkmcnt(0)
	v_mfma_f32_16x16x32_f16 v[88:91], v[88:91], v[12:15], 0
	v_mul_f32_e32 v50, 0x3db504f3, v85
	v_max3_f32 v17, v17, s7, v50
	v_mul_f32_e32 v50, 0x3db504f3, v86
	v_mfma_f32_16x16x32_f16 v[88:91], v[144:147], v[8:11], v[88:91]
	ds_read_b128 v[144:147], v97 offset:21888
	v_mul_f32_e32 v51, 0x3db504f3, v87
	v_max3_f32 v17, v17, v50, v51
	s_waitcnt lgkmcnt(0)
	v_mfma_f32_16x16x32_f16 v[88:91], v[144:147], v[4:7], v[88:91]
	ds_read_b128 v[144:147], v97 offset:21952
	s_waitcnt lgkmcnt(0)
	v_mfma_f32_16x16x32_f16 v[88:91], v[144:147], v[0:3], v[88:91]
	ds_read_b128 v[144:147], v97 offset:26112
	s_nop 6
	v_mul_f32_e32 v50, 0x3db504f3, v88
	s_waitcnt lgkmcnt(0)
	v_mfma_f32_16x16x32_f16 v[144:147], v[144:147], v[12:15], 0
	v_mul_f32_e32 v51, 0x3db504f3, v89
	v_max3_f32 v17, v17, v50, v51
	v_mul_f32_e32 v50, 0x3db504f3, v90
	v_mfma_f32_16x16x32_f16 v[144:147], v[148:151], v[8:11], v[144:147]
	ds_read_b128 v[148:151], v97 offset:26240
	v_mul_f32_e32 v51, 0x3db504f3, v91
	v_max3_f32 v17, v17, v50, v51
	s_waitcnt lgkmcnt(0)
	v_mfma_f32_16x16x32_f16 v[144:147], v[148:151], v[4:7], v[144:147]
	ds_read_b128 v[148:151], v97 offset:26304
	s_waitcnt lgkmcnt(0)
	v_mfma_f32_16x16x32_f16 v[144:147], v[148:151], v[0:3], v[144:147]
	ds_read_b128 v[148:151], v97 offset:30464
	s_nop 6
	v_mul_f32_e32 v50, 0x3db504f3, v144
	s_waitcnt lgkmcnt(0)
	v_mfma_f32_16x16x32_f16 v[148:151], v[148:151], v[12:15], 0
	v_mul_f32_e32 v51, 0x3db504f3, v145
	v_max3_f32 v17, v17, v50, v51
	v_mul_f32_e32 v50, 0x3db504f3, v146
	v_mfma_f32_16x16x32_f16 v[148:151], v[152:155], v[8:11], v[148:151]
	ds_read_b128 v[152:155], v97 offset:30592
	v_mul_f32_e32 v51, 0x3db504f3, v147
	v_max3_f32 v17, v17, v50, v51
	s_waitcnt lgkmcnt(0)
	v_mfma_f32_16x16x32_f16 v[148:151], v[152:155], v[4:7], v[148:151]
	ds_read_b128 v[152:155], v97 offset:30656
	s_waitcnt lgkmcnt(0)
	v_mfma_f32_16x16x32_f16 v[148:151], v[152:155], v[0:3], v[148:151]
	s_nop 7
	v_mul_f32_e32 v50, 0x3db504f3, v148
	v_mul_f32_e32 v51, 0x3db504f3, v149
	v_max3_f32 v17, v17, v50, v51
	v_mul_f32_e32 v50, 0x3db504f3, v150
	v_mul_f32_e32 v51, 0x3db504f3, v151
	v_max3_f32 v17, v17, v50, v51
	ds_bpermute_b32 v50, v132, v17
	s_waitcnt lgkmcnt(0)
	v_max_f32_e32 v50, v50, v50
	v_max_f32_e32 v17, v17, v50
	ds_bpermute_b32 v50, v133, v17
	s_waitcnt lgkmcnt(0)
	v_max3_f32 v113, v109, v17, v50
	v_sub_f32_e32 v17, v109, v113
	v_mul_f32_e32 v112, 0x3fb8aa3b, v17
	v_fma_f32 v17, v84, s6, -v113
	v_mul_f32_e32 v17, 0x3fb8aa3b, v17
	v_exp_f32_e32 v115, v17
	v_fma_f32 v17, v85, s6, -v113
	v_mul_f32_e32 v17, 0x3fb8aa3b, v17
	v_exp_f32_e32 v117, v17
	v_fma_f32 v17, v86, s6, -v113
	v_mul_f32_e32 v17, 0x3fb8aa3b, v17
	v_exp_f32_e32 v119, v17
	v_fma_f32 v17, v87, s6, -v113
	v_mul_f32_e32 v17, 0x3fb8aa3b, v17
	v_exp_f32_e32 v121, v17
	v_fma_f32 v17, v88, s6, -v113
	v_mul_f32_e32 v17, 0x3fb8aa3b, v17
	v_exp_f32_e32 v123, v17
	v_fma_f32 v17, v89, s6, -v113
	v_mul_f32_e32 v17, 0x3fb8aa3b, v17
	v_exp_f32_e32 v125, v17
	v_fma_f32 v17, v90, s6, -v113
	v_mul_f32_e32 v17, 0x3fb8aa3b, v17
	v_exp_f32_e32 v127, v17
	v_fma_f32 v17, v91, s6, -v113
	v_mul_f32_e32 v17, 0x3fb8aa3b, v17
	v_exp_f32_e32 v129, v17
	v_fma_f32 v17, v144, s6, -v113
	v_mul_f32_e32 v17, 0x3fb8aa3b, v17
	v_exp_f32_e32 v101, v17
	v_fma_f32 v17, v145, s6, -v113
	v_mul_f32_e32 v17, 0x3fb8aa3b, v17
	v_pk_add_f32 v[50:51], v[114:115], v[130:131]
	v_exp_f32_e32 v103, v17
	v_fma_f32 v17, v146, s6, -v113
	v_pk_add_f32 v[50:51], v[116:117], v[50:51]
	v_mul_f32_e32 v17, 0x3fb8aa3b, v17
	v_pk_add_f32 v[50:51], v[118:119], v[50:51]
	v_exp_f32_e32 v105, v17
	v_fma_f32 v17, v147, s6, -v113
	v_pk_add_f32 v[50:51], v[120:121], v[50:51]
	v_mul_f32_e32 v17, 0x3fb8aa3b, v17
	v_exp_f32_e32 v107, v17
	v_fma_f32 v17, v148, s6, -v113
	v_pk_add_f32 v[50:51], v[122:123], v[50:51]
	v_mul_f32_e32 v17, 0x3fb8aa3b, v17
	v_pk_add_f32 v[50:51], v[124:125], v[50:51]
	v_exp_f32_e32 v109, v17
	v_fma_f32 v17, v149, s6, -v113
	v_pk_add_f32 v[50:51], v[126:127], v[50:51]
	v_mul_f32_e32 v17, 0x3fb8aa3b, v17
	v_pk_add_f32 v[50:51], v[128:129], v[50:51]
	v_exp_f32_e32 v111, v17
	v_fma_f32 v17, v150, s6, -v113
	v_pk_add_f32 v[50:51], v[100:101], v[50:51]
	v_mul_f32_e32 v17, 0x3fb8aa3b, v17
	v_pk_add_f32 v[50:51], v[102:103], v[50:51]
	v_exp_f32_e32 v17, v17
	v_exp_f32_e32 v112, v112
	v_pk_add_f32 v[50:51], v[104:105], v[50:51]
	v_add_u32_e32 v120, 0xe000, v142
	v_pk_add_f32 v[50:51], v[106:107], v[50:51]
	v_pk_mul_f32 v[148:149], v[56:57], v[112:113] op_sel_hi:[1,0]
	v_pk_add_f32 v[50:51], v[108:109], v[50:51]
	v_pk_mul_f32 v[56:57], v[78:79], v[112:113] op_sel_hi:[1,0]
	v_pk_add_f32 v[50:51], v[110:111], v[50:51]
	v_pk_mul_f32 v[146:147], v[54:55], v[112:113] op_sel_hi:[1,0]
	v_pk_add_f32 v[130:131], v[16:17], v[50:51]
	v_pk_mul_f32 v[50:51], v[80:81], v[112:113] op_sel_hi:[1,0]
	ds_read2_b64 v[78:81], v120 offset0:64 offset1:68
	v_pk_mul_f32 v[90:91], v[62:63], v[112:113] op_sel_hi:[1,0]
	v_pk_mul_f32 v[88:89], v[60:61], v[112:113] op_sel_hi:[1,0]
	v_pk_mul_f32 v[60:61], v[74:75], v[112:113] op_sel_hi:[1,0]
	v_pk_mul_f32 v[54:55], v[76:77], v[112:113] op_sel_hi:[1,0]
	v_cvt_pk_f16_f32 v77, v127, v129
	v_cvt_pk_f16_f32 v76, v123, v125
	v_cvt_pk_f16_f32 v75, v119, v121
	v_cvt_pk_f16_f32 v74, v115, v117
	v_add_u32_e32 v121, 0xe800, v142
	v_fma_f32 v84, v151, s6, -v113
	s_waitcnt lgkmcnt(0)
	v_mfma_f32_16x16x32_f16 v[78:81], v[78:81], v[74:77], v[88:91]
	v_mul_f32_e32 v84, 0x3fb8aa3b, v84
	v_exp_f32_e32 v114, v84
	v_pk_mul_f32 v[86:87], v[66:67], v[112:113] op_sel_hi:[1,0]
	ds_read2_b64 v[88:91], v121 offset0:96 offset1:100
	v_pk_mul_f32 v[84:85], v[64:65], v[112:113] op_sel_hi:[1,0]
	v_add_u32_e32 v122, 0xf000, v142
	v_pk_mul_f32 v[144:145], v[52:53], v[112:113] op_sel_hi:[1,0]
	v_pk_mul_f32 v[52:53], v[82:83], v[112:113] op_sel_hi:[1,0]
	s_waitcnt lgkmcnt(0)
	v_mfma_f32_16x16x32_f16 v[82:85], v[88:91], v[74:77], v[84:87]
	s_nop 2
	ds_read2_b64 v[86:89], v122 offset0:128 offset1:132
	v_pk_mul_f32 v[64:65], v[70:71], v[112:113] op_sel_hi:[1,0]
	v_pk_mul_f32 v[62:63], v[68:69], v[112:113] op_sel_hi:[1,0]
	v_add_u32_e32 v123, 0xf800, v142
	v_add_u32_e32 v118, 0xd000, v142
	s_waitcnt lgkmcnt(0)
	v_mfma_f32_16x16x32_f16 v[86:89], v[86:89], v[74:77], v[62:65]
	s_nop 2
	ds_read2_b64 v[62:65], v123 offset0:160 offset1:164
	v_pk_mul_f32 v[150:151], v[58:59], v[112:113] op_sel_hi:[1,0]
	v_pk_mul_f32 v[58:59], v[72:73], v[112:113] op_sel_hi:[1,0]
	v_add_u32_e32 v124, 0x3000, v118
	ds_read2_b64 v[66:69], v118 offset1:4
	s_waitcnt lgkmcnt(1)
	v_mfma_f32_16x16x32_f16 v[126:129], v[62:65], v[74:77], v[58:61]
	s_nop 2
	ds_read2_b64 v[58:61], v124 offset0:192 offset1:196
	v_add_u32_e32 v119, 0xd800, v142
	v_add_u32_e32 v125, 0x3800, v118
	s_waitcnt lgkmcnt(1)
	v_mfma_f32_16x16x32_f16 v[66:69], v[66:69], v[74:77], v[144:147]
	ds_read2_b64 v[70:73], v119 offset0:32 offset1:36
	v_cvt_pk_f16_f32 v153, v17, v114
	v_cvt_pk_f16_f32 v152, v109, v111
	s_waitcnt lgkmcnt(1)
	v_mfma_f32_16x16x32_f16 v[142:145], v[58:61], v[74:77], v[54:57]
	ds_read2_b64 v[58:61], v120 offset0:72 offset1:76
	s_nop 1
	ds_read2_b64 v[54:57], v125 offset0:224 offset1:228
	ds_read2_b64 v[62:65], v121 offset0:104 offset1:108
	s_waitcnt lgkmcnt(3)
	v_mfma_f32_16x16x32_f16 v[70:73], v[70:73], v[74:77], v[148:151]
	v_mov_b32_e32 v117, v169
	s_waitcnt lgkmcnt(1)
	v_mfma_f32_16x16x32_f16 v[146:149], v[54:57], v[74:77], v[50:53]
	s_nop 2
	ds_read2_b64 v[50:53], v118 offset0:8 offset1:12
	ds_read2_b64 v[54:57], v119 offset0:40 offset1:44
	v_cvt_pk_f16_f32 v151, v105, v107
	v_cvt_pk_f16_f32 v150, v101, v103
	ds_read2_b64 v[74:77], v124 offset0:200 offset1:204
	s_waitcnt lgkmcnt(2)
	v_mfma_f32_16x16x32_f16 v[50:53], v[50:53], v[150:153], v[66:69]
	s_nop 2
	ds_read2_b64 v[66:69], v122 offset0:136 offset1:140
	s_waitcnt lgkmcnt(2)
	v_mfma_f32_16x16x32_f16 v[54:57], v[54:57], v[150:153], v[70:73]
	v_mfma_f32_16x16x32_f16 v[58:61], v[58:61], v[150:153], v[78:81]
	s_nop 1
	ds_read2_b64 v[70:73], v123 offset0:168 offset1:172
	ds_read2_b64 v[78:81], v125 offset0:232 offset1:236
	s_waitcnt lgkmcnt(0)
	s_barrier
	s_waitcnt vmcnt(7)
	ds_write_b128 v98, v[18:21] offset:17408
	s_waitcnt vmcnt(6)
	ds_write_b128 v98, v[22:25] offset:21760
	s_waitcnt vmcnt(5)
	ds_write_b128 v98, v[26:29] offset:26112
	s_waitcnt vmcnt(4)
	ds_write_b128 v98, v[30:33] offset:30464
	s_waitcnt vmcnt(3)
	ds_write_b128 v96, v[34:37] offset:53248
	s_waitcnt vmcnt(2)
	ds_write_b128 v96, v[38:41] offset:57856
	s_waitcnt vmcnt(1)
	ds_write_b128 v96, v[42:45] offset:62464
	s_waitcnt vmcnt(0)
	ds_write_b128 v99, v[46:49] offset:32256
	ds_read_b128 v[16:19], v97
	ds_read_b128 v[20:23], v97 offset:64
	s_waitcnt lgkmcnt(1)
	v_mfma_f32_16x16x32_f16 v[16:19], v[16:19], v[12:15], 0
	ds_read_b128 v[24:27], v97 offset:4416
	ds_read_b128 v[28:31], v97 offset:8768
	ds_read_b128 v[32:35], v97 offset:13120
	s_waitcnt lgkmcnt(3)
	v_mfma_f32_16x16x32_f16 v[16:19], v[20:23], v[8:11], v[16:19]
	ds_read_b128 v[20:23], v97 offset:128
	s_waitcnt lgkmcnt(0)
	v_mfma_f32_16x16x32_f16 v[16:19], v[20:23], v[4:7], v[16:19]
	ds_read_b128 v[20:23], v97 offset:192
	s_waitcnt lgkmcnt(0)
	v_mfma_f32_16x16x32_f16 v[16:19], v[20:23], v[0:3], v[16:19]
	ds_read_b128 v[20:23], v97 offset:4352
	s_waitcnt lgkmcnt(0)
	v_mfma_f32_16x16x32_f16 v[20:23], v[20:23], v[12:15], 0
	v_mfma_f32_16x16x32_f16 v[20:23], v[24:27], v[8:11], v[20:23]
	ds_read_b128 v[24:27], v97 offset:4480
	s_waitcnt lgkmcnt(0)
	v_mfma_f32_16x16x32_f16 v[20:23], v[24:27], v[4:7], v[20:23]
	ds_read_b128 v[24:27], v97 offset:4544
	s_waitcnt lgkmcnt(0)
	v_mfma_f32_16x16x32_f16 v[20:23], v[24:27], v[0:3], v[20:23]
	ds_read_b128 v[24:27], v97 offset:8704
	s_waitcnt lgkmcnt(0)
	v_mfma_f32_16x16x32_f16 v[24:27], v[24:27], v[12:15], 0
	v_mfma_f32_16x16x32_f16 v[24:27], v[28:31], v[8:11], v[24:27]
	ds_read_b128 v[28:31], v97 offset:8832
	s_waitcnt lgkmcnt(0)
	v_mfma_f32_16x16x32_f16 v[24:27], v[28:31], v[4:7], v[24:27]
	ds_read_b128 v[28:31], v97 offset:8896
	s_waitcnt lgkmcnt(0)
	v_mfma_f32_16x16x32_f16 v[24:27], v[28:31], v[0:3], v[24:27]
	ds_read_b128 v[28:31], v97 offset:13056
	s_waitcnt lgkmcnt(0)
	v_mfma_f32_16x16x32_f16 v[28:31], v[28:31], v[12:15], 0
	v_mfma_f32_16x16x32_f16 v[28:31], v[32:35], v[8:11], v[28:31]
	ds_read_b128 v[32:35], v97 offset:13184
	s_waitcnt lgkmcnt(0)
	v_mfma_f32_16x16x32_f16 v[28:31], v[32:35], v[4:7], v[28:31]
	ds_read_b128 v[32:35], v97 offset:13248
	s_waitcnt lgkmcnt(0)
	v_mfma_f32_16x16x32_f16 v[28:31], v[32:35], v[0:3], v[28:31]
	v_mul_f32_e32 v32, 0x3db504f3, v16
	v_mul_f32_e32 v33, 0x3db504f3, v17
	v_max3_f32 v32, v32, s7, v33
	v_mul_f32_e32 v33, 0x3db504f3, v18
	v_mul_f32_e32 v34, 0x3db504f3, v19
	v_max3_f32 v32, v32, v33, v34
	v_mul_f32_e32 v33, 0x3db504f3, v20
	v_mul_f32_e32 v34, 0x3db504f3, v21
	v_max3_f32 v32, v32, v33, v34
	v_mul_f32_e32 v33, 0x3db504f3, v22
	v_mul_f32_e32 v34, 0x3db504f3, v23
	v_max3_f32 v32, v32, v33, v34
	v_mul_f32_e32 v33, 0x3db504f3, v24
	v_mul_f32_e32 v34, 0x3db504f3, v25
	v_max3_f32 v32, v32, v33, v34
	v_mul_f32_e32 v33, 0x3db504f3, v26
	v_mul_f32_e32 v34, 0x3db504f3, v27
	v_max3_f32 v32, v32, v33, v34
	v_mul_f32_e32 v33, 0x3db504f3, v28
	v_mul_f32_e32 v34, 0x3db504f3, v29
	v_max3_f32 v32, v32, v33, v34
	v_mul_f32_e32 v33, 0x3db504f3, v30
	v_mul_f32_e32 v34, 0x3db504f3, v31
	v_max3_f32 v32, v32, v33, v34
	ds_bpermute_b32 v33, v132, v32
	v_mfma_f32_16x16x32_f16 v[62:65], v[62:65], v[150:153], v[82:85]
	s_waitcnt lgkmcnt(0)
	v_max_f32_e32 v33, v33, v33
	v_max_f32_e32 v32, v32, v33
	ds_bpermute_b32 v33, v133, v32
	v_add_f32_e32 v85, v131, v114
	v_fmac_f32_e32 v85, v130, v112
	v_mfma_f32_16x16x32_f16 v[66:69], v[66:69], v[150:153], v[86:89]
	s_waitcnt lgkmcnt(0)
	v_max3_f32 v83, v113, v32, v33
	v_fma_f32 v16, v16, s6, -v83
	v_mul_f32_e32 v16, 0x3fb8aa3b, v16
	v_fma_f32 v17, v17, s6, -v83
	v_exp_f32_e32 v48, v16
	v_mul_f32_e32 v17, 0x3fb8aa3b, v17
	v_exp_f32_e32 v49, v17
	v_sub_f32_e32 v32, v113, v83
	v_add_f32_e32 v16, 0, v48
	v_mul_f32_e32 v32, 0x3fb8aa3b, v32
	v_add_f32_e32 v116, v49, v16
	v_fma_f32 v16, v18, s6, -v83
	v_mul_f32_e32 v16, 0x3fb8aa3b, v16
	v_exp_f32_e32 v100, v16
	v_fma_f32 v16, v19, s6, -v83
	v_mul_f32_e32 v16, 0x3fb8aa3b, v16
	v_exp_f32_e32 v102, v16
	v_fma_f32 v16, v20, s6, -v83
	v_mul_f32_e32 v16, 0x3fb8aa3b, v16
	v_exp_f32_e32 v104, v16
	v_fma_f32 v16, v21, s6, -v83
	v_mul_f32_e32 v16, 0x3fb8aa3b, v16
	v_exp_f32_e32 v106, v16
	v_fma_f32 v16, v22, s6, -v83
	v_mul_f32_e32 v16, 0x3fb8aa3b, v16
	v_exp_f32_e32 v108, v16
	v_fma_f32 v16, v23, s6, -v83
	v_mul_f32_e32 v16, 0x3fb8aa3b, v16
	v_exp_f32_e32 v110, v16
	v_fma_f32 v16, v24, s6, -v83
	v_mul_f32_e32 v16, 0x3fb8aa3b, v16
	v_exp_f32_e32 v112, v16
	v_fma_f32 v16, v25, s6, -v83
	v_mul_f32_e32 v16, 0x3fb8aa3b, v16
	v_exp_f32_e32 v114, v16
	v_fma_f32 v16, v26, s6, -v83
	v_mul_f32_e32 v16, 0x3fb8aa3b, v16
	v_exp_f32_e32 v82, v16
	v_fma_f32 v16, v27, s6, -v83
	v_mul_f32_e32 v16, 0x3fb8aa3b, v16
	v_exp_f32_e32 v84, v16
	v_fma_f32 v16, v28, s6, -v83
	v_mul_f32_e32 v16, 0x3fb8aa3b, v16
	v_exp_f32_e32 v86, v16
	v_fma_f32 v16, v29, s6, -v83
	v_mul_f32_e32 v16, 0x3fb8aa3b, v16
	v_exp_f32_e32 v88, v16
	v_fma_f32 v16, v30, s6, -v83
	v_mul_f32_e32 v16, 0x3fb8aa3b, v16
	v_exp_f32_e32 v90, v16
	v_fma_f32 v16, v31, s6, -v83
	v_mul_f32_e32 v16, 0x3fb8aa3b, v16
	v_exp_f32_e32 v96, v16
	v_exp_f32_e32 v16, v32
	v_cvt_pk_f16_f32 v23, v108, v110
	v_cvt_pk_f16_f32 v22, v104, v106
	v_cvt_pk_f16_f32 v21, v100, v102
	v_pk_mul_f32 v[46:47], v[56:57], v[16:17] op_sel_hi:[1,0]
	v_pk_mul_f32 v[44:45], v[54:55], v[16:17] op_sel_hi:[1,0]
	ds_read2_b64 v[54:57], v134 offset1:4
	v_pk_mul_f32 v[52:53], v[52:53], v[16:17] op_sel_hi:[1,0]
	v_pk_mul_f32 v[50:51], v[50:51], v[16:17] op_sel_hi:[1,0]
	v_cvt_pk_f16_f32 v20, v48, v49
	v_pk_mul_f32 v[42:43], v[60:61], v[16:17] op_sel_hi:[1,0]
	v_pk_mul_f32 v[40:41], v[58:59], v[16:17] op_sel_hi:[1,0]
	s_waitcnt lgkmcnt(0)
	v_mfma_f32_16x16x32_f16 v[48:51], v[54:57], v[20:23], v[50:53]
	s_nop 2
	ds_read2_b64 v[52:55], v135 offset0:32 offset1:36
	v_pk_mul_f32 v[38:39], v[64:65], v[16:17] op_sel_hi:[1,0]
	v_pk_mul_f32 v[36:37], v[62:63], v[16:17] op_sel_hi:[1,0]
	s_waitcnt lgkmcnt(0)
	v_mfma_f32_16x16x32_f16 v[44:47], v[52:55], v[20:23], v[44:47]
	ds_read2_b64 v[52:55], v136 offset0:64 offset1:68
	v_pk_mul_f32 v[34:35], v[68:69], v[16:17] op_sel_hi:[1,0]
	v_pk_mul_f32 v[32:33], v[66:67], v[16:17] op_sel_hi:[1,0]
	s_waitcnt lgkmcnt(0)
	v_mfma_f32_16x16x32_f16 v[40:43], v[52:55], v[20:23], v[40:43]
	ds_read2_b64 v[52:55], v137 offset0:96 offset1:100
	v_cvt_pk_f16_f32 v67, v90, v96
	v_cvt_pk_f16_f32 v66, v86, v88
	s_waitcnt lgkmcnt(0)
	v_mfma_f32_16x16x32_f16 v[36:39], v[52:55], v[20:23], v[36:39]
	ds_read2_b64 v[52:55], v138 offset0:128 offset1:132
	v_cvt_pk_f16_f32 v65, v82, v84
	v_cvt_pk_f16_f32 v64, v112, v114
	s_waitcnt lgkmcnt(0)
	v_mfma_f32_16x16x32_f16 v[32:35], v[52:55], v[20:23], v[32:35]
	ds_read2_b64 v[52:55], v139 offset0:160 offset1:164
	v_mul_f32_e32 v98, v85, v16
	v_mfma_f32_16x16x32_f16 v[70:73], v[70:73], v[150:153], v[126:129]
	v_mfma_f32_16x16x32_f16 v[74:77], v[74:77], v[150:153], v[142:145]
	v_mfma_f32_16x16x32_f16 v[78:81], v[78:81], v[150:153], v[146:149]
	s_nop 5
	v_mul_f32_e64 v30, v72, v16
	v_mul_f32_e64 v31, v73, v16
	v_pk_mul_f32 v[28:29], v[70:71], v[16:17] op_sel_hi:[1,0]
	v_pk_mul_f32 v[26:27], v[76:77], v[16:17] op_sel_hi:[1,0]
	v_pk_mul_f32 v[24:25], v[74:75], v[16:17] op_sel_hi:[1,0]
	s_waitcnt lgkmcnt(0)
	v_mfma_f32_16x16x32_f16 v[52:55], v[52:55], v[20:23], v[28:31]
	v_mul_f32_e64 v18, v80, v16
	v_mul_f32_e64 v19, v81, v16
	v_pk_mul_f32 v[16:17], v[78:79], v[16:17] op_sel_hi:[1,0]
	ds_read2_b64 v[28:31], v140 offset0:192 offset1:196
	s_waitcnt lgkmcnt(0)
	v_mfma_f32_16x16x32_f16 v[56:59], v[28:31], v[20:23], v[24:27]
	ds_read2_b64 v[28:31], v137 offset0:104 offset1:108
	s_nop 1
	ds_read2_b64 v[24:27], v141 offset0:224 offset1:228
	s_waitcnt lgkmcnt(1)
	v_mfma_f32_16x16x32_f16 v[28:31], v[28:31], v[64:67], v[36:39]
	s_nop 2
	ds_read2_b64 v[36:39], v138 offset0:136 offset1:140
	s_waitcnt lgkmcnt(1)
	v_mfma_f32_16x16x32_f16 v[60:63], v[24:27], v[20:23], v[16:19]
	ds_read2_b64 v[20:23], v135 offset0:40 offset1:44
	ds_read2_b64 v[24:27], v136 offset0:72 offset1:76
	s_nop 0
	ds_read2_b64 v[16:19], v134 offset0:8 offset1:12
	s_waitcnt lgkmcnt(3)
	v_mfma_f32_16x16x32_f16 v[32:35], v[36:39], v[64:67], v[32:35]
	ds_read2_b64 v[36:39], v139 offset0:168 offset1:172
	s_waitcnt lgkmcnt(1)
	v_mfma_f32_16x16x32_f16 v[16:19], v[16:19], v[64:67], v[48:51]
	v_mfma_f32_16x16x32_f16 v[20:23], v[20:23], v[64:67], v[44:47]
	v_mfma_f32_16x16x32_f16 v[24:27], v[24:27], v[64:67], v[40:43]
	s_nop 1
	ds_read2_b64 v[44:47], v141 offset0:232 offset1:236
	ds_read2_b64 v[40:43], v140 offset0:200 offset1:204
	s_waitcnt lgkmcnt(0)
	s_barrier
	ds_read_b128 v[48:51], v97 offset:17408
	v_mfma_f32_16x16x32_f16 v[36:39], v[36:39], v[64:67], v[52:55]
	s_nop 2
	ds_read_b128 v[52:55], v97 offset:17472
	s_waitcnt lgkmcnt(1)
	v_mfma_f32_16x16x32_f16 v[48:51], v[48:51], v[12:15], 0
	s_waitcnt lgkmcnt(0)
	v_mfma_f32_16x16x32_f16 v[48:51], v[52:55], v[8:11], v[48:51]
	ds_read_b128 v[52:55], v97 offset:17536
	v_mfma_f32_16x16x32_f16 v[40:43], v[40:43], v[64:67], v[56:59]
	s_nop 2
	ds_read_b128 v[56:59], v97 offset:21824
	s_waitcnt lgkmcnt(1)
	v_mfma_f32_16x16x32_f16 v[48:51], v[52:55], v[4:7], v[48:51]
	ds_read_b128 v[52:55], v97 offset:17600
	v_mfma_f32_16x16x32_f16 v[44:47], v[44:47], v[64:67], v[60:63]
	s_nop 2
	ds_read_b128 v[60:63], v97 offset:26176
	s_waitcnt lgkmcnt(1)
	v_mfma_f32_16x16x32_f16 v[48:51], v[52:55], v[0:3], v[48:51]
	ds_read_b128 v[52:55], v97 offset:21760
	s_waitcnt lgkmcnt(0)
	v_mfma_f32_16x16x32_f16 v[52:55], v[52:55], v[12:15], 0
	v_mfma_f32_16x16x32_f16 v[52:55], v[56:59], v[8:11], v[52:55]
	ds_read_b128 v[56:59], v97 offset:21888
	s_waitcnt lgkmcnt(0)
	v_mfma_f32_16x16x32_f16 v[52:55], v[56:59], v[4:7], v[52:55]
	ds_read_b128 v[56:59], v97 offset:21952
	s_waitcnt lgkmcnt(0)
	v_mfma_f32_16x16x32_f16 v[52:55], v[56:59], v[0:3], v[52:55]
	ds_read_b128 v[56:59], v97 offset:26112
	s_waitcnt lgkmcnt(0)
	v_mfma_f32_16x16x32_f16 v[56:59], v[56:59], v[12:15], 0
	v_mfma_f32_16x16x32_f16 v[56:59], v[60:63], v[8:11], v[56:59]
	ds_read_b128 v[60:63], v97 offset:26240
	s_waitcnt lgkmcnt(0)
	v_mfma_f32_16x16x32_f16 v[56:59], v[60:63], v[4:7], v[56:59]
	ds_read_b128 v[60:63], v97 offset:26304
	s_waitcnt lgkmcnt(0)
	v_mfma_f32_16x16x32_f16 v[58:61], v[60:63], v[0:3], v[56:59]
	ds_read_b128 v[62:65], v97 offset:30464
	s_waitcnt lgkmcnt(0)
	v_mfma_f32_16x16x32_f16 v[12:15], v[62:65], v[12:15], 0
	ds_read_b128 v[62:65], v97 offset:30528
	s_waitcnt lgkmcnt(0)
	v_mfma_f32_16x16x32_f16 v[8:11], v[62:65], v[8:11], v[12:15]
	s_nop 4
	ds_read_b128 v[12:15], v97 offset:30592
	s_waitcnt lgkmcnt(0)
	v_mfma_f32_16x16x32_f16 v[4:7], v[12:15], v[4:7], v[8:11]
	s_nop 2
	ds_read_b128 v[8:11], v97 offset:30656
	s_waitcnt lgkmcnt(0)
	v_mfma_f32_16x16x32_f16 v[0:3], v[8:11], v[0:3], v[4:7]
	s_nop 2
	v_mul_f32_e32 v4, 0x3db504f3, v48
	v_mul_f32_e32 v5, 0x3db504f3, v49
	v_max3_f32 v4, v4, s7, v5
	v_mul_f32_e32 v5, 0x3db504f3, v50
	v_mul_f32_e32 v6, 0x3db504f3, v51
	v_max3_f32 v4, v4, v5, v6
	v_mul_f32_e32 v5, 0x3db504f3, v52
	v_mul_f32_e32 v6, 0x3db504f3, v53
	v_max3_f32 v4, v4, v5, v6
	v_mul_f32_e32 v5, 0x3db504f3, v54
	v_mul_f32_e32 v6, 0x3db504f3, v55
	v_max3_f32 v4, v4, v5, v6
	v_mul_f32_e32 v5, 0x3db504f3, v58
	v_mul_f32_e32 v6, 0x3db504f3, v59
	v_max3_f32 v4, v4, v5, v6
	v_mul_f32_e32 v5, 0x3db504f3, v60
	v_mul_f32_e32 v6, 0x3db504f3, v61
	v_max3_f32 v4, v4, v5, v6
	v_mul_f32_e32 v5, 0x3db504f3, v0
	v_mul_f32_e32 v6, 0x3db504f3, v1
	v_max3_f32 v4, v4, v5, v6
	v_mul_f32_e32 v5, 0x3db504f3, v2
	v_mul_f32_e32 v6, 0x3db504f3, v3
	v_max3_f32 v4, v4, v5, v6
	ds_bpermute_b32 v5, v132, v4
	s_waitcnt lgkmcnt(0)
	v_max_f32_e32 v5, v5, v5
	v_max_f32_e32 v4, v4, v5
	ds_bpermute_b32 v5, v133, v4
	s_waitcnt lgkmcnt(0)
	v_max3_f32 v57, v83, v4, v5
	v_fma_f32 v7, v52, s6, -v57
	v_mul_f32_e32 v7, 0x3fb8aa3b, v7
	v_sub_f32_e32 v4, v83, v57
	v_exp_f32_e32 v109, v7
	v_fma_f32 v7, v53, s6, -v57
	v_mul_f32_e32 v6, 0x3fb8aa3b, v4
	v_fma_f32 v4, v48, s6, -v57
	v_mul_f32_e32 v7, 0x3fb8aa3b, v7
	v_mul_f32_e32 v4, 0x3fb8aa3b, v4
	v_exp_f32_e32 v111, v7
	v_fma_f32 v7, v54, s6, -v57
	v_exp_f32_e32 v56, v6
	v_exp_f32_e32 v101, v4
	v_fma_f32 v4, v49, s6, -v57
	v_mul_f32_e32 v7, 0x3fb8aa3b, v7
	v_mul_f32_e32 v4, 0x3fb8aa3b, v4
	v_exp_f32_e32 v113, v7
	v_fma_f32 v7, v55, s6, -v57
	v_exp_f32_e32 v103, v4
	v_fma_f32 v4, v50, s6, -v57
	v_mul_f32_e32 v7, 0x3fb8aa3b, v7
	v_mul_f32_e32 v4, 0x3fb8aa3b, v4
	v_exp_f32_e32 v115, v7
	v_fma_f32 v7, v58, s6, -v57
	v_fma_f32 v0, v0, s6, -v57
	v_pk_mul_f32 v[14:15], v[38:39], v[56:57] op_sel_hi:[1,0]
	v_pk_mul_f32 v[12:13], v[36:37], v[56:57] op_sel_hi:[1,0]
	ds_read2_b64 v[36:39], v120 offset0:64 offset1:68
	v_exp_f32_e32 v105, v4
	v_fma_f32 v4, v51, s6, -v57
	v_mul_f32_e32 v7, 0x3fb8aa3b, v7
	v_mul_f32_e32 v0, 0x3fb8aa3b, v0
	v_mul_f32_e32 v4, 0x3fb8aa3b, v4
	v_exp_f32_e32 v83, v7
	v_fma_f32 v7, v59, s6, -v57
	v_exp_f32_e32 v91, v0
	v_fma_f32 v0, v1, s6, -v57
	v_exp_f32_e32 v107, v4
	v_mul_f32_e32 v7, 0x3fb8aa3b, v7
	v_mul_f32_e32 v0, 0x3fb8aa3b, v0
	v_pk_add_f32 v[4:5], v[100:101], v[116:117]
	v_exp_f32_e32 v85, v7
	v_fma_f32 v7, v60, s6, -v57
	v_exp_f32_e32 v97, v0
	v_fma_f32 v0, v2, s6, -v57
	v_pk_add_f32 v[4:5], v[102:103], v[4:5]
	v_mul_f32_e32 v7, 0x3fb8aa3b, v7
	v_mul_f32_e32 v0, 0x3fb8aa3b, v0
	v_pk_add_f32 v[4:5], v[104:105], v[4:5]
	v_exp_f32_e32 v87, v7
	v_fma_f32 v7, v61, s6, -v57
	v_exp_f32_e32 v99, v0
	v_fma_f32 v0, v3, s6, -v57
	v_pk_add_f32 v[4:5], v[106:107], v[4:5]
	v_mul_f32_e32 v7, 0x3fb8aa3b, v7
	v_mul_f32_e32 v0, 0x3fb8aa3b, v0
	v_exp_f32_e32 v89, v7
	v_exp_f32_e32 v60, v0
	v_pk_add_f32 v[0:1], v[108:109], v[4:5]
	v_pk_mul_f32 v[26:27], v[26:27], v[56:57] op_sel_hi:[1,0]
	v_pk_mul_f32 v[24:25], v[24:25], v[56:57] op_sel_hi:[1,0]
	v_cvt_pk_f16_f32 v7, v113, v115
	v_cvt_pk_f16_f32 v6, v109, v111
	v_cvt_pk_f16_f32 v5, v105, v107
	v_cvt_pk_f16_f32 v4, v101, v103
	v_pk_mul_f32 v[50:51], v[22:23], v[56:57] op_sel_hi:[1,0]
	v_pk_mul_f32 v[48:49], v[20:21], v[56:57] op_sel_hi:[1,0]
	s_waitcnt lgkmcnt(0)
	v_mfma_f32_16x16x32_f16 v[36:39], v[36:39], v[4:7], v[24:27]
	v_mul_f32_e64 v22, v30, v56
	v_mul_f32_e64 v23, v31, v56
	v_pk_mul_f32 v[20:21], v[28:29], v[56:57] op_sel_hi:[1,0]
	v_pk_add_f32 v[0:1], v[110:111], v[0:1]
	ds_read2_b64 v[24:27], v121 offset0:96 offset1:100
	v_pk_mul_f32 v[10:11], v[42:43], v[56:57] op_sel_hi:[1,0]
	v_pk_mul_f32 v[8:9], v[40:41], v[56:57] op_sel_hi:[1,0]
	s_waitcnt lgkmcnt(0)
	v_mfma_f32_16x16x32_f16 v[40:43], v[24:27], v[4:7], v[20:23]
	s_nop 2
	ds_read2_b64 v[20:23], v122 offset0:128 offset1:132
	v_pk_add_f32 v[0:1], v[112:113], v[0:1]
	v_pk_mul_f32 v[54:55], v[18:19], v[56:57] op_sel_hi:[1,0]
	v_pk_add_f32 v[0:1], v[114:115], v[0:1]
	v_pk_mul_f32 v[52:53], v[16:17], v[56:57] op_sel_hi:[1,0]
	v_pk_add_f32 v[0:1], v[82:83], v[0:1]
	v_pk_mul_f32 v[18:19], v[34:35], v[56:57] op_sel_hi:[1,0]
	v_pk_add_f32 v[0:1], v[84:85], v[0:1]
	v_pk_mul_f32 v[16:17], v[32:33], v[56:57] op_sel_hi:[1,0]
	v_pk_add_f32 v[0:1], v[86:87], v[0:1]
	v_pk_mul_f32 v[2:3], v[46:47], v[56:57] op_sel_hi:[1,0]
	v_pk_add_f32 v[0:1], v[88:89], v[0:1]
	ds_read2_b64 v[32:35], v119 offset0:32 offset1:36
	v_pk_add_f32 v[0:1], v[90:91], v[0:1]
	ds_read2_b64 v[28:31], v118 offset1:4
	v_pk_add_f32 v[0:1], v[96:97], v[0:1]
	s_waitcnt lgkmcnt(1)
	v_mfma_f32_16x16x32_f16 v[32:35], v[32:35], v[4:7], v[48:51]
	v_add_f32_e64 v58, v98, v0
	v_add_f32_e64 v59, v99, v1
	v_pk_mul_f32 v[0:1], v[44:45], v[56:57] op_sel_hi:[1,0]
	v_cvt_pk_f16_f32 v65, v99, v60
	v_mfma_f32_16x16x32_f16 v[44:47], v[20:23], v[4:7], v[16:19]
	v_cvt_pk_f16_f32 v64, v91, v97
	v_cvt_pk_f16_f32 v63, v87, v89
	v_cvt_pk_f16_f32 v62, v83, v85
	ds_read2_b64 v[16:19], v123 offset0:160 offset1:164
	s_waitcnt lgkmcnt(0)
	v_mfma_f32_16x16x32_f16 v[48:51], v[16:19], v[4:7], v[12:15]
	s_nop 2
	ds_read2_b64 v[12:15], v124 offset0:192 offset1:196
	v_mfma_f32_16x16x32_f16 v[28:31], v[28:31], v[4:7], v[52:55]
	s_waitcnt lgkmcnt(0)
	v_mfma_f32_16x16x32_f16 v[52:55], v[12:15], v[4:7], v[8:11]
	s_nop 2
	ds_read2_b64 v[8:11], v125 offset0:224 offset1:228
	s_waitcnt lgkmcnt(0)
	v_mfma_f32_16x16x32_f16 v[0:3], v[8:11], v[4:7], v[0:3]
	ds_read2_b64 v[4:7], v118 offset0:8 offset1:12
	s_waitcnt lgkmcnt(0)
	v_mfma_f32_16x16x32_f16 v[28:31], v[4:7], v[62:65], v[28:31]
	ds_read2_b64 v[4:7], v119 offset0:40 offset1:44
	s_waitcnt lgkmcnt(0)
	v_mfma_f32_16x16x32_f16 v[24:27], v[4:7], v[62:65], v[32:35]
	ds_read2_b64 v[4:7], v120 offset0:72 offset1:76
	s_nop 1
	ds_read2_b64 v[32:35], v125 offset0:232 offset1:236
	s_waitcnt lgkmcnt(1)
	v_mfma_f32_16x16x32_f16 v[20:23], v[4:7], v[62:65], v[36:39]
	ds_read2_b64 v[4:7], v121 offset0:104 offset1:108
	s_waitcnt lgkmcnt(0)
	v_mfma_f32_16x16x32_f16 v[16:19], v[4:7], v[62:65], v[40:43]
	ds_read2_b64 v[4:7], v122 offset0:136 offset1:140
	v_mfma_f32_16x16x32_f16 v[0:3], v[32:35], v[62:65], v[0:3]
	v_add_f32_e32 v32, v59, v60
	v_fmac_f32_e32 v32, v58, v56
	ds_bpermute_b32 v33, v132, v32
	s_waitcnt lgkmcnt(1)
	v_mfma_f32_16x16x32_f16 v[12:15], v[4:7], v[62:65], v[44:47]
	ds_read2_b64 v[4:7], v123 offset0:168 offset1:172
	s_waitcnt lgkmcnt(1)
	v_add_f32_e32 v32, v32, v33
	ds_bpermute_b32 v33, v133, v32
	s_waitcnt lgkmcnt(1)
	v_mfma_f32_16x16x32_f16 v[8:11], v[4:7], v[62:65], v[48:51]
	ds_read2_b64 v[4:7], v124 offset0:200 offset1:204
	s_waitcnt lgkmcnt(0)
	s_barrier
	v_add_f32_e32 v32, v32, v33
	global_load_dword v33, v169, s[4:5]
	v_mfma_f32_16x16x32_f16 v[4:7], v[4:7], v[62:65], v[52:55]
	s_waitcnt vmcnt(0)
	v_sub_f32_e32 v33, v33, v57
	v_mul_f32_e32 v33, 0x3fb8aa3b, v33
	v_exp_f32_e32 v33, v33
	s_nop 0
	v_add_f32_e32 v32, v32, v33
	v_div_scale_f32 v33, s[4:5], v32, v32, 1.0
	v_rcp_f32_e32 v34, v33
	v_readlane_b32 s4, v254, 12
	v_readlane_b32 s5, v254, 13
	v_fma_f32 v35, -v33, v34, 1.0
	v_fmac_f32_e32 v34, v35, v34
	v_div_scale_f32 v35, vcc, 1.0, v32, 1.0
	v_mul_f32_e32 v36, v35, v34
	v_fma_f32 v37, -v33, v36, v35
	v_fmac_f32_e32 v36, v37, v34
	v_fma_f32 v33, -v33, v36, v35
	v_div_fmas_f32 v33, v33, v34, v36
	v_lshlrev_b64 v[34:35], 12, v[94:95]
	v_lshl_add_u64 v[34:35], s[4:5], 0, v[34:35]
	v_lshl_add_u64 v[36:37], v[34:35], 0, s[0:1]
	v_lshl_add_u64 v[34:35], v[92:93], 0, v[168:169]
	global_load_dwordx2 v[60:61], v[34:35], off offset:2048
	global_load_dwordx2 v[62:63], v[34:35], off offset:2080
	global_load_dwordx2 v[64:65], v[34:35], off offset:2112
	global_load_dwordx2 v[66:67], v[34:35], off offset:2144
	global_load_dwordx2 v[68:69], v[34:35], off offset:2176
	global_load_dwordx2 v[70:71], v[34:35], off offset:2208
	global_load_dwordx2 v[72:73], v[34:35], off offset:2240
	global_load_dwordx2 v[74:75], v[34:35], off offset:2272
	v_div_fixup_f32 v32, v33, v32, 1.0
	s_waitcnt vmcnt(7)
	v_cvt_f32_f16_sdwa v33, v60 dst_sel:DWORD dst_unused:UNUSED_PAD src0_sel:WORD_1
	v_cvt_f32_f16_e32 v38, v60
	v_mul_f32_e32 v41, 0xbfb8aa3b, v33
	v_mul_f32_e32 v40, 0xbfb8aa3b, v38
	v_exp_f32_e32 v40, v40
	v_exp_f32_e32 v41, v41
	v_pk_mul_f32 v[28:29], v[28:29], v[32:33] op_sel_hi:[1,0]
	v_pk_add_f32 v[40:41], v[40:41], 1.0 op_sel_hi:[1,0]
	s_nop 0
	v_div_scale_f32 v42, s[4:5], v41, v41, v33
	v_rcp_f32_e32 v43, v42
	s_nop 0
	v_fma_f32 v44, -v42, v43, 1.0
	v_fmac_f32_e32 v43, v44, v43
	v_div_scale_f32 v44, vcc, v33, v41, v33
	v_mul_f32_e32 v45, v44, v43
	v_fma_f32 v46, -v42, v45, v44
	v_fmac_f32_e32 v45, v46, v43
	v_fma_f32 v42, -v42, v45, v44
	v_div_fmas_f32 v42, v42, v43, v45
	v_div_fixup_f32 v41, v42, v41, v33
	v_div_scale_f32 v33, s[4:5], v40, v40, v38
	v_rcp_f32_e32 v42, v33
	s_nop 0
	v_fma_f32 v43, -v33, v42, 1.0
	v_fmac_f32_e32 v42, v43, v42
	v_div_scale_f32 v43, vcc, v38, v40, v38
	v_mul_f32_e32 v44, v43, v42
	v_fma_f32 v45, -v33, v44, v43
	v_fmac_f32_e32 v44, v45, v42
	v_fma_f32 v33, -v33, v44, v43
	v_div_fmas_f32 v33, v33, v42, v44
	v_div_fixup_f32 v40, v33, v40, v38
	v_cvt_f32_f16_sdwa v33, v61 dst_sel:DWORD dst_unused:UNUSED_PAD src0_sel:WORD_1
	v_cvt_f32_f16_e32 v39, v61
	v_pk_mul_f32 v[28:29], v[28:29], v[40:41]
	v_pk_mul_f32 v[30:31], v[30:31], v[32:33] op_sel_hi:[1,0]
	v_cvt_pk_f16_f32 v38, v28, v29
	v_mul_f32_e32 v28, 0xbfb8aa3b, v39
	v_mul_f32_e32 v29, 0xbfb8aa3b, v33
	v_exp_f32_e32 v28, v28
	v_exp_f32_e32 v29, v29
	s_nop 0
	v_pk_add_f32 v[28:29], v[28:29], 1.0 op_sel_hi:[1,0]
	s_nop 0
	v_div_scale_f32 v40, s[4:5], v29, v29, v33
	v_rcp_f32_e32 v41, v40
	s_nop 0
	v_fma_f32 v42, -v40, v41, 1.0
	v_fmac_f32_e32 v41, v42, v41
	v_div_scale_f32 v42, vcc, v33, v29, v33
	v_mul_f32_e32 v43, v42, v41
	v_fma_f32 v44, -v40, v43, v42
	v_fmac_f32_e32 v43, v44, v41
	v_fma_f32 v40, -v40, v43, v42
	v_div_fmas_f32 v40, v40, v41, v43
	v_div_fixup_f32 v29, v40, v29, v33
	v_div_scale_f32 v33, s[4:5], v28, v28, v39
	v_rcp_f32_e32 v40, v33
	s_nop 0
	v_fma_f32 v41, -v33, v40, 1.0
	v_fmac_f32_e32 v40, v41, v40
	v_div_scale_f32 v41, vcc, v39, v28, v39
	v_mul_f32_e32 v42, v41, v40
	v_fma_f32 v43, -v33, v42, v41
	v_fmac_f32_e32 v42, v43, v40
	v_fma_f32 v33, -v33, v42, v41
	v_div_fmas_f32 v33, v33, v40, v42
	v_div_fixup_f32 v28, v33, v28, v39
	v_pk_mul_f32 v[28:29], v[30:31], v[28:29]
	s_nop 0
	v_cvt_pk_f16_f32 v39, v28, v29
	v_lshl_add_u64 v[28:29], v[36:37], 0, v[168:169]
	global_store_dwordx2 v[28:29], v[38:39], off
	s_waitcnt vmcnt(7)
	v_cvt_f32_f16_sdwa v33, v62 dst_sel:DWORD dst_unused:UNUSED_PAD src0_sel:WORD_1
	v_cvt_f32_f16_e32 v30, v62
	v_mul_f32_e32 v37, 0xbfb8aa3b, v33
	v_mul_f32_e32 v36, 0xbfb8aa3b, v30
	v_exp_f32_e32 v36, v36
	v_exp_f32_e32 v37, v37
	v_pk_mul_f32 v[24:25], v[24:25], v[32:33] op_sel_hi:[1,0]
	v_pk_add_f32 v[36:37], v[36:37], 1.0 op_sel_hi:[1,0]
	s_nop 0
	v_div_scale_f32 v38, s[4:5], v37, v37, v33
	v_rcp_f32_e32 v39, v38
	s_nop 0
	v_fma_f32 v40, -v38, v39, 1.0
	v_fmac_f32_e32 v39, v40, v39
	v_div_scale_f32 v40, vcc, v33, v37, v33
	v_mul_f32_e32 v41, v40, v39
	v_fma_f32 v42, -v38, v41, v40
	v_fmac_f32_e32 v41, v42, v39
	v_fma_f32 v38, -v38, v41, v40
	v_div_fmas_f32 v38, v38, v39, v41
	v_div_fixup_f32 v37, v38, v37, v33
	v_div_scale_f32 v33, s[4:5], v36, v36, v30
	v_rcp_f32_e32 v38, v33
	s_nop 0
	v_fma_f32 v39, -v33, v38, 1.0
	v_fmac_f32_e32 v38, v39, v38
	v_div_scale_f32 v39, vcc, v30, v36, v30
	v_mul_f32_e32 v40, v39, v38
	v_fma_f32 v41, -v33, v40, v39
	v_fmac_f32_e32 v40, v41, v38
	v_fma_f32 v33, -v33, v40, v39
	v_div_fmas_f32 v33, v33, v38, v40
	v_div_fixup_f32 v36, v33, v36, v30
	v_pk_mul_f32 v[24:25], v[24:25], v[36:37]
	v_cvt_f32_f16_e32 v33, v63
	v_cvt_pk_f16_f32 v24, v24, v25
	v_cvt_f32_f16_sdwa v25, v63 dst_sel:DWORD dst_unused:UNUSED_PAD src0_sel:WORD_1
	v_mul_f32_e32 v30, 0xbfb8aa3b, v33
	v_exp_f32_e32 v30, v30
	v_mul_f32_e32 v31, 0xbfb8aa3b, v25
	v_exp_f32_e32 v31, v31
	v_pk_mul_f32 v[26:27], v[26:27], v[32:33] op_sel_hi:[1,0]
	v_pk_mul_f32 v[20:21], v[20:21], v[32:33] op_sel_hi:[1,0]
	v_pk_add_f32 v[30:31], v[30:31], 1.0 op_sel_hi:[1,0]
	s_nop 0
	v_div_scale_f32 v36, s[4:5], v31, v31, v25
	v_rcp_f32_e32 v37, v36
	s_nop 0
	v_fma_f32 v38, -v36, v37, 1.0
	v_fmac_f32_e32 v37, v38, v37
	v_div_scale_f32 v38, vcc, v25, v31, v25
	v_mul_f32_e32 v39, v38, v37
	v_fma_f32 v40, -v36, v39, v38
	v_fmac_f32_e32 v39, v40, v37
	v_fma_f32 v36, -v36, v39, v38
	v_div_fmas_f32 v36, v36, v37, v39
	v_div_fixup_f32 v31, v36, v31, v25
	v_div_scale_f32 v25, s[4:5], v30, v30, v33
	v_rcp_f32_e32 v36, v25
	s_nop 0
	v_fma_f32 v37, -v25, v36, 1.0
	v_fmac_f32_e32 v36, v37, v36
	v_div_scale_f32 v37, vcc, v33, v30, v33
	v_mul_f32_e32 v38, v37, v36
	v_fma_f32 v39, -v25, v38, v37
	v_fmac_f32_e32 v38, v39, v36
	v_fma_f32 v25, -v25, v38, v37
	v_div_fmas_f32 v25, v25, v36, v38
	v_div_fixup_f32 v30, v25, v30, v33
	v_pk_mul_f32 v[26:27], v[26:27], v[30:31]
	s_nop 0
	v_cvt_pk_f16_f32 v25, v26, v27
	global_store_dwordx2 v[28:29], v[24:25], off offset:32
	s_waitcnt vmcnt(7)
	v_cvt_f32_f16_sdwa v30, v64 dst_sel:DWORD dst_unused:UNUSED_PAD src0_sel:WORD_1
	v_cvt_f32_f16_e32 v24, v64
	v_mul_f32_e32 v27, 0xbfb8aa3b, v30
	v_mul_f32_e32 v26, 0xbfb8aa3b, v24
	v_exp_f32_e32 v26, v26
	v_exp_f32_e32 v27, v27
	s_nop 0
	v_pk_add_f32 v[26:27], v[26:27], 1.0 op_sel_hi:[1,0]
	s_nop 0
	v_div_scale_f32 v31, s[4:5], v27, v27, v30
	v_rcp_f32_e32 v33, v31
	s_nop 0
	v_fma_f32 v36, -v31, v33, 1.0
	v_fmac_f32_e32 v33, v36, v33
	v_div_scale_f32 v36, vcc, v30, v27, v30
	v_mul_f32_e32 v37, v36, v33
	v_fma_f32 v38, -v31, v37, v36
	v_fmac_f32_e32 v37, v38, v33
	v_fma_f32 v31, -v31, v37, v36
	v_div_fmas_f32 v31, v31, v33, v37
	v_div_fixup_f32 v27, v31, v27, v30
	v_div_scale_f32 v30, s[4:5], v26, v26, v24
	v_rcp_f32_e32 v31, v30
	s_nop 0
	v_fma_f32 v33, -v30, v31, 1.0
	v_fmac_f32_e32 v31, v33, v31
	v_div_scale_f32 v33, vcc, v24, v26, v24
	v_mul_f32_e32 v36, v33, v31
	v_fma_f32 v37, -v30, v36, v33
	v_fmac_f32_e32 v36, v37, v31
	v_fma_f32 v30, -v30, v36, v33
	v_div_fmas_f32 v30, v30, v31, v36
	v_div_fixup_f32 v26, v30, v26, v24
	v_pk_mul_f32 v[20:21], v[20:21], v[26:27]
	v_cvt_f32_f16_e32 v26, v65
	v_cvt_pk_f16_f32 v20, v20, v21
	v_cvt_f32_f16_sdwa v21, v65 dst_sel:DWORD dst_unused:UNUSED_PAD src0_sel:WORD_1
	v_pk_mul_f32 v[22:23], v[22:23], v[32:33] op_sel_hi:[1,0]
	v_mul_f32_e32 v24, 0xbfb8aa3b, v26
	v_exp_f32_e32 v24, v24
	v_mul_f32_e32 v25, 0xbfb8aa3b, v21
	v_exp_f32_e32 v25, v25
	s_nop 0
	v_pk_add_f32 v[24:25], v[24:25], 1.0 op_sel_hi:[1,0]
	s_nop 0
	v_div_scale_f32 v27, s[4:5], v25, v25, v21
	v_rcp_f32_e32 v30, v27
	s_nop 0
	v_fma_f32 v31, -v27, v30, 1.0
	v_fmac_f32_e32 v30, v31, v30
	v_div_scale_f32 v31, vcc, v21, v25, v21
	v_mul_f32_e32 v33, v31, v30
	v_fma_f32 v36, -v27, v33, v31
	v_fmac_f32_e32 v33, v36, v30
	v_fma_f32 v27, -v27, v33, v31
	v_div_fmas_f32 v27, v27, v30, v33
	v_div_fixup_f32 v25, v27, v25, v21
	v_div_scale_f32 v21, s[4:5], v24, v24, v26
	v_rcp_f32_e32 v27, v21
	s_nop 0
	v_fma_f32 v30, -v21, v27, 1.0
	v_fmac_f32_e32 v27, v30, v27
	v_div_scale_f32 v30, vcc, v26, v24, v26
	v_mul_f32_e32 v31, v30, v27
	v_fma_f32 v33, -v21, v31, v30
	v_fmac_f32_e32 v31, v33, v27
	v_fma_f32 v21, -v21, v31, v30
	v_div_fmas_f32 v21, v21, v27, v31
	v_div_fixup_f32 v24, v21, v24, v26
	v_pk_mul_f32 v[22:23], v[22:23], v[24:25]
	v_pk_mul_f32 v[16:17], v[16:17], v[32:33] op_sel_hi:[1,0]
	v_cvt_pk_f16_f32 v21, v22, v23
	global_store_dwordx2 v[28:29], v[20:21], off offset:64
	v_pk_mul_f32 v[18:19], v[18:19], v[32:33] op_sel_hi:[1,0]
	v_pk_mul_f32 v[12:13], v[12:13], v[32:33] op_sel_hi:[1,0]
	v_pk_mul_f32 v[14:15], v[14:15], v[32:33] op_sel_hi:[1,0]
	v_pk_mul_f32 v[8:9], v[8:9], v[32:33] op_sel_hi:[1,0]
	v_pk_mul_f32 v[10:11], v[10:11], v[32:33] op_sel_hi:[1,0]
	v_pk_mul_f32 v[4:5], v[4:5], v[32:33] op_sel_hi:[1,0]
	v_pk_mul_f32 v[6:7], v[6:7], v[32:33] op_sel_hi:[1,0]
	v_pk_mul_f32 v[0:1], v[0:1], v[32:33] op_sel_hi:[1,0]
	v_pk_mul_f32 v[2:3], v[2:3], v[32:33] op_sel_hi:[1,0]
	s_waitcnt vmcnt(7)
	v_cvt_f32_f16_sdwa v24, v66 dst_sel:DWORD dst_unused:UNUSED_PAD src0_sel:WORD_1
	v_cvt_f32_f16_e32 v20, v66
	v_mul_f32_e32 v23, 0xbfb8aa3b, v24
	v_mul_f32_e32 v22, 0xbfb8aa3b, v20
	v_exp_f32_e32 v22, v22
	v_exp_f32_e32 v23, v23
	s_nop 0
	v_pk_add_f32 v[22:23], v[22:23], 1.0 op_sel_hi:[1,0]
	s_nop 0
	v_div_scale_f32 v25, s[4:5], v23, v23, v24
	v_rcp_f32_e32 v26, v25
	s_nop 0
	v_fma_f32 v27, -v25, v26, 1.0
	v_fmac_f32_e32 v26, v27, v26
	v_div_scale_f32 v27, vcc, v24, v23, v24
	v_mul_f32_e32 v30, v27, v26
	v_fma_f32 v31, -v25, v30, v27
	v_fmac_f32_e32 v30, v31, v26
	v_fma_f32 v25, -v25, v30, v27
	v_div_fmas_f32 v25, v25, v26, v30
	v_div_fixup_f32 v23, v25, v23, v24
	v_div_scale_f32 v24, s[4:5], v22, v22, v20
	v_rcp_f32_e32 v25, v24
	s_nop 0
	v_fma_f32 v26, -v24, v25, 1.0
	v_fmac_f32_e32 v25, v26, v25
	v_div_scale_f32 v26, vcc, v20, v22, v20
	v_mul_f32_e32 v27, v26, v25
	v_fma_f32 v30, -v24, v27, v26
	v_fmac_f32_e32 v27, v30, v25
	v_fma_f32 v24, -v24, v27, v26
	v_div_fmas_f32 v24, v24, v25, v27
	v_div_fixup_f32 v22, v24, v22, v20
	v_pk_mul_f32 v[16:17], v[16:17], v[22:23]
	v_cvt_f32_f16_e32 v22, v67
	v_cvt_pk_f16_f32 v16, v16, v17
	v_cvt_f32_f16_sdwa v17, v67 dst_sel:DWORD dst_unused:UNUSED_PAD src0_sel:WORD_1
	v_mul_f32_e32 v20, 0xbfb8aa3b, v22
	v_exp_f32_e32 v20, v20
	v_mul_f32_e32 v21, 0xbfb8aa3b, v17
	v_exp_f32_e32 v21, v21
	s_nop 0
	v_pk_add_f32 v[20:21], v[20:21], 1.0 op_sel_hi:[1,0]
	s_nop 0
	v_div_scale_f32 v23, s[4:5], v21, v21, v17
	v_rcp_f32_e32 v24, v23
	s_nop 0
	v_fma_f32 v25, -v23, v24, 1.0
	v_fmac_f32_e32 v24, v25, v24
	v_div_scale_f32 v25, vcc, v17, v21, v17
	v_mul_f32_e32 v26, v25, v24
	v_fma_f32 v27, -v23, v26, v25
	v_fmac_f32_e32 v26, v27, v24
	v_fma_f32 v23, -v23, v26, v25
	v_div_fmas_f32 v23, v23, v24, v26
	v_div_fixup_f32 v21, v23, v21, v17
	v_div_scale_f32 v17, s[4:5], v20, v20, v22
	v_rcp_f32_e32 v23, v17
	s_nop 0
	v_fma_f32 v24, -v17, v23, 1.0
	v_fmac_f32_e32 v23, v24, v23
	v_div_scale_f32 v24, vcc, v22, v20, v22
	v_mul_f32_e32 v25, v24, v23
	v_fma_f32 v26, -v17, v25, v24
	v_fmac_f32_e32 v25, v26, v23
	v_fma_f32 v17, -v17, v25, v24
	v_div_fmas_f32 v17, v17, v23, v25
	v_div_fixup_f32 v20, v17, v20, v22
	v_pk_mul_f32 v[18:19], v[18:19], v[20:21]
	s_nop 0
	v_cvt_pk_f16_f32 v17, v18, v19
	global_store_dwordx2 v[28:29], v[16:17], off offset:96
	s_waitcnt vmcnt(7)
	v_cvt_f32_f16_sdwa v20, v68 dst_sel:DWORD dst_unused:UNUSED_PAD src0_sel:WORD_1
	v_cvt_f32_f16_e32 v16, v68
	v_mul_f32_e32 v19, 0xbfb8aa3b, v20
	v_mul_f32_e32 v18, 0xbfb8aa3b, v16
	v_exp_f32_e32 v18, v18
	v_exp_f32_e32 v19, v19
	s_nop 0
	v_pk_add_f32 v[18:19], v[18:19], 1.0 op_sel_hi:[1,0]
	s_nop 0
	v_div_scale_f32 v21, s[4:5], v19, v19, v20
	v_rcp_f32_e32 v22, v21
	s_nop 0
	v_fma_f32 v23, -v21, v22, 1.0
	v_fmac_f32_e32 v22, v23, v22
	v_div_scale_f32 v23, vcc, v20, v19, v20
	v_mul_f32_e32 v24, v23, v22
	v_fma_f32 v25, -v21, v24, v23
	v_fmac_f32_e32 v24, v25, v22
	v_fma_f32 v21, -v21, v24, v23
	v_div_fmas_f32 v21, v21, v22, v24
	v_div_fixup_f32 v19, v21, v19, v20
	v_div_scale_f32 v20, s[4:5], v18, v18, v16
	v_rcp_f32_e32 v21, v20
	s_nop 0
	v_fma_f32 v22, -v20, v21, 1.0
	v_fmac_f32_e32 v21, v22, v21
	v_div_scale_f32 v22, vcc, v16, v18, v16
	v_mul_f32_e32 v23, v22, v21
	v_fma_f32 v24, -v20, v23, v22
	v_fmac_f32_e32 v23, v24, v21
	v_fma_f32 v20, -v20, v23, v22
	v_div_fmas_f32 v20, v20, v21, v23
	v_div_fixup_f32 v18, v20, v18, v16
	v_pk_mul_f32 v[12:13], v[12:13], v[18:19]
	v_cvt_f32_f16_e32 v18, v69
	v_cvt_pk_f16_f32 v12, v12, v13
	v_cvt_f32_f16_sdwa v13, v69 dst_sel:DWORD dst_unused:UNUSED_PAD src0_sel:WORD_1
	v_mul_f32_e32 v16, 0xbfb8aa3b, v18
	v_exp_f32_e32 v16, v16
	v_mul_f32_e32 v17, 0xbfb8aa3b, v13
	v_exp_f32_e32 v17, v17
	s_nop 0
	v_pk_add_f32 v[16:17], v[16:17], 1.0 op_sel_hi:[1,0]
	s_nop 0
	v_div_scale_f32 v19, s[4:5], v17, v17, v13
	v_rcp_f32_e32 v20, v19
	s_nop 0
	v_fma_f32 v21, -v19, v20, 1.0
	v_fmac_f32_e32 v20, v21, v20
	v_div_scale_f32 v21, vcc, v13, v17, v13
	v_mul_f32_e32 v22, v21, v20
	v_fma_f32 v23, -v19, v22, v21
	v_fmac_f32_e32 v22, v23, v20
	v_fma_f32 v19, -v19, v22, v21
	v_div_fmas_f32 v19, v19, v20, v22
	v_div_fixup_f32 v17, v19, v17, v13
	v_div_scale_f32 v13, s[4:5], v16, v16, v18
	v_rcp_f32_e32 v19, v13
	s_nop 0
	v_fma_f32 v20, -v13, v19, 1.0
	v_fmac_f32_e32 v19, v20, v19
	v_div_scale_f32 v20, vcc, v18, v16, v18
	v_mul_f32_e32 v21, v20, v19
	v_fma_f32 v22, -v13, v21, v20
	v_fmac_f32_e32 v21, v22, v19
	v_fma_f32 v13, -v13, v21, v20
	v_div_fmas_f32 v13, v13, v19, v21
	v_div_fixup_f32 v16, v13, v16, v18
	v_pk_mul_f32 v[14:15], v[14:15], v[16:17]
	s_nop 0
	v_cvt_pk_f16_f32 v13, v14, v15
	global_store_dwordx2 v[28:29], v[12:13], off offset:128
	s_waitcnt vmcnt(7)
	v_cvt_f32_f16_sdwa v16, v70 dst_sel:DWORD dst_unused:UNUSED_PAD src0_sel:WORD_1
	v_cvt_f32_f16_e32 v12, v70
	v_mul_f32_e32 v15, 0xbfb8aa3b, v16
	v_mul_f32_e32 v14, 0xbfb8aa3b, v12
	v_exp_f32_e32 v14, v14
	v_exp_f32_e32 v15, v15
	s_nop 0
	v_pk_add_f32 v[14:15], v[14:15], 1.0 op_sel_hi:[1,0]
	s_nop 0
	v_div_scale_f32 v17, s[4:5], v15, v15, v16
	v_rcp_f32_e32 v18, v17
	s_nop 0
	v_fma_f32 v19, -v17, v18, 1.0
	v_fmac_f32_e32 v18, v19, v18
	v_div_scale_f32 v19, vcc, v16, v15, v16
	v_mul_f32_e32 v20, v19, v18
	v_fma_f32 v21, -v17, v20, v19
	v_fmac_f32_e32 v20, v21, v18
	v_fma_f32 v17, -v17, v20, v19
	v_div_fmas_f32 v17, v17, v18, v20
	v_div_fixup_f32 v15, v17, v15, v16
	v_div_scale_f32 v16, s[4:5], v14, v14, v12
	v_rcp_f32_e32 v17, v16
	s_nop 0
	v_fma_f32 v18, -v16, v17, 1.0
	v_fmac_f32_e32 v17, v18, v17
	v_div_scale_f32 v18, vcc, v12, v14, v12
	v_mul_f32_e32 v19, v18, v17
	v_fma_f32 v20, -v16, v19, v18
	v_fmac_f32_e32 v19, v20, v17
	v_fma_f32 v16, -v16, v19, v18
	v_div_fmas_f32 v16, v16, v17, v19
	v_div_fixup_f32 v14, v16, v14, v12
	v_pk_mul_f32 v[8:9], v[8:9], v[14:15]
	v_cvt_f32_f16_e32 v14, v71
	v_cvt_pk_f16_f32 v8, v8, v9
	v_cvt_f32_f16_sdwa v9, v71 dst_sel:DWORD dst_unused:UNUSED_PAD src0_sel:WORD_1
	v_mul_f32_e32 v12, 0xbfb8aa3b, v14
	v_exp_f32_e32 v12, v12
	v_mul_f32_e32 v13, 0xbfb8aa3b, v9
	v_exp_f32_e32 v13, v13
	s_nop 0
	v_pk_add_f32 v[12:13], v[12:13], 1.0 op_sel_hi:[1,0]
	s_nop 0
	v_div_scale_f32 v15, s[4:5], v13, v13, v9
	v_rcp_f32_e32 v16, v15
	s_nop 0
	v_fma_f32 v17, -v15, v16, 1.0
	v_fmac_f32_e32 v16, v17, v16
	v_div_scale_f32 v17, vcc, v9, v13, v9
	v_mul_f32_e32 v18, v17, v16
	v_fma_f32 v19, -v15, v18, v17
	v_fmac_f32_e32 v18, v19, v16
	v_fma_f32 v15, -v15, v18, v17
	v_div_fmas_f32 v15, v15, v16, v18
	v_div_fixup_f32 v13, v15, v13, v9
	v_div_scale_f32 v9, s[4:5], v12, v12, v14
	v_rcp_f32_e32 v15, v9
	s_nop 0
	v_fma_f32 v16, -v9, v15, 1.0
	v_fmac_f32_e32 v15, v16, v15
	v_div_scale_f32 v16, vcc, v14, v12, v14
	v_mul_f32_e32 v17, v16, v15
	v_fma_f32 v18, -v9, v17, v16
	v_fmac_f32_e32 v17, v18, v15
	v_fma_f32 v9, -v9, v17, v16
	v_div_fmas_f32 v9, v9, v15, v17
	v_div_fixup_f32 v12, v9, v12, v14
	v_pk_mul_f32 v[10:11], v[10:11], v[12:13]
	s_nop 0
	v_cvt_pk_f16_f32 v9, v10, v11
	global_store_dwordx2 v[28:29], v[8:9], off offset:160
	s_waitcnt vmcnt(7)
	v_cvt_f32_f16_sdwa v12, v72 dst_sel:DWORD dst_unused:UNUSED_PAD src0_sel:WORD_1
	v_cvt_f32_f16_e32 v8, v72
	v_mul_f32_e32 v11, 0xbfb8aa3b, v12
	v_mul_f32_e32 v10, 0xbfb8aa3b, v8
	v_exp_f32_e32 v10, v10
	v_exp_f32_e32 v11, v11
	s_nop 0
	v_pk_add_f32 v[10:11], v[10:11], 1.0 op_sel_hi:[1,0]
	s_nop 0
	v_div_scale_f32 v13, s[4:5], v11, v11, v12
	v_rcp_f32_e32 v14, v13
	s_nop 0
	v_fma_f32 v15, -v13, v14, 1.0
	v_fmac_f32_e32 v14, v15, v14
	v_div_scale_f32 v15, vcc, v12, v11, v12
	v_mul_f32_e32 v16, v15, v14
	v_fma_f32 v17, -v13, v16, v15
	v_fmac_f32_e32 v16, v17, v14
	v_fma_f32 v13, -v13, v16, v15
	v_div_fmas_f32 v13, v13, v14, v16
	v_div_fixup_f32 v11, v13, v11, v12
	v_div_scale_f32 v12, s[4:5], v10, v10, v8
	v_rcp_f32_e32 v13, v12
	s_nop 0
	v_fma_f32 v14, -v12, v13, 1.0
	v_fmac_f32_e32 v13, v14, v13
	v_div_scale_f32 v14, vcc, v8, v10, v8
	v_mul_f32_e32 v15, v14, v13
	v_fma_f32 v16, -v12, v15, v14
	v_fmac_f32_e32 v15, v16, v13
	v_fma_f32 v12, -v12, v15, v14
	v_div_fmas_f32 v12, v12, v13, v15
	v_div_fixup_f32 v10, v12, v10, v8
	v_pk_mul_f32 v[4:5], v[4:5], v[10:11]
	v_cvt_f32_f16_e32 v10, v73
	v_cvt_pk_f16_f32 v4, v4, v5
	v_cvt_f32_f16_sdwa v5, v73 dst_sel:DWORD dst_unused:UNUSED_PAD src0_sel:WORD_1
	v_mul_f32_e32 v8, 0xbfb8aa3b, v10
	v_exp_f32_e32 v8, v8
	v_mul_f32_e32 v9, 0xbfb8aa3b, v5
	v_exp_f32_e32 v9, v9
	s_nop 0
	v_pk_add_f32 v[8:9], v[8:9], 1.0 op_sel_hi:[1,0]
	s_nop 0
	v_div_scale_f32 v11, s[4:5], v9, v9, v5
	v_rcp_f32_e32 v12, v11
	s_nop 0
	v_fma_f32 v13, -v11, v12, 1.0
	v_fmac_f32_e32 v12, v13, v12
	v_div_scale_f32 v13, vcc, v5, v9, v5
	v_mul_f32_e32 v14, v13, v12
	v_fma_f32 v15, -v11, v14, v13
	v_fmac_f32_e32 v14, v15, v12
	v_fma_f32 v11, -v11, v14, v13
	v_div_fmas_f32 v11, v11, v12, v14
	v_div_fixup_f32 v9, v11, v9, v5
	v_div_scale_f32 v5, s[4:5], v8, v8, v10
	v_rcp_f32_e32 v11, v5
	s_nop 0
	v_fma_f32 v12, -v5, v11, 1.0
	v_fmac_f32_e32 v11, v12, v11
	v_div_scale_f32 v12, vcc, v10, v8, v10
	v_mul_f32_e32 v13, v12, v11
	v_fma_f32 v14, -v5, v13, v12
	v_fmac_f32_e32 v13, v14, v11
	v_fma_f32 v5, -v5, v13, v12
	v_div_fmas_f32 v5, v5, v11, v13
	v_div_fixup_f32 v8, v5, v8, v10
	v_pk_mul_f32 v[6:7], v[6:7], v[8:9]
	s_nop 0
	v_cvt_pk_f16_f32 v5, v6, v7
	global_store_dwordx2 v[28:29], v[4:5], off offset:192
	s_waitcnt vmcnt(7)
	v_cvt_f32_f16_sdwa v8, v74 dst_sel:DWORD dst_unused:UNUSED_PAD src0_sel:WORD_1
	v_cvt_f32_f16_e32 v4, v74
	v_mul_f32_e32 v7, 0xbfb8aa3b, v8
	v_mul_f32_e32 v6, 0xbfb8aa3b, v4
	v_exp_f32_e32 v6, v6
	v_exp_f32_e32 v7, v7
	s_nop 0
	v_pk_add_f32 v[6:7], v[6:7], 1.0 op_sel_hi:[1,0]
	s_nop 0
	v_div_scale_f32 v9, s[4:5], v7, v7, v8
	v_rcp_f32_e32 v10, v9
	s_nop 0
	v_fma_f32 v11, -v9, v10, 1.0
	v_fmac_f32_e32 v10, v11, v10
	v_div_scale_f32 v11, vcc, v8, v7, v8
	v_mul_f32_e32 v12, v11, v10
	v_fma_f32 v13, -v9, v12, v11
	v_fmac_f32_e32 v12, v13, v10
	v_fma_f32 v9, -v9, v12, v11
	v_div_fmas_f32 v9, v9, v10, v12
	v_div_fixup_f32 v7, v9, v7, v8
	v_div_scale_f32 v8, s[4:5], v6, v6, v4
	v_rcp_f32_e32 v9, v8
	s_nop 0
	v_fma_f32 v10, -v8, v9, 1.0
	v_fmac_f32_e32 v9, v10, v9
	v_div_scale_f32 v10, vcc, v4, v6, v4
	v_mul_f32_e32 v11, v10, v9
	v_fma_f32 v12, -v8, v11, v10
	v_fmac_f32_e32 v11, v12, v9
	v_fma_f32 v8, -v8, v11, v10
	v_div_fmas_f32 v8, v8, v9, v11
	v_div_fixup_f32 v6, v8, v6, v4
	v_pk_mul_f32 v[0:1], v[0:1], v[6:7]
	v_cvt_f32_f16_e32 v6, v75
	v_cvt_pk_f16_f32 v0, v0, v1
	v_cvt_f32_f16_sdwa v1, v75 dst_sel:DWORD dst_unused:UNUSED_PAD src0_sel:WORD_1
	v_mul_f32_e32 v4, 0xbfb8aa3b, v6
	v_exp_f32_e32 v4, v4
	v_mul_f32_e32 v5, 0xbfb8aa3b, v1
	v_exp_f32_e32 v5, v5
	s_nop 0
	v_pk_add_f32 v[4:5], v[4:5], 1.0 op_sel_hi:[1,0]
	s_nop 0
	v_div_scale_f32 v7, s[4:5], v5, v5, v1
	v_rcp_f32_e32 v8, v7
	s_nop 0
	v_fma_f32 v9, -v7, v8, 1.0
	v_fmac_f32_e32 v8, v9, v8
	v_div_scale_f32 v9, vcc, v1, v5, v1
	v_mul_f32_e32 v10, v9, v8
	v_fma_f32 v11, -v7, v10, v9
	v_fmac_f32_e32 v10, v11, v8
	v_fma_f32 v7, -v7, v10, v9
	v_div_fmas_f32 v7, v7, v8, v10
	v_div_fixup_f32 v5, v7, v5, v1
	v_div_scale_f32 v1, s[4:5], v4, v4, v6
	v_rcp_f32_e32 v7, v1
	s_nop 0
	v_fma_f32 v8, -v1, v7, 1.0
	v_fmac_f32_e32 v7, v8, v7
	v_div_scale_f32 v8, vcc, v6, v4, v6
	v_mul_f32_e32 v9, v8, v7
	v_fma_f32 v10, -v1, v9, v8
	v_fmac_f32_e32 v9, v10, v7
	v_fma_f32 v1, -v1, v9, v8
	v_div_fmas_f32 v1, v1, v7, v9
	v_div_fixup_f32 v4, v1, v4, v6
	v_pk_mul_f32 v[2:3], v[2:3], v[4:5]
	s_nop 0
	v_cvt_pk_f16_f32 v1, v2, v3
	global_store_dwordx2 v[28:29], v[0:1], off offset:224

.LBB0_193:
	v_cmp_lt_i32_e32 vcc, v97, v99
	v_readlane_b32 s0, v255, 47
	s_or_b32 s4, s40, s0
	v_cndmask_b32_e32 v28, v81, v97, vcc
	v_lshlrev_b32_e32 v28, 2, v28
	ds_bpermute_b32 v28, v28, v131
	v_cmp_lt_i32_e32 vcc, v108, v99
	s_ashr_i32 s5, s4, 31
	s_lshl_b64 s[4:5], s[4:5], 2
	v_cndmask_b32_e32 v29, v81, v108, vcc
	s_waitcnt lgkmcnt(0)
	v_add_f32_e32 v28, v131, v28
	v_lshlrev_b32_e32 v29, 2, v29
	ds_bpermute_b32 v29, v29, v28
	v_readlane_b32 s44, v253, 32
	v_readlane_b32 s45, v253, 33
	s_add_u32 s4, s44, s4
	s_addc_u32 s5, s45, s5
	s_waitcnt lgkmcnt(0)
	v_add_f32_e32 v28, v28, v29
	global_load_dword v29, v169, s[4:5]
	v_mov_b32_e32 v81, v169
	s_lshl_b32 s0, s9, 1
	v_mov_b32_e32 v91, v169
	v_mov_b32_e32 v89, v169
	v_mov_b32_e32 v87, v169
	v_readlane_b32 s46, v253, 34
	v_readlane_b32 s47, v253, 35
	v_readlane_b32 s48, v253, 36
	v_readlane_b32 s49, v253, 37
	v_readlane_b32 s50, v253, 38
	v_readlane_b32 s51, v253, 39
	v_readlane_b32 s52, v253, 40
	v_readlane_b32 s53, v253, 41
	v_readlane_b32 s54, v253, 42
	v_readlane_b32 s55, v253, 43
	v_readlane_b32 s56, v253, 44
	v_readlane_b32 s57, v253, 45
	v_readlane_b32 s58, v253, 46
	v_readlane_b32 s59, v253, 47
	s_waitcnt vmcnt(0)
	v_sub_f32_e32 v29, v29, v95
	v_mul_f32_e32 v29, 0x3fb8aa3b, v29
	v_exp_f32_e32 v29, v29
	s_nop 0
	v_add_f32_e32 v28, v28, v29
	v_div_scale_f32 v29, s[4:5], v28, v28, 1.0
	v_rcp_f32_e32 v30, v29
	v_readlane_b32 s4, v254, 12
	v_readlane_b32 s5, v254, 13
	v_fma_f32 v31, -v29, v30, 1.0
	v_fmac_f32_e32 v30, v31, v30
	v_div_scale_f32 v31, vcc, 1.0, v28, 1.0
	v_mul_f32_e32 v32, v31, v30
	v_fma_f32 v33, -v29, v32, v31
	v_fmac_f32_e32 v32, v33, v30
	v_fma_f32 v29, -v29, v32, v31
	v_div_fmas_f32 v29, v29, v30, v32
	v_lshlrev_b64 v[30:31], 12, v[92:93]
	v_lshl_add_u64 v[30:31], s[4:5], 0, v[30:31]
	v_lshlrev_b64 v[32:33], 1, v[80:81]
	v_lshl_add_u64 v[34:35], v[30:31], 0, s[0:1]
	v_lshl_add_u64 v[30:31], v[84:85], 0, v[32:33]
	global_load_dwordx2 v[36:37], v[30:31], off offset:2048
	v_div_fixup_f32 v28, v29, v28, 1.0
	v_lshl_add_u64 v[32:33], v[34:35], 0, v[32:33]
	s_waitcnt vmcnt(0)
	v_cvt_f32_f16_sdwa v29, v36 dst_sel:DWORD dst_unused:UNUSED_PAD src0_sel:WORD_1
	v_cvt_f32_f16_e32 v36, v36
	v_mul_f32_e32 v39, 0xbfb8aa3b, v29
	v_mul_f32_e32 v38, 0xbfb8aa3b, v36
	v_exp_f32_e32 v38, v38
	v_exp_f32_e32 v39, v39
	v_pk_mul_f32 v[40:41], v[44:45], v[28:29] op_sel_hi:[1,0]
	v_pk_add_f32 v[38:39], v[38:39], 1.0 op_sel_hi:[1,0]
	s_nop 0
	v_div_scale_f32 v42, s[4:5], v39, v39, v29
	v_rcp_f32_e32 v43, v42
	s_nop 0
	v_fma_f32 v44, -v42, v43, 1.0
	v_fmac_f32_e32 v43, v44, v43
	v_div_scale_f32 v44, vcc, v29, v39, v29
	v_mul_f32_e32 v45, v44, v43
	v_fma_f32 v48, -v42, v45, v44
	v_fmac_f32_e32 v45, v48, v43
	v_fma_f32 v42, -v42, v45, v44
	v_div_fmas_f32 v42, v42, v43, v45
	v_div_fixup_f32 v39, v42, v39, v29
	v_div_scale_f32 v29, s[4:5], v38, v38, v36
	v_rcp_f32_e32 v42, v29
	s_nop 0
	v_fma_f32 v43, -v29, v42, 1.0
	v_fmac_f32_e32 v42, v43, v42
	v_div_scale_f32 v43, vcc, v36, v38, v36
	v_mul_f32_e32 v44, v43, v42
	v_fma_f32 v45, -v29, v44, v43
	v_fmac_f32_e32 v44, v45, v42
	v_fma_f32 v29, -v29, v44, v43
	v_div_fmas_f32 v29, v29, v42, v44
	v_div_fixup_f32 v38, v29, v38, v36
	v_cvt_f32_f16_sdwa v29, v37 dst_sel:DWORD dst_unused:UNUSED_PAD src0_sel:WORD_1
	v_cvt_f32_f16_e32 v37, v37
	v_pk_mul_f32 v[38:39], v[40:41], v[38:39]
	v_mul_f32_e32 v41, 0xbfb8aa3b, v29
	v_cvt_pk_f16_f32 v36, v38, v39
	v_mul_f32_e32 v38, 0xbfb8aa3b, v37
	v_exp_f32_e32 v40, v38
	v_exp_f32_e32 v41, v41
	v_pk_mul_f32 v[38:39], v[46:47], v[28:29] op_sel_hi:[1,0]
	v_pk_add_f32 v[40:41], v[40:41], 1.0 op_sel_hi:[1,0]
	s_nop 0
	v_div_scale_f32 v42, s[4:5], v41, v41, v29
	v_rcp_f32_e32 v43, v42
	s_nop 0
	v_fma_f32 v44, -v42, v43, 1.0
	v_fmac_f32_e32 v43, v44, v43
	v_div_scale_f32 v44, vcc, v29, v41, v29
	v_mul_f32_e32 v45, v44, v43
	v_fma_f32 v46, -v42, v45, v44
	v_fmac_f32_e32 v45, v46, v43
	v_fma_f32 v42, -v42, v45, v44
	v_div_fmas_f32 v42, v42, v43, v45
	v_div_fixup_f32 v41, v42, v41, v29
	v_div_scale_f32 v29, s[4:5], v40, v40, v37
	v_rcp_f32_e32 v42, v29
	s_nop 0
	v_fma_f32 v43, -v29, v42, 1.0
	v_fmac_f32_e32 v42, v43, v42
	v_div_scale_f32 v43, vcc, v37, v40, v37
	v_mul_f32_e32 v44, v43, v42
	v_fma_f32 v45, -v29, v44, v43
	v_fmac_f32_e32 v44, v45, v42
	v_fma_f32 v29, -v29, v44, v43
	v_div_fmas_f32 v29, v29, v42, v44
	v_div_fixup_f32 v40, v29, v40, v37
	v_pk_mul_f32 v[38:39], v[38:39], v[40:41]
	s_nop 0
	v_cvt_pk_f16_f32 v37, v38, v39
	global_store_dwordx2 v[32:33], v[36:37], off
	v_lshlrev_b64 v[36:37], 1, v[90:91]
	v_lshl_add_u64 v[38:39], v[84:85], 0, v[36:37]
	global_load_dwordx2 v[38:39], v[38:39], off offset:2048
	s_waitcnt vmcnt(0)
	v_cvt_f32_f16_sdwa v29, v38 dst_sel:DWORD dst_unused:UNUSED_PAD src0_sel:WORD_1
	v_cvt_f32_f16_e32 v38, v38
	v_mul_f32_e32 v41, 0xbfb8aa3b, v29
	v_mul_f32_e32 v40, 0xbfb8aa3b, v38
	v_exp_f32_e32 v40, v40
	v_exp_f32_e32 v41, v41
	v_pk_mul_f32 v[24:25], v[24:25], v[28:29] op_sel_hi:[1,0]
	v_pk_add_f32 v[40:41], v[40:41], 1.0 op_sel_hi:[1,0]
	s_nop 0
	v_div_scale_f32 v42, s[4:5], v41, v41, v29
	v_rcp_f32_e32 v43, v42
	s_nop 0
	v_fma_f32 v44, -v42, v43, 1.0
	v_fmac_f32_e32 v43, v44, v43
	v_div_scale_f32 v44, vcc, v29, v41, v29
	v_mul_f32_e32 v45, v44, v43
	v_fma_f32 v46, -v42, v45, v44
	v_fmac_f32_e32 v45, v46, v43
	v_fma_f32 v42, -v42, v45, v44
	v_div_fmas_f32 v42, v42, v43, v45
	v_div_fixup_f32 v41, v42, v41, v29
	v_div_scale_f32 v29, s[4:5], v40, v40, v38
	v_rcp_f32_e32 v42, v29
	s_nop 0
	v_fma_f32 v43, -v29, v42, 1.0
	v_fmac_f32_e32 v42, v43, v42
	v_div_scale_f32 v43, vcc, v38, v40, v38
	v_mul_f32_e32 v44, v43, v42
	v_fma_f32 v45, -v29, v44, v43
	v_fmac_f32_e32 v44, v45, v42
	v_fma_f32 v29, -v29, v44, v43
	v_div_fmas_f32 v29, v29, v42, v44
	v_div_fixup_f32 v40, v29, v40, v38
	v_pk_mul_f32 v[24:25], v[24:25], v[40:41]
	v_cvt_f32_f16_e32 v29, v39
	v_cvt_pk_f16_f32 v24, v24, v25
	v_cvt_f32_f16_sdwa v25, v39 dst_sel:DWORD dst_unused:UNUSED_PAD src0_sel:WORD_1
	v_mul_f32_e32 v38, 0xbfb8aa3b, v29
	v_exp_f32_e32 v38, v38
	v_mul_f32_e32 v39, 0xbfb8aa3b, v25
	v_exp_f32_e32 v39, v39
	v_pk_mul_f32 v[26:27], v[26:27], v[28:29] op_sel_hi:[1,0]
	v_pk_add_f32 v[38:39], v[38:39], 1.0 op_sel_hi:[1,0]
	s_nop 0
	v_div_scale_f32 v40, s[4:5], v39, v39, v25
	v_rcp_f32_e32 v41, v40
	s_nop 0
	v_fma_f32 v42, -v40, v41, 1.0
	v_fmac_f32_e32 v41, v42, v41
	v_div_scale_f32 v42, vcc, v25, v39, v25
	v_mul_f32_e32 v43, v42, v41
	v_fma_f32 v44, -v40, v43, v42
	v_fmac_f32_e32 v43, v44, v41
	v_fma_f32 v40, -v40, v43, v42
	v_div_fmas_f32 v40, v40, v41, v43
	v_div_fixup_f32 v39, v40, v39, v25
	v_div_scale_f32 v25, s[4:5], v38, v38, v29
	v_rcp_f32_e32 v40, v25
	s_nop 0
	v_fma_f32 v41, -v25, v40, 1.0
	v_fmac_f32_e32 v40, v41, v40
	v_div_scale_f32 v41, vcc, v29, v38, v29
	v_mul_f32_e32 v42, v41, v40
	v_fma_f32 v43, -v25, v42, v41
	v_fmac_f32_e32 v42, v43, v40
	v_fma_f32 v25, -v25, v42, v41
	v_div_fmas_f32 v25, v25, v40, v42
	v_div_fixup_f32 v38, v25, v38, v29
	v_pk_mul_f32 v[26:27], v[26:27], v[38:39]
	s_nop 0
	v_cvt_pk_f16_f32 v25, v26, v27
	v_lshl_add_u64 v[26:27], v[34:35], 0, v[36:37]
	global_store_dwordx2 v[26:27], v[24:25], off
	v_lshlrev_b64 v[24:25], 1, v[88:89]
	v_lshl_add_u64 v[26:27], v[84:85], 0, v[24:25]
	global_load_dwordx2 v[26:27], v[26:27], off offset:2048
	s_waitcnt vmcnt(0)
	v_cvt_f32_f16_sdwa v29, v26 dst_sel:DWORD dst_unused:UNUSED_PAD src0_sel:WORD_1
	v_cvt_f32_f16_e32 v26, v26
	v_mul_f32_e32 v37, 0xbfb8aa3b, v29
	v_mul_f32_e32 v36, 0xbfb8aa3b, v26
	v_exp_f32_e32 v36, v36
	v_exp_f32_e32 v37, v37
	v_pk_mul_f32 v[20:21], v[20:21], v[28:29] op_sel_hi:[1,0]
	v_pk_add_f32 v[36:37], v[36:37], 1.0 op_sel_hi:[1,0]
	s_nop 0
	v_div_scale_f32 v38, s[4:5], v37, v37, v29
	v_rcp_f32_e32 v39, v38
	s_nop 0
	v_fma_f32 v40, -v38, v39, 1.0
	v_fmac_f32_e32 v39, v40, v39
	v_div_scale_f32 v40, vcc, v29, v37, v29
	v_mul_f32_e32 v41, v40, v39
	v_fma_f32 v42, -v38, v41, v40
	v_fmac_f32_e32 v41, v42, v39
	v_fma_f32 v38, -v38, v41, v40
	v_div_fmas_f32 v38, v38, v39, v41
	v_div_fixup_f32 v37, v38, v37, v29
	v_div_scale_f32 v29, s[4:5], v36, v36, v26
	v_rcp_f32_e32 v38, v29
	s_nop 0
	v_fma_f32 v39, -v29, v38, 1.0
	v_fmac_f32_e32 v38, v39, v38
	v_div_scale_f32 v39, vcc, v26, v36, v26
	v_mul_f32_e32 v40, v39, v38
	v_fma_f32 v41, -v29, v40, v39
	v_fmac_f32_e32 v40, v41, v38
	v_fma_f32 v29, -v29, v40, v39
	v_div_fmas_f32 v29, v29, v38, v40
	v_div_fixup_f32 v36, v29, v36, v26
	v_pk_mul_f32 v[20:21], v[20:21], v[36:37]
	v_cvt_f32_f16_e32 v29, v27
	v_cvt_pk_f16_f32 v20, v20, v21
	v_cvt_f32_f16_sdwa v21, v27 dst_sel:DWORD dst_unused:UNUSED_PAD src0_sel:WORD_1
	v_mul_f32_e32 v26, 0xbfb8aa3b, v29
	v_exp_f32_e32 v26, v26
	v_mul_f32_e32 v27, 0xbfb8aa3b, v21
	v_exp_f32_e32 v27, v27
	v_pk_mul_f32 v[22:23], v[22:23], v[28:29] op_sel_hi:[1,0]
	v_pk_mul_f32 v[16:17], v[16:17], v[28:29] op_sel_hi:[1,0]
	v_pk_add_f32 v[26:27], v[26:27], 1.0 op_sel_hi:[1,0]
	s_nop 0
	v_div_scale_f32 v36, s[4:5], v27, v27, v21
	v_rcp_f32_e32 v37, v36
	s_nop 0
	v_fma_f32 v38, -v36, v37, 1.0
	v_fmac_f32_e32 v37, v38, v37
	v_div_scale_f32 v38, vcc, v21, v27, v21
	v_mul_f32_e32 v39, v38, v37
	v_fma_f32 v40, -v36, v39, v38
	v_fmac_f32_e32 v39, v40, v37
	v_fma_f32 v36, -v36, v39, v38
	v_div_fmas_f32 v36, v36, v37, v39
	v_div_fixup_f32 v27, v36, v27, v21
	v_div_scale_f32 v21, s[4:5], v26, v26, v29
	v_rcp_f32_e32 v36, v21
	s_nop 0
	v_fma_f32 v37, -v21, v36, 1.0
	v_fmac_f32_e32 v36, v37, v36
	v_div_scale_f32 v37, vcc, v29, v26, v29
	v_mul_f32_e32 v38, v37, v36
	v_fma_f32 v39, -v21, v38, v37
	v_fmac_f32_e32 v38, v39, v36
	v_fma_f32 v21, -v21, v38, v37
	v_div_fmas_f32 v21, v21, v36, v38
	v_div_fixup_f32 v26, v21, v26, v29
	v_pk_mul_f32 v[22:23], v[22:23], v[26:27]
	s_nop 0
	v_cvt_pk_f16_f32 v21, v22, v23
	v_lshl_add_u64 v[22:23], v[34:35], 0, v[24:25]
	global_store_dwordx2 v[22:23], v[20:21], off
	v_lshlrev_b64 v[20:21], 1, v[86:87]
	v_lshl_add_u64 v[22:23], v[84:85], 0, v[20:21]
	global_load_dwordx2 v[22:23], v[22:23], off offset:2048
	s_waitcnt vmcnt(0)
	v_cvt_f32_f16_sdwa v26, v22 dst_sel:DWORD dst_unused:UNUSED_PAD src0_sel:WORD_1
	v_cvt_f32_f16_e32 v22, v22
	v_mul_f32_e32 v25, 0xbfb8aa3b, v26
	v_mul_f32_e32 v24, 0xbfb8aa3b, v22
	v_exp_f32_e32 v24, v24
	v_exp_f32_e32 v25, v25
	s_nop 0
	v_pk_add_f32 v[24:25], v[24:25], 1.0 op_sel_hi:[1,0]
	s_nop 0
	v_div_scale_f32 v27, s[4:5], v25, v25, v26
	v_rcp_f32_e32 v29, v27
	s_nop 0
	v_fma_f32 v36, -v27, v29, 1.0
	v_fmac_f32_e32 v29, v36, v29
	v_div_scale_f32 v36, vcc, v26, v25, v26
	v_mul_f32_e32 v37, v36, v29
	v_fma_f32 v38, -v27, v37, v36
	v_fmac_f32_e32 v37, v38, v29
	v_fma_f32 v27, -v27, v37, v36
	v_div_fmas_f32 v27, v27, v29, v37
	v_div_fixup_f32 v25, v27, v25, v26
	v_div_scale_f32 v26, s[4:5], v24, v24, v22
	v_rcp_f32_e32 v27, v26
	s_nop 0
	v_fma_f32 v29, -v26, v27, 1.0
	v_fmac_f32_e32 v27, v29, v27
	v_div_scale_f32 v29, vcc, v22, v24, v22
	v_mul_f32_e32 v36, v29, v27
	v_fma_f32 v37, -v26, v36, v29
	v_fmac_f32_e32 v36, v37, v27
	v_fma_f32 v26, -v26, v36, v29
	v_div_fmas_f32 v26, v26, v27, v36
	v_div_fixup_f32 v24, v26, v24, v22
	v_pk_mul_f32 v[16:17], v[16:17], v[24:25]
	v_cvt_f32_f16_e32 v24, v23
	v_cvt_pk_f16_f32 v16, v16, v17
	v_cvt_f32_f16_sdwa v17, v23 dst_sel:DWORD dst_unused:UNUSED_PAD src0_sel:WORD_1
	v_pk_mul_f32 v[18:19], v[18:19], v[28:29] op_sel_hi:[1,0]
	v_mul_f32_e32 v22, 0xbfb8aa3b, v24
	v_exp_f32_e32 v22, v22
	v_mul_f32_e32 v23, 0xbfb8aa3b, v17
	v_exp_f32_e32 v23, v23
	s_nop 0
	v_pk_add_f32 v[22:23], v[22:23], 1.0 op_sel_hi:[1,0]
	s_nop 0
	v_div_scale_f32 v25, s[4:5], v23, v23, v17
	v_rcp_f32_e32 v26, v25
	s_nop 0
	v_fma_f32 v27, -v25, v26, 1.0
	v_fmac_f32_e32 v26, v27, v26
	v_div_scale_f32 v27, vcc, v17, v23, v17
	v_mul_f32_e32 v29, v27, v26
	v_fma_f32 v36, -v25, v29, v27
	v_fmac_f32_e32 v29, v36, v26
	v_fma_f32 v25, -v25, v29, v27
	v_div_fmas_f32 v25, v25, v26, v29
	v_div_fixup_f32 v23, v25, v23, v17
	v_div_scale_f32 v17, s[4:5], v22, v22, v24
	v_rcp_f32_e32 v25, v17
	s_nop 0
	v_fma_f32 v26, -v17, v25, 1.0
	v_fmac_f32_e32 v25, v26, v25
	v_div_scale_f32 v26, vcc, v24, v22, v24
	v_mul_f32_e32 v27, v26, v25
	v_fma_f32 v29, -v17, v27, v26
	v_fmac_f32_e32 v27, v29, v25
	v_fma_f32 v17, -v17, v27, v26
	v_div_fmas_f32 v17, v17, v25, v27
	v_div_fixup_f32 v22, v17, v22, v24
	v_pk_mul_f32 v[18:19], v[18:19], v[22:23]
	v_pk_mul_f32 v[12:13], v[12:13], v[28:29] op_sel_hi:[1,0]
	v_cvt_pk_f16_f32 v17, v18, v19
	v_lshl_add_u64 v[18:19], v[34:35], 0, v[20:21]
	global_load_dwordx2 v[60:61], v[30:31], off offset:2176
	global_load_dwordx2 v[62:63], v[30:31], off offset:2208
	global_load_dwordx2 v[64:65], v[30:31], off offset:2240
	global_load_dwordx2 v[66:67], v[30:31], off offset:2272
	global_store_dwordx2 v[18:19], v[16:17], off
	v_pk_mul_f32 v[14:15], v[14:15], v[28:29] op_sel_hi:[1,0]
	v_pk_mul_f32 v[8:9], v[8:9], v[28:29] op_sel_hi:[1,0]
	v_pk_mul_f32 v[10:11], v[10:11], v[28:29] op_sel_hi:[1,0]
	v_pk_mul_f32 v[4:5], v[4:5], v[28:29] op_sel_hi:[1,0]
	v_pk_mul_f32 v[6:7], v[6:7], v[28:29] op_sel_hi:[1,0]
	v_pk_mul_f32 v[0:1], v[0:1], v[28:29] op_sel_hi:[1,0]
	v_pk_mul_f32 v[2:3], v[2:3], v[28:29] op_sel_hi:[1,0]
	s_waitcnt vmcnt(4)
	v_cvt_f32_f16_sdwa v20, v60 dst_sel:DWORD dst_unused:UNUSED_PAD src0_sel:WORD_1
	v_cvt_f32_f16_e32 v16, v60
	v_mul_f32_e32 v19, 0xbfb8aa3b, v20
	v_mul_f32_e32 v18, 0xbfb8aa3b, v16
	v_exp_f32_e32 v18, v18
	v_exp_f32_e32 v19, v19
	s_nop 0
	v_pk_add_f32 v[18:19], v[18:19], 1.0 op_sel_hi:[1,0]
	s_nop 0
	v_div_scale_f32 v21, s[4:5], v19, v19, v20
	v_rcp_f32_e32 v22, v21
	s_nop 0
	v_fma_f32 v23, -v21, v22, 1.0
	v_fmac_f32_e32 v22, v23, v22
	v_div_scale_f32 v23, vcc, v20, v19, v20
	v_mul_f32_e32 v24, v23, v22
	v_fma_f32 v25, -v21, v24, v23
	v_fmac_f32_e32 v24, v25, v22
	v_fma_f32 v21, -v21, v24, v23
	v_div_fmas_f32 v21, v21, v22, v24
	v_div_fixup_f32 v19, v21, v19, v20
	v_div_scale_f32 v20, s[4:5], v18, v18, v16
	v_rcp_f32_e32 v21, v20
	s_nop 0
	v_fma_f32 v22, -v20, v21, 1.0
	v_fmac_f32_e32 v21, v22, v21
	v_div_scale_f32 v22, vcc, v16, v18, v16
	v_mul_f32_e32 v23, v22, v21
	v_fma_f32 v24, -v20, v23, v22
	v_fmac_f32_e32 v23, v24, v21
	v_fma_f32 v20, -v20, v23, v22
	v_div_fmas_f32 v20, v20, v21, v23
	v_div_fixup_f32 v18, v20, v18, v16
	v_pk_mul_f32 v[12:13], v[12:13], v[18:19]
	v_cvt_f32_f16_e32 v18, v61
	v_cvt_pk_f16_f32 v12, v12, v13
	v_cvt_f32_f16_sdwa v13, v61 dst_sel:DWORD dst_unused:UNUSED_PAD src0_sel:WORD_1
	v_mul_f32_e32 v16, 0xbfb8aa3b, v18
	v_exp_f32_e32 v16, v16
	v_mul_f32_e32 v17, 0xbfb8aa3b, v13
	v_exp_f32_e32 v17, v17
	s_nop 0
	v_pk_add_f32 v[16:17], v[16:17], 1.0 op_sel_hi:[1,0]
	s_nop 0
	v_div_scale_f32 v19, s[4:5], v17, v17, v13
	v_rcp_f32_e32 v20, v19
	s_nop 0
	v_fma_f32 v21, -v19, v20, 1.0
	v_fmac_f32_e32 v20, v21, v20
	v_div_scale_f32 v21, vcc, v13, v17, v13
	v_mul_f32_e32 v22, v21, v20
	v_fma_f32 v23, -v19, v22, v21
	v_fmac_f32_e32 v22, v23, v20
	v_fma_f32 v19, -v19, v22, v21
	v_div_fmas_f32 v19, v19, v20, v22
	v_div_fixup_f32 v17, v19, v17, v13
	v_div_scale_f32 v13, s[4:5], v16, v16, v18
	v_rcp_f32_e32 v19, v13
	s_nop 0
	v_fma_f32 v20, -v13, v19, 1.0
	v_fmac_f32_e32 v19, v20, v19
	v_div_scale_f32 v20, vcc, v18, v16, v18
	v_mul_f32_e32 v21, v20, v19
	v_fma_f32 v22, -v13, v21, v20
	v_fmac_f32_e32 v21, v22, v19
	v_fma_f32 v13, -v13, v21, v20
	v_div_fmas_f32 v13, v13, v19, v21
	v_div_fixup_f32 v16, v13, v16, v18
	v_pk_mul_f32 v[14:15], v[14:15], v[16:17]
	s_nop 0
	v_cvt_pk_f16_f32 v13, v14, v15
	global_store_dwordx2 v[32:33], v[12:13], off offset:128
	s_waitcnt vmcnt(4)
	v_cvt_f32_f16_sdwa v16, v62 dst_sel:DWORD dst_unused:UNUSED_PAD src0_sel:WORD_1
	v_cvt_f32_f16_e32 v12, v62
	v_mul_f32_e32 v15, 0xbfb8aa3b, v16
	v_mul_f32_e32 v14, 0xbfb8aa3b, v12
	v_exp_f32_e32 v14, v14
	v_exp_f32_e32 v15, v15
	s_nop 0
	v_pk_add_f32 v[14:15], v[14:15], 1.0 op_sel_hi:[1,0]
	s_nop 0
	v_div_scale_f32 v17, s[4:5], v15, v15, v16
	v_rcp_f32_e32 v18, v17
	s_nop 0
	v_fma_f32 v19, -v17, v18, 1.0
	v_fmac_f32_e32 v18, v19, v18
	v_div_scale_f32 v19, vcc, v16, v15, v16
	v_mul_f32_e32 v20, v19, v18
	v_fma_f32 v21, -v17, v20, v19
	v_fmac_f32_e32 v20, v21, v18
	v_fma_f32 v17, -v17, v20, v19
	v_div_fmas_f32 v17, v17, v18, v20
	v_div_fixup_f32 v15, v17, v15, v16
	v_div_scale_f32 v16, s[4:5], v14, v14, v12
	v_rcp_f32_e32 v17, v16
	s_nop 0
	v_fma_f32 v18, -v16, v17, 1.0
	v_fmac_f32_e32 v17, v18, v17
	v_div_scale_f32 v18, vcc, v12, v14, v12
	v_mul_f32_e32 v19, v18, v17
	v_fma_f32 v20, -v16, v19, v18
	v_fmac_f32_e32 v19, v20, v17
	v_fma_f32 v16, -v16, v19, v18
	v_div_fmas_f32 v16, v16, v17, v19
	v_div_fixup_f32 v14, v16, v14, v12
	v_pk_mul_f32 v[8:9], v[8:9], v[14:15]
	v_cvt_f32_f16_e32 v14, v63
	v_cvt_pk_f16_f32 v8, v8, v9
	v_cvt_f32_f16_sdwa v9, v63 dst_sel:DWORD dst_unused:UNUSED_PAD src0_sel:WORD_1
	v_mul_f32_e32 v12, 0xbfb8aa3b, v14
	v_exp_f32_e32 v12, v12
	v_mul_f32_e32 v13, 0xbfb8aa3b, v9
	v_exp_f32_e32 v13, v13
	s_nop 0
	v_pk_add_f32 v[12:13], v[12:13], 1.0 op_sel_hi:[1,0]
	s_nop 0
	v_div_scale_f32 v15, s[4:5], v13, v13, v9
	v_rcp_f32_e32 v16, v15
	s_nop 0
	v_fma_f32 v17, -v15, v16, 1.0
	v_fmac_f32_e32 v16, v17, v16
	v_div_scale_f32 v17, vcc, v9, v13, v9
	v_mul_f32_e32 v18, v17, v16
	v_fma_f32 v19, -v15, v18, v17
	v_fmac_f32_e32 v18, v19, v16
	v_fma_f32 v15, -v15, v18, v17
	v_div_fmas_f32 v15, v15, v16, v18
	v_div_fixup_f32 v13, v15, v13, v9
	v_div_scale_f32 v9, s[4:5], v12, v12, v14
	v_rcp_f32_e32 v15, v9
	s_nop 0
	v_fma_f32 v16, -v9, v15, 1.0
	v_fmac_f32_e32 v15, v16, v15
	v_div_scale_f32 v16, vcc, v14, v12, v14
	v_mul_f32_e32 v17, v16, v15
	v_fma_f32 v18, -v9, v17, v16
	v_fmac_f32_e32 v17, v18, v15
	v_fma_f32 v9, -v9, v17, v16
	v_div_fmas_f32 v9, v9, v15, v17
	v_div_fixup_f32 v12, v9, v12, v14
	v_pk_mul_f32 v[10:11], v[10:11], v[12:13]
	s_nop 0
	v_cvt_pk_f16_f32 v9, v10, v11
	global_store_dwordx2 v[32:33], v[8:9], off offset:160
	s_waitcnt vmcnt(4)
	v_cvt_f32_f16_sdwa v12, v64 dst_sel:DWORD dst_unused:UNUSED_PAD src0_sel:WORD_1
	v_cvt_f32_f16_e32 v8, v64
	v_mul_f32_e32 v11, 0xbfb8aa3b, v12
	v_mul_f32_e32 v10, 0xbfb8aa3b, v8
	v_exp_f32_e32 v10, v10
	v_exp_f32_e32 v11, v11
	s_nop 0
	v_pk_add_f32 v[10:11], v[10:11], 1.0 op_sel_hi:[1,0]
	s_nop 0
	v_div_scale_f32 v13, s[4:5], v11, v11, v12
	v_rcp_f32_e32 v14, v13
	s_nop 0
	v_fma_f32 v15, -v13, v14, 1.0
	v_fmac_f32_e32 v14, v15, v14
	v_div_scale_f32 v15, vcc, v12, v11, v12
	v_mul_f32_e32 v16, v15, v14
	v_fma_f32 v17, -v13, v16, v15
	v_fmac_f32_e32 v16, v17, v14
	v_fma_f32 v13, -v13, v16, v15
	v_div_fmas_f32 v13, v13, v14, v16
	v_div_fixup_f32 v11, v13, v11, v12
	v_div_scale_f32 v12, s[4:5], v10, v10, v8
	v_rcp_f32_e32 v13, v12
	s_nop 0
	v_fma_f32 v14, -v12, v13, 1.0
	v_fmac_f32_e32 v13, v14, v13
	v_div_scale_f32 v14, vcc, v8, v10, v8
	v_mul_f32_e32 v15, v14, v13
	v_fma_f32 v16, -v12, v15, v14
	v_fmac_f32_e32 v15, v16, v13
	v_fma_f32 v12, -v12, v15, v14
	v_div_fmas_f32 v12, v12, v13, v15
	v_div_fixup_f32 v10, v12, v10, v8
	v_pk_mul_f32 v[4:5], v[4:5], v[10:11]
	v_cvt_f32_f16_e32 v10, v65
	v_cvt_pk_f16_f32 v4, v4, v5
	v_cvt_f32_f16_sdwa v5, v65 dst_sel:DWORD dst_unused:UNUSED_PAD src0_sel:WORD_1
	v_mul_f32_e32 v8, 0xbfb8aa3b, v10
	v_exp_f32_e32 v8, v8
	v_mul_f32_e32 v9, 0xbfb8aa3b, v5
	v_exp_f32_e32 v9, v9
	s_nop 0
	v_pk_add_f32 v[8:9], v[8:9], 1.0 op_sel_hi:[1,0]
	s_nop 0
	v_div_scale_f32 v11, s[4:5], v9, v9, v5
	v_rcp_f32_e32 v12, v11
	s_nop 0
	v_fma_f32 v13, -v11, v12, 1.0
	v_fmac_f32_e32 v12, v13, v12
	v_div_scale_f32 v13, vcc, v5, v9, v5
	v_mul_f32_e32 v14, v13, v12
	v_fma_f32 v15, -v11, v14, v13
	v_fmac_f32_e32 v14, v15, v12
	v_fma_f32 v11, -v11, v14, v13
	v_div_fmas_f32 v11, v11, v12, v14
	v_div_fixup_f32 v9, v11, v9, v5
	v_div_scale_f32 v5, s[4:5], v8, v8, v10
	v_rcp_f32_e32 v11, v5
	s_nop 0
	v_fma_f32 v12, -v5, v11, 1.0
	v_fmac_f32_e32 v11, v12, v11
	v_div_scale_f32 v12, vcc, v10, v8, v10
	v_mul_f32_e32 v13, v12, v11
	v_fma_f32 v14, -v5, v13, v12
	v_fmac_f32_e32 v13, v14, v11
	v_fma_f32 v5, -v5, v13, v12
	v_div_fmas_f32 v5, v5, v11, v13
	v_div_fixup_f32 v8, v5, v8, v10
	v_pk_mul_f32 v[6:7], v[6:7], v[8:9]
	s_nop 0
	v_cvt_pk_f16_f32 v5, v6, v7
	global_store_dwordx2 v[32:33], v[4:5], off offset:192
	s_waitcnt vmcnt(4)
	v_cvt_f32_f16_sdwa v8, v66 dst_sel:DWORD dst_unused:UNUSED_PAD src0_sel:WORD_1
	v_cvt_f32_f16_e32 v4, v66
	v_mul_f32_e32 v7, 0xbfb8aa3b, v8
	v_mul_f32_e32 v6, 0xbfb8aa3b, v4
	v_exp_f32_e32 v6, v6
	v_exp_f32_e32 v7, v7
	s_nop 0
	v_pk_add_f32 v[6:7], v[6:7], 1.0 op_sel_hi:[1,0]
	s_nop 0
	v_div_scale_f32 v9, s[4:5], v7, v7, v8
	v_rcp_f32_e32 v10, v9
	s_nop 0
	v_fma_f32 v11, -v9, v10, 1.0
	v_fmac_f32_e32 v10, v11, v10
	v_div_scale_f32 v11, vcc, v8, v7, v8
	v_mul_f32_e32 v12, v11, v10
	v_fma_f32 v13, -v9, v12, v11
	v_fmac_f32_e32 v12, v13, v10
	v_fma_f32 v9, -v9, v12, v11
	v_div_fmas_f32 v9, v9, v10, v12
	v_div_fixup_f32 v7, v9, v7, v8
	v_div_scale_f32 v8, s[4:5], v6, v6, v4
	v_rcp_f32_e32 v9, v8
	s_nop 0
	v_fma_f32 v10, -v8, v9, 1.0
	v_fmac_f32_e32 v9, v10, v9
	v_div_scale_f32 v10, vcc, v4, v6, v4
	v_mul_f32_e32 v11, v10, v9
	v_fma_f32 v12, -v8, v11, v10
	v_fmac_f32_e32 v11, v12, v9
	v_fma_f32 v8, -v8, v11, v10
	v_div_fmas_f32 v8, v8, v9, v11
	v_div_fixup_f32 v6, v8, v6, v4
	v_pk_mul_f32 v[0:1], v[0:1], v[6:7]
	v_cvt_f32_f16_e32 v6, v67
	v_cvt_pk_f16_f32 v0, v0, v1
	v_cvt_f32_f16_sdwa v1, v67 dst_sel:DWORD dst_unused:UNUSED_PAD src0_sel:WORD_1
	v_mul_f32_e32 v4, 0xbfb8aa3b, v6
	v_exp_f32_e32 v4, v4
	v_mul_f32_e32 v5, 0xbfb8aa3b, v1
	v_exp_f32_e32 v5, v5
	s_nop 0
	v_pk_add_f32 v[4:5], v[4:5], 1.0 op_sel_hi:[1,0]
	s_nop 0
	v_div_scale_f32 v7, s[4:5], v5, v5, v1
	v_rcp_f32_e32 v8, v7
	s_nop 0
	v_fma_f32 v9, -v7, v8, 1.0
	v_fmac_f32_e32 v8, v9, v8
	v_div_scale_f32 v9, vcc, v1, v5, v1
	v_mul_f32_e32 v10, v9, v8
	v_fma_f32 v11, -v7, v10, v9
	v_fmac_f32_e32 v10, v11, v8
	v_fma_f32 v7, -v7, v10, v9
	v_div_fmas_f32 v7, v7, v8, v10
	v_div_fixup_f32 v5, v7, v5, v1
	v_div_scale_f32 v1, s[4:5], v4, v4, v6
	v_rcp_f32_e32 v7, v1
	s_nop 0
	v_fma_f32 v8, -v1, v7, 1.0
	v_fmac_f32_e32 v7, v8, v7
	v_div_scale_f32 v8, vcc, v6, v4, v6
	v_mul_f32_e32 v9, v8, v7
	v_fma_f32 v10, -v1, v9, v8
	v_fmac_f32_e32 v9, v10, v7
	v_fma_f32 v1, -v1, v9, v8
	v_div_fmas_f32 v1, v1, v7, v9
	v_div_fixup_f32 v4, v1, v4, v6
	v_pk_mul_f32 v[2:3], v[2:3], v[4:5]
	s_nop 0
	v_cvt_pk_f16_f32 v1, v2, v3
	global_store_dwordx2 v[32:33], v[0:1], off offset:224
